# GEMM K-loops: drop duplicate lgkmcnt(0) after setprio 1, sink post-MFMA address prep below the barrier, s_setprio 0 moved after the post-MFMA barrier
# speedup vs baseline: 1.0063x; 1.0063x over previous
; #define PG8_STAGE(bufoff, gbase, voff) do { _Pragma("unroll") for (int _i = 0; _i < 2; ++_i) \
;     __builtin_amdgcn_global_load_lds((const unsigned*)((const char*)(gbase) + (voff)[_i]), (LAS unsigned*)(lds + (bufoff) + ldsw + _i * 8192), 16, 0, 0); } while (0)
; #define PG8_LDA(dst, b, h) do { _Pragma("unroll") for (int m = 0; m < 4; ++m) _Pragma("unroll") for (int k = 0; k < 2; ++k) dst[m][k] = *(const LAS bf16x8*)(lds + PG8_SA(b, h) + aoff + m * 2048 + k * 1024); } while (0)
; #define PG8_LDB(dst, b, h) do { _Pragma("unroll") for (int n = 0; n < 2; ++n) _Pragma("unroll") for (int k = 0; k < 2; ++k) dst[n][k] = *(const LAS bf16x8*)(lds + PG8_SB(b, h) + boff + n * 2048 + k * 1024); } while (0)
; #define PG8_MMA(ai, bj, At, Bt) do { __builtin_amdgcn_s_setprio(1); _Pragma("unroll") for (int m = 0; m < 4; ++m) _Pragma("unroll") for (int n = 0; n < 2; ++n) _Pragma("unroll") for (int k = 0; k < 2; ++k) \
;     acc[ai][bj][m][n] = __builtin_amdgcn_mfma_f32_16x16x32_bf16(Bt[n][k], At[m][k], acc[ai][bj][m][n], 0, 0, 0); __builtin_amdgcn_s_setprio(0); } while (0)
; #define PG8_WAIT_V(n) asm volatile("s_waitcnt vmcnt(" #n ")" ::: "memory")
; #define PG8_WAIT_L(n) asm volatile("s_waitcnt lgkmcnt(" #n ")" ::: "memory")
; #define PG8_BAR __builtin_amdgcn_s_barrier()
; #define PG8_SCHED __builtin_amdgcn_sched_barrier(0)
; template <class Epi, class Sched = StaticOrder>
; DI void gemm_phase(LAS unsigned char* lds, const Gemm g, const Sched& S, const Epi& E) {
;     ...
;     for (int t = 0; t < nt; t += 2) {
;       const bool last = (t == nt - 2);
;       const char* a1 = cA + (size_t)(t + 1) * kstep;
;       const char* a2 = last ? nA : cA + (size_t)(t + 2) * kstep; const char* b2 = last ? nB : cB + (size_t)(t + 2) * kstep;
;       const char* a3 = a2 + kstep; const char* b3 = b2 + kstep;
;       PG8_LDB(B0, 0, 0); PG8_SCHED; PG8_LDA(At, 0, 0); PG8_STAGE(PG8_SA(1, 1), a1 + hstep, voffA);
;       PG8_WAIT_L(8); PG8_BAR; PG8_WAIT_L(0); PG8_MMA(0, 0, At, B0); PG8_BAR; PG8_SCHED;
;       PG8_LDB(B1, 0, 1); PG8_STAGE(PG8_SB(0, 0), b2, voffB);
;       PG8_BAR; PG8_WAIT_L(0); PG8_MMA(0, 1, At, B1); PG8_BAR;
;       PG8_LDA(At, 0, 1); PG8_STAGE(PG8_SA(0, 0), a2, voffA);
;       PG8_BAR; PG8_WAIT_L(0); PG8_MMA(1, 0, At, B0); PG8_BAR; PG8_SCHED;
;       PG8_STAGE(PG8_SB(0, 1), b2 + hstep, voffB);
;       PG8_WAIT_V(6); PG8_BAR; PG8_MMA(1, 1, At, B1); PG8_BAR;
.LBB0_346:
	ds_read_b128 v[128:131], v173
	ds_read_b128 v[132:135], v173 offset:1024
	ds_read_b128 v[154:157], v173 offset:2048
	ds_read_b128 v[158:161], v173 offset:3072
	s_add_u32 s8, s6, 0xfff80080
	s_addc_u32 s9, s7, -1
	s_cmp_eq_u32 s52, 28
	s_cselect_b32 s11, s31, s9
	s_cselect_b32 s10, s42, s8
	s_cselect_b32 s9, s29, s45
	s_cselect_b32 s8, s43, s44
	v_lshl_add_u64 v[202:203], s[6:7], 0, v[146:147]
	s_add_i32 m0, s48, 0xc000
	ds_read_b128 v[162:165], v174
	ds_read_b128 v[166:169], v174 offset:1024
	ds_read_b128 v[178:181], v174 offset:2048
	ds_read_b128 v[182:185], v174 offset:3072
	ds_read_b128 v[186:189], v174 offset:4096
	ds_read_b128 v[190:193], v174 offset:5120
	ds_read_b128 v[194:197], v174 offset:6144
	ds_read_b128 v[198:201], v174 offset:7168
	global_load_lds_dwordx4 v[202:203], off
	v_lshl_add_u64 v[202:203], s[6:7], 0, v[148:149]
	s_add_i32 m0, s48, 0xe000
	s_nop 0
	global_load_lds_dwordx4 v[202:203], off
	s_waitcnt lgkmcnt(8)
	s_barrier
	s_waitcnt lgkmcnt(0)
	s_setprio 1
	v_mfma_f32_16x16x32_bf16 v[124:127], v[128:131], v[162:165], v[124:127]
	v_mfma_f32_16x16x32_bf16 v[120:123], v[154:157], v[162:165], v[120:123]
	v_mfma_f32_16x16x32_bf16 v[108:111], v[128:131], v[178:181], v[108:111]
	v_mfma_f32_16x16x32_bf16 v[104:107], v[154:157], v[178:181], v[104:107]
	v_mfma_f32_16x16x32_bf16 v[100:103], v[128:131], v[186:189], v[100:103]
	v_mfma_f32_16x16x32_bf16 v[92:95], v[154:157], v[186:189], v[92:95]
	v_mfma_f32_16x16x32_bf16 v[84:87], v[128:131], v[194:197], v[84:87]
	v_mfma_f32_16x16x32_bf16 v[76:79], v[154:157], v[194:197], v[76:79]
	v_mfma_f32_16x16x32_bf16 v[124:127], v[132:135], v[166:169], v[124:127]
	v_mfma_f32_16x16x32_bf16 v[120:123], v[158:161], v[166:169], v[120:123]
	v_mfma_f32_16x16x32_bf16 v[108:111], v[132:135], v[182:185], v[108:111]
	v_mfma_f32_16x16x32_bf16 v[104:107], v[158:161], v[182:185], v[104:107]
	v_mfma_f32_16x16x32_bf16 v[100:103], v[132:135], v[190:193], v[100:103]
	v_mfma_f32_16x16x32_bf16 v[92:95], v[158:161], v[190:193], v[92:95]
	v_mfma_f32_16x16x32_bf16 v[84:87], v[132:135], v[198:201], v[84:87]
	v_mfma_f32_16x16x32_bf16 v[76:79], v[158:161], v[198:201], v[76:79]
	s_barrier
	s_setprio 0
	s_add_i32 s53, s65, s41
	v_lshl_add_u64 v[220:221], s[8:9], 0, v[140:141]
	s_mov_b32 m0, s53
	ds_read_b128 v[202:205], v175
	ds_read_b128 v[206:209], v175 offset:1024
	ds_read_b128 v[212:215], v175 offset:2048
	ds_read_b128 v[216:219], v175 offset:3072
	global_load_lds_dwordx4 v[220:221], off
	v_lshl_add_u64 v[222:223], s[8:9], 0, v[136:137]
	s_add_i32 m0, s53, 0x2000
	s_nop 0
	global_load_lds_dwordx4 v[222:223], off
	s_barrier
	s_waitcnt lgkmcnt(0)
	s_setprio 1
	v_mfma_f32_16x16x32_bf16 v[116:119], v[202:205], v[162:165], v[116:119]
	v_mfma_f32_16x16x32_bf16 v[112:115], v[212:215], v[162:165], v[112:115]
	v_mfma_f32_16x16x32_bf16 v[96:99], v[202:205], v[178:181], v[96:99]
	v_mfma_f32_16x16x32_bf16 v[88:91], v[212:215], v[178:181], v[88:91]
	v_mfma_f32_16x16x32_bf16 v[80:83], v[202:205], v[186:189], v[80:83]
	v_mfma_f32_16x16x32_bf16 v[72:75], v[212:215], v[186:189], v[72:75]
	v_mfma_f32_16x16x32_bf16 v[68:71], v[202:205], v[194:197], v[68:71]
	v_mfma_f32_16x16x32_bf16 v[64:67], v[212:215], v[194:197], v[64:67]
	v_mfma_f32_16x16x32_bf16 v[116:119], v[206:209], v[166:169], v[116:119]
	v_mfma_f32_16x16x32_bf16 v[112:115], v[216:219], v[166:169], v[112:115]
	v_mfma_f32_16x16x32_bf16 v[96:99], v[206:209], v[182:185], v[96:99]
	v_mfma_f32_16x16x32_bf16 v[88:91], v[216:219], v[182:185], v[88:91]
	v_mfma_f32_16x16x32_bf16 v[80:83], v[206:209], v[190:193], v[80:83]
	v_mfma_f32_16x16x32_bf16 v[72:75], v[216:219], v[190:193], v[72:75]
	v_mfma_f32_16x16x32_bf16 v[68:71], v[206:209], v[198:201], v[68:71]
	v_mfma_f32_16x16x32_bf16 v[64:67], v[216:219], v[198:201], v[64:67]
	s_barrier
	s_setprio 0
	s_mov_b32 m0, s48
	v_lshl_add_u64 v[224:225], s[10:11], 0, v[142:143]
	ds_read_b128 v[162:165], v174 offset:16384
	ds_read_b128 v[166:169], v174 offset:17408
	ds_read_b128 v[178:181], v174 offset:18432
	ds_read_b128 v[182:185], v174 offset:19456
	ds_read_b128 v[186:189], v174 offset:20480
	ds_read_b128 v[190:193], v174 offset:21504
	ds_read_b128 v[194:197], v174 offset:22528
	ds_read_b128 v[198:201], v174 offset:23552
	global_load_lds_dwordx4 v[224:225], off
	v_lshl_add_u64 v[226:227], s[10:11], 0, v[138:139]
	s_mov_b32 m0, s49
	s_nop 0
	global_load_lds_dwordx4 v[226:227], off
	s_barrier
	s_waitcnt lgkmcnt(0)
	s_setprio 1
	v_mfma_f32_16x16x32_bf16 v[60:63], v[128:131], v[162:165], v[60:63]
	v_mfma_f32_16x16x32_bf16 v[56:59], v[154:157], v[162:165], v[56:59]
	v_mfma_f32_16x16x32_bf16 v[52:55], v[128:131], v[178:181], v[52:55]
	v_mfma_f32_16x16x32_bf16 v[44:47], v[154:157], v[178:181], v[44:47]
	v_mfma_f32_16x16x32_bf16 v[36:39], v[128:131], v[186:189], v[36:39]
	v_mfma_f32_16x16x32_bf16 v[28:31], v[154:157], v[186:189], v[28:31]
	v_mfma_f32_16x16x32_bf16 v[20:23], v[128:131], v[194:197], v[20:23]
	v_mfma_f32_16x16x32_bf16 v[12:15], v[154:157], v[194:197], v[12:15]
	v_mfma_f32_16x16x32_bf16 v[60:63], v[132:135], v[166:169], v[60:63]
	v_mfma_f32_16x16x32_bf16 v[56:59], v[158:161], v[166:169], v[56:59]
	v_mfma_f32_16x16x32_bf16 v[52:55], v[132:135], v[182:185], v[52:55]
	v_mfma_f32_16x16x32_bf16 v[44:47], v[158:161], v[182:185], v[44:47]
	v_mfma_f32_16x16x32_bf16 v[36:39], v[132:135], v[190:193], v[36:39]
	v_mfma_f32_16x16x32_bf16 v[28:31], v[158:161], v[190:193], v[28:31]
	v_mfma_f32_16x16x32_bf16 v[20:23], v[132:135], v[198:201], v[20:23]
	v_mfma_f32_16x16x32_bf16 v[12:15], v[158:161], v[198:201], v[12:15]
	s_barrier
; #define PG8_STAGE(bufoff, gbase, voff) do { _Pragma("unroll") for (int _i = 0; _i < 2; ++_i) \
;     __builtin_amdgcn_global_load_lds((const unsigned*)((const char*)(gbase) + (voff)[_i]), (LAS unsigned*)(lds + (bufoff) + ldsw + _i * 8192), 16, 0, 0); } while (0)
; #define PG8_LDA(dst, b, h) do { _Pragma("unroll") for (int m = 0; m < 4; ++m) _Pragma("unroll") for (int k = 0; k < 2; ++k) dst[m][k] = *(const LAS bf16x8*)(lds + PG8_SA(b, h) + aoff + m * 2048 + k * 1024); } while (0)
; #define PG8_LDB(dst, b, h) do { _Pragma("unroll") for (int n = 0; n < 2; ++n) _Pragma("unroll") for (int k = 0; k < 2; ++k) dst[n][k] = *(const LAS bf16x8*)(lds + PG8_SB(b, h) + boff + n * 2048 + k * 1024); } while (0)
; #define PG8_MMA(ai, bj, At, Bt) do { __builtin_amdgcn_s_setprio(1); _Pragma("unroll") for (int m = 0; m < 4; ++m) _Pragma("unroll") for (int n = 0; n < 2; ++n) _Pragma("unroll") for (int k = 0; k < 2; ++k) \
;     acc[ai][bj][m][n] = __builtin_amdgcn_mfma_f32_16x16x32_bf16(Bt[n][k], At[m][k], acc[ai][bj][m][n], 0, 0, 0); __builtin_amdgcn_s_setprio(0); } while (0)
; #define PG8_WAIT_V(n) asm volatile("s_waitcnt vmcnt(" #n ")" ::: "memory")
; #define PG8_WAIT_L(n) asm volatile("s_waitcnt lgkmcnt(" #n ")" ::: "memory")
; #define PG8_BAR __builtin_amdgcn_s_barrier()
; #define PG8_SCHED __builtin_amdgcn_sched_barrier(0)
; template <class Epi, class Sched = StaticOrder>
; DI void gemm_phase(LAS unsigned char* lds, const Gemm g, const Sched& S, const Epi& E) {
;     ...
;       PG8_STAGE(PG8_SB(0, 1), b2 + hstep, voffB);
;       PG8_WAIT_V(6); PG8_BAR; PG8_MMA(1, 1, At, B1); PG8_BAR;
;       PG8_LDB(B0, 1, 0); PG8_SCHED; PG8_LDA(At, 1, 0); PG8_STAGE(PG8_SA(0, 1), a2 + hstep, voffA);
;       PG8_WAIT_L(8); PG8_BAR; PG8_WAIT_L(0); PG8_MMA(0, 0, At, B0); PG8_BAR; PG8_SCHED;
;       PG8_LDB(B1, 1, 1); PG8_STAGE(PG8_SB(1, 0), b3, voffB);
;       PG8_BAR; PG8_WAIT_L(0); PG8_MMA(0, 1, At, B1); PG8_BAR;
;       PG8_LDA(At, 1, 1); PG8_STAGE(PG8_SA(1, 0), a3, voffA);
;       PG8_BAR; PG8_WAIT_L(0); PG8_MMA(1, 0, At, B0); PG8_BAR; PG8_SCHED;
	s_setprio 0
	s_add_u32 s54, s8, 0x80000
	s_addc_u32 s55, s9, 0
	s_add_i32 s53, s72, s41
	v_lshl_add_u64 v[128:129], s[54:55], 0, v[140:141]
	s_mov_b32 m0, s53
	s_nop 0
	global_load_lds_dwordx4 v[128:129], off
	v_lshl_add_u64 v[128:129], s[54:55], 0, v[136:137]
	s_add_i32 m0, s53, 0x2000
	s_nop 0
	global_load_lds_dwordx4 v[128:129], off
	s_waitcnt vmcnt(6)
	s_barrier
	s_setprio 1
	v_mfma_f32_16x16x32_bf16 v[48:51], v[202:205], v[162:165], v[48:51]
	v_mfma_f32_16x16x32_bf16 v[40:43], v[212:215], v[162:165], v[40:43]
	v_mfma_f32_16x16x32_bf16 v[32:35], v[202:205], v[178:181], v[32:35]
	v_mfma_f32_16x16x32_bf16 v[24:27], v[212:215], v[178:181], v[24:27]
	v_mfma_f32_16x16x32_bf16 v[16:19], v[202:205], v[186:189], v[16:19]
	v_mfma_f32_16x16x32_bf16 v[8:11], v[212:215], v[186:189], v[8:11]
	v_mfma_f32_16x16x32_bf16 v[4:7], v[202:205], v[194:197], v[4:7]
	v_mfma_f32_16x16x32_bf16 v[0:3], v[212:215], v[194:197], v[0:3]
	v_mfma_f32_16x16x32_bf16 v[48:51], v[206:209], v[166:169], v[48:51]
	v_mfma_f32_16x16x32_bf16 v[40:43], v[216:219], v[166:169], v[40:43]
	v_mfma_f32_16x16x32_bf16 v[32:35], v[206:209], v[182:185], v[32:35]
	v_mfma_f32_16x16x32_bf16 v[24:27], v[216:219], v[182:185], v[24:27]
	v_mfma_f32_16x16x32_bf16 v[16:19], v[206:209], v[190:193], v[16:19]
	v_mfma_f32_16x16x32_bf16 v[8:11], v[216:219], v[190:193], v[8:11]
	v_mfma_f32_16x16x32_bf16 v[4:7], v[206:209], v[198:201], v[4:7]
	v_mfma_f32_16x16x32_bf16 v[0:3], v[216:219], v[198:201], v[0:3]
	s_barrier
	s_setprio 0
	s_add_i32 s53, 0, 0x18000
	v_add_u32_e32 v158, s53, v171
	ds_read_b128 v[128:131], v158
	ds_read_b128 v[132:135], v158 offset:1024
	ds_read_b128 v[154:157], v158 offset:2048
	ds_read_b128 v[158:161], v158 offset:3072
	s_add_u32 s10, s10, 0x80000
	s_addc_u32 s11, s11, 0
	s_mov_b32 m0, s50
	v_lshl_add_u64 v[202:203], s[10:11], 0, v[142:143]
	ds_read_b128 v[162:165], v174 offset:32768
	ds_read_b128 v[166:169], v174 offset:33792
	ds_read_b128 v[178:181], v174 offset:34816
	ds_read_b128 v[182:185], v174 offset:35840
	ds_read_b128 v[186:189], v174 offset:36864
	ds_read_b128 v[190:193], v174 offset:37888
	ds_read_b128 v[194:197], v174 offset:38912
	ds_read_b128 v[198:201], v174 offset:39936
	global_load_lds_dwordx4 v[202:203], off
	v_lshl_add_u64 v[202:203], s[10:11], 0, v[138:139]
	s_mov_b32 m0, s51
	s_nop 0
	global_load_lds_dwordx4 v[202:203], off
	s_waitcnt lgkmcnt(8)
	s_barrier
	s_waitcnt lgkmcnt(0)
	s_setprio 1
	v_mfma_f32_16x16x32_bf16 v[124:127], v[128:131], v[162:165], v[124:127]
	v_mfma_f32_16x16x32_bf16 v[120:123], v[154:157], v[162:165], v[120:123]
	v_mfma_f32_16x16x32_bf16 v[108:111], v[128:131], v[178:181], v[108:111]
	v_mfma_f32_16x16x32_bf16 v[104:107], v[154:157], v[178:181], v[104:107]
	v_mfma_f32_16x16x32_bf16 v[100:103], v[128:131], v[186:189], v[100:103]
	v_mfma_f32_16x16x32_bf16 v[92:95], v[154:157], v[186:189], v[92:95]
	v_mfma_f32_16x16x32_bf16 v[84:87], v[128:131], v[194:197], v[84:87]
	v_mfma_f32_16x16x32_bf16 v[76:79], v[154:157], v[194:197], v[76:79]
	v_mfma_f32_16x16x32_bf16 v[124:127], v[132:135], v[166:169], v[124:127]
	v_mfma_f32_16x16x32_bf16 v[120:123], v[158:161], v[166:169], v[120:123]
	v_mfma_f32_16x16x32_bf16 v[108:111], v[132:135], v[182:185], v[108:111]
	v_mfma_f32_16x16x32_bf16 v[104:107], v[158:161], v[182:185], v[104:107]
	v_mfma_f32_16x16x32_bf16 v[100:103], v[132:135], v[190:193], v[100:103]
	v_mfma_f32_16x16x32_bf16 v[92:95], v[158:161], v[190:193], v[92:95]
	v_mfma_f32_16x16x32_bf16 v[84:87], v[132:135], v[198:201], v[84:87]
	v_mfma_f32_16x16x32_bf16 v[76:79], v[158:161], v[198:201], v[76:79]
	s_barrier
	s_setprio 0
	s_add_i32 s10, 0, 0x1c000
	s_add_i32 s11, s53, s41
	v_add_u32_e32 v177, s10, v171
	v_lshl_add_u64 v[220:221], v[220:221], 0, s[22:23]
	s_mov_b32 m0, s11
	ds_read_b128 v[202:205], v177
	ds_read_b128 v[206:209], v177 offset:1024
	ds_read_b128 v[212:215], v177 offset:2048
	ds_read_b128 v[216:219], v177 offset:3072
	global_load_lds_dwordx4 v[220:221], off
	v_lshl_add_u64 v[220:221], v[222:223], 0, s[22:23]
	s_add_i32 m0, s11, 0x2000
	s_nop 0
	global_load_lds_dwordx4 v[220:221], off
	s_barrier
	s_waitcnt lgkmcnt(0)
	s_setprio 1
	v_mfma_f32_16x16x32_bf16 v[116:119], v[202:205], v[162:165], v[116:119]
	v_mfma_f32_16x16x32_bf16 v[112:115], v[212:215], v[162:165], v[112:115]
	v_mfma_f32_16x16x32_bf16 v[96:99], v[202:205], v[178:181], v[96:99]
	v_mfma_f32_16x16x32_bf16 v[88:91], v[212:215], v[178:181], v[88:91]
	v_mfma_f32_16x16x32_bf16 v[80:83], v[202:205], v[186:189], v[80:83]
	v_mfma_f32_16x16x32_bf16 v[72:75], v[212:215], v[186:189], v[72:75]
	v_mfma_f32_16x16x32_bf16 v[68:71], v[202:205], v[194:197], v[68:71]
	v_mfma_f32_16x16x32_bf16 v[64:67], v[212:215], v[194:197], v[64:67]
	v_mfma_f32_16x16x32_bf16 v[116:119], v[206:209], v[166:169], v[116:119]
	v_mfma_f32_16x16x32_bf16 v[112:115], v[216:219], v[166:169], v[112:115]
	v_mfma_f32_16x16x32_bf16 v[96:99], v[206:209], v[182:185], v[96:99]
	v_mfma_f32_16x16x32_bf16 v[88:91], v[216:219], v[182:185], v[88:91]
	v_mfma_f32_16x16x32_bf16 v[80:83], v[206:209], v[190:193], v[80:83]
	v_mfma_f32_16x16x32_bf16 v[72:75], v[216:219], v[190:193], v[72:75]
	v_mfma_f32_16x16x32_bf16 v[68:71], v[206:209], v[198:201], v[68:71]
	v_mfma_f32_16x16x32_bf16 v[64:67], v[216:219], v[198:201], v[64:67]
	s_barrier
	s_setprio 0
	s_mov_b32 m0, s56
	v_lshl_add_u64 v[220:221], v[224:225], 0, s[22:23]
	ds_read_b128 v[162:165], v174 offset:49152
	ds_read_b128 v[166:169], v174 offset:50176
	ds_read_b128 v[178:181], v174 offset:51200
	ds_read_b128 v[182:185], v174 offset:52224
	ds_read_b128 v[186:189], v174 offset:53248
	ds_read_b128 v[190:193], v174 offset:54272
	ds_read_b128 v[194:197], v174 offset:55296
	ds_read_b128 v[198:201], v174 offset:56320
	global_load_lds_dwordx4 v[220:221], off
	v_lshl_add_u64 v[220:221], v[226:227], 0, s[22:23]
	s_mov_b32 m0, s57
	s_nop 0
	global_load_lds_dwordx4 v[220:221], off
	s_barrier
; #define PG8_STAGE(bufoff, gbase, voff) do { _Pragma("unroll") for (int _i = 0; _i < 2; ++_i) \
;     __builtin_amdgcn_global_load_lds((const unsigned*)((const char*)(gbase) + (voff)[_i]), (LAS unsigned*)(lds + (bufoff) + ldsw + _i * 8192), 16, 0, 0); } while (0)
; #define PG8_MMA(ai, bj, At, Bt) do { __builtin_amdgcn_s_setprio(1); _Pragma("unroll") for (int m = 0; m < 4; ++m) _Pragma("unroll") for (int n = 0; n < 2; ++n) _Pragma("unroll") for (int k = 0; k < 2; ++k) \
;     acc[ai][bj][m][n] = __builtin_amdgcn_mfma_f32_16x16x32_bf16(Bt[n][k], At[m][k], acc[ai][bj][m][n], 0, 0, 0); __builtin_amdgcn_s_setprio(0); } while (0)
; #define PG8_WAIT_V(n) asm volatile("s_waitcnt vmcnt(" #n ")" ::: "memory")
; #define PG8_WAIT_L(n) asm volatile("s_waitcnt lgkmcnt(" #n ")" ::: "memory")
; #define PG8_BAR __builtin_amdgcn_s_barrier()
; #define PG8_SCHED __builtin_amdgcn_sched_barrier(0)
; DI float row_rstd(const float* ssq, int row, int fq) {
;   const f32x4 a = *(const f32x4*)(ssq + (size_t)row * 32 + fq * 8), b = *(const f32x4*)(ssq + (size_t)row * 32 + fq * 8 + 4);
;   float sm = ((a[0] + a[1]) + (a[2] + a[3])) + ((b[0] + b[1]) + (b[2] + b[3]));
;   sm += __shfl_xor(sm, 16); sm += __shfl_xor(sm, 32);
;   return rsqrtf(sm * (1.0f / 2048.f) + 1e-6f);
; }
; template <class Epi, class Sched = StaticOrder>
; DI void gemm_phase(LAS unsigned char* lds, const Gemm g, const Sched& S, const Epi& E) {
;     ...
;       PG8_BAR; PG8_WAIT_L(0); PG8_MMA(1, 0, At, B0); PG8_BAR; PG8_SCHED;
;       PG8_STAGE(PG8_SB(1, 1), b3 + hstep, voffB);
;       PG8_WAIT_V(6); PG8_BAR; PG8_MMA(1, 1, At, B1); PG8_BAR;
;     }
	s_waitcnt lgkmcnt(0)
	s_setprio 1
	v_mfma_f32_16x16x32_bf16 v[60:63], v[128:131], v[162:165], v[60:63]
	v_mfma_f32_16x16x32_bf16 v[56:59], v[154:157], v[162:165], v[56:59]
	v_mfma_f32_16x16x32_bf16 v[52:55], v[128:131], v[178:181], v[52:55]
	v_mfma_f32_16x16x32_bf16 v[44:47], v[154:157], v[178:181], v[44:47]
	v_mfma_f32_16x16x32_bf16 v[36:39], v[128:131], v[186:189], v[36:39]
	v_mfma_f32_16x16x32_bf16 v[28:31], v[154:157], v[186:189], v[28:31]
	v_mfma_f32_16x16x32_bf16 v[20:23], v[128:131], v[194:197], v[20:23]
	v_mfma_f32_16x16x32_bf16 v[12:15], v[154:157], v[194:197], v[12:15]
	v_mfma_f32_16x16x32_bf16 v[60:63], v[132:135], v[166:169], v[60:63]
	v_mfma_f32_16x16x32_bf16 v[56:59], v[158:161], v[166:169], v[56:59]
	v_mfma_f32_16x16x32_bf16 v[52:55], v[132:135], v[182:185], v[52:55]
	v_mfma_f32_16x16x32_bf16 v[44:47], v[158:161], v[182:185], v[44:47]
	v_mfma_f32_16x16x32_bf16 v[36:39], v[132:135], v[190:193], v[36:39]
	v_mfma_f32_16x16x32_bf16 v[28:31], v[158:161], v[190:193], v[28:31]
	v_mfma_f32_16x16x32_bf16 v[20:23], v[132:135], v[198:201], v[20:23]
	v_mfma_f32_16x16x32_bf16 v[12:15], v[158:161], v[198:201], v[12:15]
	s_barrier
	s_setprio 0
	s_add_u32 s8, s8, 0x80080
	s_addc_u32 s9, s9, 0
	s_add_i32 s10, s10, s41
	v_lshl_add_u64 v[128:129], s[8:9], 0, v[140:141]
	s_mov_b32 m0, s10
	s_nop 0
	global_load_lds_dwordx4 v[128:129], off
	v_lshl_add_u64 v[128:129], s[8:9], 0, v[136:137]
	s_add_i32 m0, s10, 0x2000
	s_nop 0
	global_load_lds_dwordx4 v[128:129], off
	s_waitcnt vmcnt(6)
	s_barrier
	s_setprio 1
	v_mfma_f32_16x16x32_bf16 v[48:51], v[202:205], v[162:165], v[48:51]
	v_mfma_f32_16x16x32_bf16 v[40:43], v[212:215], v[162:165], v[40:43]
	v_mfma_f32_16x16x32_bf16 v[32:35], v[202:205], v[178:181], v[32:35]
	v_mfma_f32_16x16x32_bf16 v[24:27], v[212:215], v[178:181], v[24:27]
	v_mfma_f32_16x16x32_bf16 v[16:19], v[202:205], v[186:189], v[16:19]
	v_mfma_f32_16x16x32_bf16 v[8:11], v[212:215], v[186:189], v[8:11]
	v_mfma_f32_16x16x32_bf16 v[4:7], v[202:205], v[194:197], v[4:7]
	v_mfma_f32_16x16x32_bf16 v[0:3], v[212:215], v[194:197], v[0:3]
	v_mfma_f32_16x16x32_bf16 v[48:51], v[206:209], v[166:169], v[48:51]
	v_mfma_f32_16x16x32_bf16 v[40:43], v[216:219], v[166:169], v[40:43]
	v_mfma_f32_16x16x32_bf16 v[32:35], v[206:209], v[182:185], v[32:35]
	v_mfma_f32_16x16x32_bf16 v[24:27], v[216:219], v[182:185], v[24:27]
	v_mfma_f32_16x16x32_bf16 v[16:19], v[206:209], v[190:193], v[16:19]
	v_mfma_f32_16x16x32_bf16 v[8:11], v[216:219], v[190:193], v[8:11]
	v_mfma_f32_16x16x32_bf16 v[4:7], v[206:209], v[198:201], v[4:7]
	v_mfma_f32_16x16x32_bf16 v[0:3], v[216:219], v[198:201], v[0:3]
	s_add_i32 s52, s52, 2
	s_add_u32 s6, s6, 0x100
	s_addc_u32 s7, s7, 0
	s_add_u32 s44, s44, 0x100
	s_addc_u32 s45, s45, 0
	s_cmp_gt_u32 s52, 29
	s_barrier
	s_setprio 0
	s_cbranch_scc0 .LBB0_346
	v_lshl_add_u32 v168, s4, 8, v170
	v_ashrrev_i32_e32 v169, 31, v168
	v_or_b32_e32 v154, 16, v168
	v_lshlrev_b64 v[128:129], 7, v[168:169]
	v_ashrrev_i32_e32 v155, 31, v154
	v_lshl_add_u64 v[128:129], v[144:145], 0, v[128:129]
	v_lshlrev_b64 v[156:157], 7, v[154:155]
	global_load_dwordx4 v[132:135], v[128:129], off
	s_nop 0
	global_load_dwordx4 v[128:131], v[128:129], off offset:16
	v_lshl_add_u64 v[156:157], v[144:145], 0, v[156:157]
	global_load_dwordx4 v[178:181], v[156:157], off
	global_load_dwordx4 v[182:185], v[156:157], off offset:16
	v_or_b32_e32 v160, 32, v168
	v_ashrrev_i32_e32 v161, 31, v160
	v_lshlrev_b64 v[156:157], 7, v[160:161]
	v_lshl_add_u64 v[156:157], v[144:145], 0, v[156:157]
	global_load_dwordx4 v[186:189], v[156:157], off
	global_load_dwordx4 v[190:193], v[156:157], off offset:16
	v_or_b32_e32 v156, 48, v168
	v_ashrrev_i32_e32 v157, 31, v156
	v_lshlrev_b64 v[158:159], 7, v[156:157]
	v_lshl_add_u64 v[158:159], v[144:145], 0, v[158:159]
	global_load_dwordx4 v[194:197], v[158:159], off
	global_load_dwordx4 v[198:201], v[158:159], off offset:16
	v_add_u32_e32 v164, 0x80, v168
	v_ashrrev_i32_e32 v165, 31, v164
	v_lshlrev_b64 v[158:159], 7, v[164:165]
	v_lshl_add_u64 v[158:159], v[144:145], 0, v[158:159]
	global_load_dwordx4 v[202:205], v[158:159], off
	global_load_dwordx4 v[206:209], v[158:159], off offset:16
	v_add_u32_e32 v158, 0x90, v168
	v_ashrrev_i32_e32 v159, 31, v158
	v_lshlrev_b64 v[162:163], 7, v[158:159]
	v_lshl_add_u64 v[162:163], v[144:145], 0, v[162:163]
	global_load_dwordx4 v[212:215], v[162:163], off
	global_load_dwordx4 v[216:219], v[162:163], off offset:16
	v_add_u32_e32 v166, 0xa0, v168
	v_ashrrev_i32_e32 v167, 31, v166
	v_lshlrev_b64 v[162:163], 7, v[166:167]
	v_lshl_add_u64 v[162:163], v[144:145], 0, v[162:163]
	global_load_dwordx4 v[220:223], v[162:163], off
	global_load_dwordx4 v[224:227], v[162:163], off offset:16
	v_add_u32_e32 v162, 0xb0, v168
	v_ashrrev_i32_e32 v163, 31, v162
	v_lshlrev_b64 v[228:229], 7, v[162:163]
	v_lshl_add_u64 v[232:233], v[144:145], 0, v[228:229]
	global_load_dwordx4 v[228:231], v[232:233], off
	s_nop 0
	global_load_dwordx4 v[232:235], v[232:233], off offset:16
	s_waitcnt vmcnt(0)
	v_mov_b32_e32 v236, v132
	v_mov_b32_e32 v237, v128
	v_mov_b32_e32 v128, v133
	v_mov_b32_e32 v132, v134
	v_mov_b32_e32 v133, v130
	v_mov_b32_e32 v130, v135
	v_pk_add_f32 v[130:131], v[132:133], v[130:131]
	v_mov_b32_e32 v132, v178
	v_mov_b32_e32 v133, v182
	v_mov_b32_e32 v182, v179
	v_mov_b32_e32 v134, v180
	v_mov_b32_e32 v135, v184
	v_mov_b32_e32 v184, v181
	v_pk_add_f32 v[128:129], v[236:237], v[128:129]
	v_pk_add_f32 v[132:133], v[132:133], v[182:183]
	v_pk_add_f32 v[134:135], v[134:135], v[184:185]
	v_pk_add_f32 v[128:129], v[128:129], v[130:131]
	v_pk_add_f32 v[130:131], v[132:133], v[134:135]
	v_mov_b32_e32 v133, v128
	v_mov_b32_e32 v132, v130
	v_and_b32_e32 v130, 64, v176
	v_add_u32_e32 v155, 64, v130
	v_xor_b32_e32 v130, 16, v176
	v_cmp_lt_i32_e32 vcc, v130, v155
	v_mov_b32_e32 v128, v131
	v_pk_add_f32 v[128:129], v[132:133], v[128:129]
	v_cndmask_b32_e32 v130, v176, v130, vcc
	v_lshlrev_b32_e32 v157, 2, v130
	ds_bpermute_b32 v131, v157, v129
	ds_bpermute_b32 v130, v157, v128
	v_mov_b32_e32 v178, v186
	v_mov_b32_e32 v179, v190
	v_mov_b32_e32 v190, v187
	v_mov_b32_e32 v186, v194
	s_waitcnt lgkmcnt(0)
; DI unsigned pack2(float lo, float hi) { f32x2 v = {lo, hi}; bf16v2 r = __builtin_convertvector(v, bf16v2); return __builtin_bit_cast(unsigned, r); }
; DI float row_rstd(const float* ssq, int row, int fq) {
;   const f32x4 a = *(const f32x4*)(ssq + (size_t)row * 32 + fq * 8), b = *(const f32x4*)(ssq + (size_t)row * 32 + fq * 8 + 4);
;   float sm = ((a[0] + a[1]) + (a[2] + a[3])) + ((b[0] + b[1]) + (b[2] + b[3]));
;   sm += __shfl_xor(sm, 16); sm += __shfl_xor(sm, 32);
;   return rsqrtf(sm * (1.0f / 2048.f) + 1e-6f);
; }
;   DI void operator()(const f32x4 (&acc)[2][2][4][2], const Unit& u, int wr, int wc, int fr, int fq) const {
;     const int row0 = u.pm * BM + wr * 64 + fr, col0 = u.pn * BM + wc * 32 + 8 * fq;
;     float rsv[2][4];
; #pragma unroll
;     for (int ai = 0; ai < 2; ++ai)
; #pragma unroll
;       for (int m = 0; m < 4; ++m) rsv[ai][m] = row_rstd(ssq, row0 + ai * HALF + m * 16, fq);
; #pragma unroll
;     for (int ai = 0; ai < 2; ++ai)
; #pragma unroll
;       for (int m = 0; m < 4; ++m) {
;         const int row = row0 + ai * HALF + m * 16;
;         const float rs = rsv[ai][m];
;         bf16_t* rowp = O + (size_t)row * ldc + col0;
; #pragma unroll
;         for (int bj = 0; bj < 2; ++bj) {
;           const f32x4 v0 = acc[ai][bj][m][0] * rs, v1 = acc[ai][bj][m][1] * rs;
;           u32x4 w; w.x = pack2(v0[0], v0[1]); w.y = pack2(v0[2], v0[3]); w.z = pack2(v1[0], v1[1]); w.w = pack2(v1[2], v1[3]);
;           *(u32x4*)(rowp + bj * HALF) = w;
;         }
	v_pk_add_f32 v[128:129], v[128:129], v[130:131]
	v_xor_b32_e32 v130, 32, v176
	v_cmp_lt_i32_e32 vcc, v130, v155
	v_mov_b32_e32 v187, v198
	v_mov_b32_e32 v198, v195
	v_cndmask_b32_e32 v130, v176, v130, vcc
	v_lshlrev_b32_e32 v155, 2, v130
	ds_bpermute_b32 v131, v155, v129
	ds_bpermute_b32 v130, v155, v128
	v_pk_add_f32 v[182:183], v[186:187], v[198:199]
	v_mov_b32_e32 v180, v188
	v_mov_b32_e32 v181, v192
	v_mov_b32_e32 v192, v189
	s_waitcnt lgkmcnt(0)
	v_pk_add_f32 v[128:129], v[128:129], v[130:131]
	v_mov_b64_e32 v[130:131], s[26:27]
	v_pk_fma_f32 v[128:129], v[128:129], s[24:25], v[130:131] op_sel_hi:[1,0,0]
	v_mov_b32_e32 v188, v196
	v_mul_f32_e32 v159, 0x4b800000, v129
	v_cmp_gt_f32_e32 vcc, s73, v129
	v_mov_b32_e32 v189, v200
	v_mov_b32_e32 v200, v197
	v_cndmask_b32_e32 v129, v129, v159, vcc
	v_rsq_f32_e32 v129, v129
	v_pk_add_f32 v[178:179], v[178:179], v[190:191]
	v_pk_add_f32 v[180:181], v[180:181], v[192:193]
	v_pk_add_f32 v[184:185], v[188:189], v[200:201]
	v_mul_f32_e32 v159, 0x45800000, v129
	v_cndmask_b32_e32 v198, v129, v159, vcc
	v_pk_mul_f32 v[126:127], v[126:127], v[198:199] op_sel_hi:[1,0]
	v_pk_mul_f32 v[124:125], v[124:125], v[198:199] op_sel_hi:[1,0]
	v_pk_mul_f32 v[122:123], v[122:123], v[198:199] op_sel_hi:[1,0]
	v_pk_mul_f32 v[120:121], v[120:121], v[198:199] op_sel_hi:[1,0]
	v_cvt_pk_bf16_f32 v124, v124, v125
	v_cvt_pk_bf16_f32 v125, v126, v127
	v_cvt_pk_bf16_f32 v127, v122, v123
	v_lshl_or_b32 v122, s5, 8, v172
	v_cvt_pk_bf16_f32 v126, v120, v121
	v_ashrrev_i32_e32 v123, 31, v122
	v_mov_b64_e32 v[120:121], s[2:3]
	v_mad_i64_i32 v[168:169], s[4:5], v168, s76, v[120:121]
	v_lshlrev_b64 v[122:123], 1, v[122:123]
	v_lshl_add_u64 v[168:169], v[168:169], 0, v[122:123]
	global_store_dwordx4 v[168:169], v[124:127], off
	v_mov_b32_e32 v194, v202
	v_mov_b32_e32 v195, v206
	v_pk_add_f32 v[124:125], v[178:179], v[180:181]
	v_pk_add_f32 v[126:127], v[182:183], v[184:185]
	v_mov_b32_e32 v179, v124
	v_mov_b32_e32 v178, v126
	v_mov_b32_e32 v124, v127
	v_pk_add_f32 v[124:125], v[178:179], v[124:125]
	ds_bpermute_b32 v127, v157, v125
	ds_bpermute_b32 v126, v157, v124
	v_mov_b32_e32 v206, v203
	v_mov_b32_e32 v196, v204
	v_mov_b32_e32 v197, v208
	v_mov_b32_e32 v208, v205
	v_mov_b32_e32 v202, v212
	v_mov_b32_e32 v203, v216
	v_mov_b32_e32 v216, v213
	v_mov_b32_e32 v204, v214
	v_mov_b32_e32 v205, v218
	v_mov_b32_e32 v218, v215
	v_pk_add_f32 v[186:187], v[194:195], v[206:207]
	v_pk_add_f32 v[188:189], v[196:197], v[208:209]
	v_pk_add_f32 v[190:191], v[202:203], v[216:217]
	v_pk_add_f32 v[192:193], v[204:205], v[218:219]
	v_pk_mul_f32 v[178:179], v[114:115], v[198:199] op_sel_hi:[1,0]
	s_waitcnt lgkmcnt(0)
	v_pk_add_f32 v[114:115], v[124:125], v[126:127]
	v_pk_add_f32 v[126:127], v[186:187], v[188:189]
	v_pk_add_f32 v[180:181], v[190:191], v[192:193]
	v_mov_b32_e32 v183, v126
	v_mov_b32_e32 v182, v180
	v_mov_b32_e32 v126, v181
	v_pk_add_f32 v[126:127], v[182:183], v[126:127]
	ds_bpermute_b32 v125, v155, v115
	ds_bpermute_b32 v124, v155, v114
	ds_bpermute_b32 v181, v157, v127
	ds_bpermute_b32 v180, v157, v126
	v_mul_f32_e32 v129, 0x4b800000, v128
	v_cmp_gt_f32_e32 vcc, s73, v128
	s_waitcnt lgkmcnt(2)
	v_pk_add_f32 v[114:115], v[114:115], v[124:125]
	v_mov_b32_e32 v194, v220
	s_waitcnt lgkmcnt(0)
	v_pk_add_f32 v[124:125], v[126:127], v[180:181]
	ds_bpermute_b32 v127, v155, v125
	ds_bpermute_b32 v126, v155, v124
	v_pk_fma_f32 v[114:115], v[114:115], s[24:25], v[130:131] op_sel_hi:[1,0,0]
	v_cndmask_b32_e32 v159, v128, v129, vcc
	v_mul_f32_e32 v128, 0x4b800000, v115
	v_cmp_gt_f32_e64 s[4:5], s73, v115
	v_cmp_gt_f32_e64 s[6:7], s73, v114
	v_mov_b32_e32 v195, v224
	v_cndmask_b32_e64 v161, v115, v128, s[4:5]
	v_mul_f32_e32 v115, 0x4b800000, v114
	v_mov_b32_e32 v224, v221
	v_mov_b32_e32 v196, v222
	v_mov_b32_e32 v197, v226
	v_mov_b32_e32 v226, v223
	v_cndmask_b32_e64 v163, v114, v115, s[6:7]
	s_waitcnt lgkmcnt(0)
	v_pk_add_f32 v[114:115], v[124:125], v[126:127]
	v_pk_add_f32 v[132:133], v[194:195], v[224:225]
	v_pk_add_f32 v[134:135], v[196:197], v[226:227]
	v_mov_b32_e32 v194, v228
	v_mov_b32_e32 v195, v232
	v_mov_b32_e32 v232, v229
	v_mov_b32_e32 v196, v230
	v_mov_b32_e32 v197, v234
	v_mov_b32_e32 v234, v231
	v_pk_fma_f32 v[114:115], v[114:115], s[24:25], v[130:131] op_sel_hi:[1,0,0]
	v_pk_add_f32 v[194:195], v[194:195], v[232:233]
	v_pk_add_f32 v[196:197], v[196:197], v[234:235]
	v_mul_f32_e32 v124, 0x4b800000, v115
	v_cmp_gt_f32_e64 s[8:9], s73, v115
	v_pk_add_f32 v[126:127], v[194:195], v[196:197]
	v_cmp_gt_f32_e64 s[10:11], s73, v114
	v_cndmask_b32_e64 v165, v115, v124, s[8:9]
	v_pk_add_f32 v[124:125], v[132:133], v[134:135]
	v_mov_b32_e32 v128, v126
	v_mov_b32_e32 v129, v124
	v_mov_b32_e32 v124, v127
	v_pk_add_f32 v[124:125], v[128:129], v[124:125]
	ds_bpermute_b32 v127, v157, v125
	ds_bpermute_b32 v126, v157, v124
	v_rsq_f32_e32 v128, v159
	v_mul_f32_e32 v115, 0x4b800000, v114
	v_cndmask_b32_e64 v129, v114, v115, s[10:11]
	v_pk_mul_f32 v[116:117], v[116:117], v[198:199] op_sel_hi:[1,0]
	s_waitcnt lgkmcnt(0)
	v_pk_add_f32 v[114:115], v[124:125], v[126:127]
	ds_bpermute_b32 v125, v155, v115
	ds_bpermute_b32 v124, v155, v114
	v_mul_f32_e32 v126, 0x45800000, v128
	v_rsq_f32_e32 v127, v161
	v_cndmask_b32_e32 v126, v128, v126, vcc
	v_rsq_f32_e32 v128, v163
	s_waitcnt lgkmcnt(0)
; DI unsigned pack2(float lo, float hi) { f32x2 v = {lo, hi}; bf16v2 r = __builtin_convertvector(v, bf16v2); return __builtin_bit_cast(unsigned, r); }
;   DI void operator()(const f32x4 (&acc)[2][2][4][2], const Unit& u, int wr, int wc, int fr, int fq) const {
;     ...
; #pragma unroll
;     for (int ai = 0; ai < 2; ++ai)
; #pragma unroll
;       for (int m = 0; m < 4; ++m) {
;         const int row = row0 + ai * HALF + m * 16;
;         const float rs = rsv[ai][m];
;         bf16_t* rowp = O + (size_t)row * ldc + col0;
; #pragma unroll
;         for (int bj = 0; bj < 2; ++bj) {
;           const f32x4 v0 = acc[ai][bj][m][0] * rs, v1 = acc[ai][bj][m][1] * rs;
;           u32x4 w; w.x = pack2(v0[0], v0[1]); w.y = pack2(v0[2], v0[3]); w.z = pack2(v1[0], v1[1]); w.w = pack2(v1[2], v1[3]);
;           *(u32x4*)(rowp + bj * HALF) = w;
;         }
	v_pk_add_f32 v[114:115], v[114:115], v[124:125]
	v_mul_f32_e32 v124, 0x45800000, v127
	v_cndmask_b32_e64 v124, v127, v124, s[4:5]
	v_mul_f32_e32 v127, 0x45800000, v128
	v_pk_fma_f32 v[114:115], v[114:115], s[24:25], v[130:131] op_sel_hi:[1,0,0]
	v_rsq_f32_e32 v125, v165
	v_cndmask_b32_e64 v128, v128, v127, s[6:7]
	v_rsq_f32_e32 v127, v129
	v_mul_f32_e32 v129, 0x4b800000, v115
	v_cmp_gt_f32_e32 vcc, s73, v115
	v_cmp_gt_f32_e64 s[4:5], s73, v114
	v_pk_mul_f32 v[118:119], v[118:119], v[198:199] op_sel_hi:[1,0]
	v_cndmask_b32_e32 v129, v115, v129, vcc
	v_mul_f32_e32 v115, 0x4b800000, v114
	v_cndmask_b32_e64 v131, v114, v115, s[4:5]
	v_cvt_pk_bf16_f32 v114, v116, v117
	v_rsq_f32_e32 v117, v129
	v_cvt_pk_bf16_f32 v115, v118, v119
	v_rsq_f32_e32 v119, v131
	v_mul_f32_e32 v116, 0x45800000, v125
	v_pk_mul_f32 v[112:113], v[112:113], v[198:199] op_sel_hi:[1,0]
	v_cndmask_b32_e64 v118, v125, v116, s[8:9]
	v_mul_f32_e32 v116, 0x45800000, v127
	v_cndmask_b32_e64 v130, v127, v116, s[10:11]
	v_cvt_pk_bf16_f32 v116, v112, v113
	v_mul_f32_e32 v112, 0x45800000, v117
	v_cndmask_b32_e32 v132, v117, v112, vcc
	v_mul_f32_e32 v112, 0x45800000, v119
	v_cvt_pk_bf16_f32 v117, v178, v179
	v_cndmask_b32_e64 v112, v119, v112, s[4:5]
	global_store_dwordx4 v[168:169], v[114:117], off offset:256
	v_pk_mul_f32 v[110:111], v[110:111], v[126:127] op_sel_hi:[1,0]
	v_pk_mul_f32 v[108:109], v[108:109], v[126:127] op_sel_hi:[1,0]
	v_mad_i64_i32 v[114:115], s[4:5], v154, s76, v[120:121]
	v_pk_mul_f32 v[116:117], v[106:107], v[126:127] op_sel_hi:[1,0]
	v_pk_mul_f32 v[106:107], v[104:105], v[126:127] op_sel_hi:[1,0]
	v_lshl_add_u64 v[114:115], v[114:115], 0, v[122:123]
	v_cvt_pk_bf16_f32 v104, v108, v109
	v_cvt_pk_bf16_f32 v105, v110, v111
	v_cvt_pk_bf16_f32 v106, v106, v107
	v_cvt_pk_bf16_f32 v107, v116, v117
	global_store_dwordx4 v[114:115], v[104:107], off
	v_pk_mul_f32 v[98:99], v[98:99], v[126:127] op_sel_hi:[1,0]
	v_pk_mul_f32 v[96:97], v[96:97], v[126:127] op_sel_hi:[1,0]
	v_pk_mul_f32 v[104:105], v[90:91], v[126:127] op_sel_hi:[1,0]
	v_pk_mul_f32 v[90:91], v[88:89], v[126:127] op_sel_hi:[1,0]
	v_cvt_pk_bf16_f32 v88, v96, v97
	v_cvt_pk_bf16_f32 v89, v98, v99
	v_cvt_pk_bf16_f32 v90, v90, v91
	v_cvt_pk_bf16_f32 v91, v104, v105
	global_store_dwordx4 v[114:115], v[88:91], off offset:256
	v_pk_mul_f32 v[94:95], v[94:95], v[124:125] op_sel_hi:[1,0]
	v_pk_mul_f32 v[92:93], v[92:93], v[124:125] op_sel_hi:[1,0]
	v_mad_i64_i32 v[88:89], s[4:5], v160, s76, v[120:121]
	v_lshl_add_u64 v[96:97], v[88:89], 0, v[122:123]
	v_pk_mul_f32 v[90:91], v[102:103], v[124:125] op_sel_hi:[1,0]
	v_pk_mul_f32 v[88:89], v[100:101], v[124:125] op_sel_hi:[1,0]
	v_pk_mul_f32 v[82:83], v[82:83], v[124:125] op_sel_hi:[1,0]
	v_cvt_pk_bf16_f32 v88, v88, v89
	v_cvt_pk_bf16_f32 v89, v90, v91
	v_cvt_pk_bf16_f32 v90, v92, v93
	v_cvt_pk_bf16_f32 v91, v94, v95
	global_store_dwordx4 v[96:97], v[88:91], off
	v_pk_mul_f32 v[80:81], v[80:81], v[124:125] op_sel_hi:[1,0]
	v_pk_mul_f32 v[78:79], v[78:79], v[128:129] op_sel_hi:[1,0]
	v_pk_mul_f32 v[88:89], v[74:75], v[124:125] op_sel_hi:[1,0]
	v_pk_mul_f32 v[74:75], v[72:73], v[124:125] op_sel_hi:[1,0]
	v_cvt_pk_bf16_f32 v72, v80, v81
	v_cvt_pk_bf16_f32 v73, v82, v83
	v_cvt_pk_bf16_f32 v74, v74, v75
	v_cvt_pk_bf16_f32 v75, v88, v89
	global_store_dwordx4 v[96:97], v[72:75], off offset:256
	v_pk_mul_f32 v[76:77], v[76:77], v[128:129] op_sel_hi:[1,0]
	v_pk_mul_f32 v[70:71], v[70:71], v[128:129] op_sel_hi:[1,0]
	v_mad_i64_i32 v[72:73], s[4:5], v156, s76, v[120:121]
	v_lshl_add_u64 v[80:81], v[72:73], 0, v[122:123]
	v_pk_mul_f32 v[74:75], v[86:87], v[128:129] op_sel_hi:[1,0]
	v_pk_mul_f32 v[72:73], v[84:85], v[128:129] op_sel_hi:[1,0]
	v_pk_mul_f32 v[68:69], v[68:69], v[128:129] op_sel_hi:[1,0]
	v_cvt_pk_bf16_f32 v72, v72, v73
	v_cvt_pk_bf16_f32 v73, v74, v75
	v_cvt_pk_bf16_f32 v74, v76, v77
	v_cvt_pk_bf16_f32 v75, v78, v79
	global_store_dwordx4 v[80:81], v[72:75], off
	v_pk_mul_f32 v[62:63], v[62:63], v[118:119] op_sel_hi:[1,0]
	v_pk_mul_f32 v[60:61], v[60:61], v[118:119] op_sel_hi:[1,0]
	v_pk_mul_f32 v[72:73], v[66:67], v[128:129] op_sel_hi:[1,0]
	v_pk_mul_f32 v[66:67], v[64:65], v[128:129] op_sel_hi:[1,0]
; DI unsigned pack2(float lo, float hi) { f32x2 v = {lo, hi}; bf16v2 r = __builtin_convertvector(v, bf16v2); return __builtin_bit_cast(unsigned, r); }
; #define PG8_WAIT_V(n) asm volatile("s_waitcnt vmcnt(" #n ")" ::: "memory")
; #define PG8_BAR __builtin_amdgcn_s_barrier()
;   DI void operator()(const f32x4 (&acc)[2][2][4][2], const Unit& u, int wr, int wc, int fr, int fq) const {
;     ...
; #pragma unroll
;     for (int ai = 0; ai < 2; ++ai)
; #pragma unroll
;       for (int m = 0; m < 4; ++m) {
;         const int row = row0 + ai * HALF + m * 16;
;         const float rs = rsv[ai][m];
;         bf16_t* rowp = O + (size_t)row * ldc + col0;
; #pragma unroll
;         for (int bj = 0; bj < 2; ++bj) {
;           const f32x4 v0 = acc[ai][bj][m][0] * rs, v1 = acc[ai][bj][m][1] * rs;
;           u32x4 w; w.x = pack2(v0[0], v0[1]); w.y = pack2(v0[2], v0[3]); w.z = pack2(v1[0], v1[1]); w.w = pack2(v1[2], v1[3]);
;           *(u32x4*)(rowp + bj * HALF) = w;
;         }
;       }
;   }
; template <class Epi, class Sched = StaticOrder>
; DI void gemm_phase(LAS unsigned char* lds, const Gemm g, const Sched& S, const Epi& E) {
;     ...
;     E(acc, cur, wr, wc, fr, fq);
;     if (!has_next) break;
; #pragma unroll
;     for (int a = 0; a < 2; ++a)
; #pragma unroll
;       for (int b = 0; b < 2; ++b)
; #pragma unroll
;         for (int m = 0; m < 4; ++m)
; #pragma unroll
;           for (int n = 0; n < 2; ++n) acc[a][b][m][n] = (f32x4){0.f, 0.f, 0.f, 0.f};
;     cur = nxt; cA = nA; cB = nB; ++ui;
;   }
;   PG8_WAIT_V(0);
;   if (wr == 0) PG8_BAR;
	v_cvt_pk_bf16_f32 v64, v68, v69
	v_cvt_pk_bf16_f32 v65, v70, v71
	v_cvt_pk_bf16_f32 v66, v66, v67
	v_cvt_pk_bf16_f32 v67, v72, v73
	global_store_dwordx4 v[80:81], v[64:67], off offset:256
	v_pk_mul_f32 v[50:51], v[50:51], v[118:119] op_sel_hi:[1,0]
	v_pk_mul_f32 v[48:49], v[48:49], v[118:119] op_sel_hi:[1,0]
	v_mad_i64_i32 v[64:65], s[4:5], v164, s76, v[120:121]
	v_pk_mul_f32 v[66:67], v[58:59], v[118:119] op_sel_hi:[1,0]
	v_pk_mul_f32 v[58:59], v[56:57], v[118:119] op_sel_hi:[1,0]
	v_lshl_add_u64 v[64:65], v[64:65], 0, v[122:123]
	v_cvt_pk_bf16_f32 v56, v60, v61
	v_cvt_pk_bf16_f32 v57, v62, v63
	v_cvt_pk_bf16_f32 v58, v58, v59
	v_cvt_pk_bf16_f32 v59, v66, v67
	global_store_dwordx4 v[64:65], v[56:59], off
	v_pk_mul_f32 v[46:47], v[46:47], v[130:131] op_sel_hi:[1,0]
	v_pk_mul_f32 v[44:45], v[44:45], v[130:131] op_sel_hi:[1,0]
	v_pk_mul_f32 v[56:57], v[42:43], v[118:119] op_sel_hi:[1,0]
	v_pk_mul_f32 v[42:43], v[40:41], v[118:119] op_sel_hi:[1,0]
	v_cvt_pk_bf16_f32 v40, v48, v49
	v_cvt_pk_bf16_f32 v41, v50, v51
	v_cvt_pk_bf16_f32 v42, v42, v43
	v_cvt_pk_bf16_f32 v43, v56, v57
	global_store_dwordx4 v[64:65], v[40:43], off offset:256
	v_pk_mul_f32 v[34:35], v[34:35], v[130:131] op_sel_hi:[1,0]
	v_pk_mul_f32 v[32:33], v[32:33], v[130:131] op_sel_hi:[1,0]
	v_mad_i64_i32 v[40:41], s[4:5], v158, s76, v[120:121]
	v_lshl_add_u64 v[48:49], v[40:41], 0, v[122:123]
	v_pk_mul_f32 v[42:43], v[54:55], v[130:131] op_sel_hi:[1,0]
	v_pk_mul_f32 v[40:41], v[52:53], v[130:131] op_sel_hi:[1,0]
	v_pk_mul_f32 v[30:31], v[30:31], v[132:133] op_sel_hi:[1,0]
	v_cvt_pk_bf16_f32 v40, v40, v41
	v_cvt_pk_bf16_f32 v41, v42, v43
	v_cvt_pk_bf16_f32 v42, v44, v45
	v_cvt_pk_bf16_f32 v43, v46, v47
	global_store_dwordx4 v[48:49], v[40:43], off
	v_pk_mul_f32 v[28:29], v[28:29], v[132:133] op_sel_hi:[1,0]
	v_pk_mul_f32 v[18:19], v[18:19], v[132:133] op_sel_hi:[1,0]
	v_pk_mul_f32 v[40:41], v[26:27], v[130:131] op_sel_hi:[1,0]
	v_pk_mul_f32 v[26:27], v[24:25], v[130:131] op_sel_hi:[1,0]
	v_cvt_pk_bf16_f32 v24, v32, v33
	v_cvt_pk_bf16_f32 v25, v34, v35
	v_cvt_pk_bf16_f32 v26, v26, v27
	v_cvt_pk_bf16_f32 v27, v40, v41
	global_store_dwordx4 v[48:49], v[24:27], off offset:256
	v_pk_mul_f32 v[16:17], v[16:17], v[132:133] op_sel_hi:[1,0]
	v_pk_mul_f32 v[14:15], v[14:15], v[112:113] op_sel_hi:[1,0]
	v_mad_i64_i32 v[24:25], s[4:5], v166, s76, v[120:121]
	v_lshl_add_u64 v[32:33], v[24:25], 0, v[122:123]
	v_pk_mul_f32 v[26:27], v[38:39], v[132:133] op_sel_hi:[1,0]
	v_pk_mul_f32 v[24:25], v[36:37], v[132:133] op_sel_hi:[1,0]
	v_pk_mul_f32 v[12:13], v[12:13], v[112:113] op_sel_hi:[1,0]
	v_cvt_pk_bf16_f32 v24, v24, v25
	v_cvt_pk_bf16_f32 v25, v26, v27
	v_cvt_pk_bf16_f32 v26, v28, v29
	v_cvt_pk_bf16_f32 v27, v30, v31
	global_store_dwordx4 v[32:33], v[24:27], off
	v_pk_mul_f32 v[6:7], v[6:7], v[112:113] op_sel_hi:[1,0]
	v_pk_mul_f32 v[4:5], v[4:5], v[112:113] op_sel_hi:[1,0]
	v_pk_mul_f32 v[24:25], v[10:11], v[132:133] op_sel_hi:[1,0]
	v_pk_mul_f32 v[10:11], v[8:9], v[132:133] op_sel_hi:[1,0]
	v_cvt_pk_bf16_f32 v8, v16, v17
	v_cvt_pk_bf16_f32 v9, v18, v19
	v_cvt_pk_bf16_f32 v10, v10, v11
	v_cvt_pk_bf16_f32 v11, v24, v25
	global_store_dwordx4 v[32:33], v[8:11], off offset:256
	s_and_b64 vcc, exec, s[0:1]
	s_mov_b64 s[8:9], s[36:37]
	v_mad_i64_i32 v[8:9], s[4:5], v162, s76, v[120:121]
	v_lshl_add_u64 v[16:17], v[8:9], 0, v[122:123]
	v_pk_mul_f32 v[10:11], v[22:23], v[112:113] op_sel_hi:[1,0]
	v_pk_mul_f32 v[8:9], v[20:21], v[112:113] op_sel_hi:[1,0]
	s_mov_b32 s5, s28
	v_cvt_pk_bf16_f32 v8, v8, v9
	v_cvt_pk_bf16_f32 v9, v10, v11
	v_cvt_pk_bf16_f32 v10, v12, v13
	v_cvt_pk_bf16_f32 v11, v14, v15
	global_store_dwordx4 v[16:17], v[8:11], off
	s_mov_b32 s4, s30
	s_mov_b64 s[6:7], s[34:35]
	v_pk_mul_f32 v[8:9], v[2:3], v[112:113] op_sel_hi:[1,0]
	v_pk_mul_f32 v[2:3], v[0:1], v[112:113] op_sel_hi:[1,0]
	v_cvt_pk_bf16_f32 v0, v4, v5
	v_cvt_pk_bf16_f32 v1, v6, v7
	v_cvt_pk_bf16_f32 v2, v2, v3
	v_cvt_pk_bf16_f32 v3, v8, v9
	global_store_dwordx4 v[16:17], v[0:3], off offset:256
	s_cbranch_vccz .LBB0_343
	s_waitcnt vmcnt(0)
	s_cmpk_gt_u32 s27, 0xff
	s_cbranch_scc1 .LBB0_350
	s_barrier

; #define PG8_STAGE(bufoff, gbase, voff) do { _Pragma("unroll") for (int _i = 0; _i < 2; ++_i) \
;     __builtin_amdgcn_global_load_lds((const unsigned*)((const char*)(gbase) + (voff)[_i]), (LAS unsigned*)(lds + (bufoff) + ldsw + _i * 8192), 16, 0, 0); } while (0)
; #define PG8_LDA(dst, b, h) do { _Pragma("unroll") for (int m = 0; m < 4; ++m) _Pragma("unroll") for (int k = 0; k < 2; ++k) dst[m][k] = *(const LAS bf16x8*)(lds + PG8_SA(b, h) + aoff + m * 2048 + k * 1024); } while (0)
; #define PG8_LDB(dst, b, h) do { _Pragma("unroll") for (int n = 0; n < 2; ++n) _Pragma("unroll") for (int k = 0; k < 2; ++k) dst[n][k] = *(const LAS bf16x8*)(lds + PG8_SB(b, h) + boff + n * 2048 + k * 1024); } while (0)
; #define PG8_MMA(ai, bj, At, Bt) do { __builtin_amdgcn_s_setprio(1); _Pragma("unroll") for (int m = 0; m < 4; ++m) _Pragma("unroll") for (int n = 0; n < 2; ++n) _Pragma("unroll") for (int k = 0; k < 2; ++k) \
;     acc[ai][bj][m][n] = __builtin_amdgcn_mfma_f32_16x16x32_bf16(Bt[n][k], At[m][k], acc[ai][bj][m][n], 0, 0, 0); __builtin_amdgcn_s_setprio(0); } while (0)
; #define PG8_WAIT_V(n) asm volatile("s_waitcnt vmcnt(" #n ")" ::: "memory")
; #define PG8_WAIT_L(n) asm volatile("s_waitcnt lgkmcnt(" #n ")" ::: "memory")
; #define PG8_BAR __builtin_amdgcn_s_barrier()
; #define PG8_SCHED __builtin_amdgcn_sched_barrier(0)
; template <class Epi, class Sched = StaticOrder>
; DI void gemm_phase(LAS unsigned char* lds, const Gemm g, const Sched& S, const Epi& E) {
;     ...
;     for (int t = 0; t < nt; t += 2) {
;       const bool last = (t == nt - 2);
;       const char* a1 = cA + (size_t)(t + 1) * kstep;
;       const char* a2 = last ? nA : cA + (size_t)(t + 2) * kstep; const char* b2 = last ? nB : cB + (size_t)(t + 2) * kstep;
;       const char* a3 = a2 + kstep; const char* b3 = b2 + kstep;
;       PG8_LDB(B0, 0, 0); PG8_SCHED; PG8_LDA(At, 0, 0); PG8_STAGE(PG8_SA(1, 1), a1 + hstep, voffA);
;       PG8_WAIT_L(8); PG8_BAR; PG8_WAIT_L(0); PG8_MMA(0, 0, At, B0); PG8_BAR; PG8_SCHED;
;       PG8_LDB(B1, 0, 1); PG8_STAGE(PG8_SB(0, 0), b2, voffB);
;       PG8_BAR; PG8_WAIT_L(0); PG8_MMA(0, 1, At, B1); PG8_BAR;
;       PG8_LDA(At, 0, 1); PG8_STAGE(PG8_SA(0, 0), a2, voffA);
;       PG8_BAR; PG8_WAIT_L(0); PG8_MMA(1, 0, At, B0); PG8_BAR; PG8_SCHED;
;       PG8_STAGE(PG8_SB(0, 1), b2 + hstep, voffB);
;       PG8_WAIT_V(6); PG8_BAR; PG8_MMA(1, 1, At, B1); PG8_BAR;
.LBB0_728:
	ds_read_b128 v[128:131], v207
	ds_read_b128 v[132:135], v207 offset:1024
	ds_read_b128 v[136:139], v207 offset:2048
	ds_read_b128 v[140:143], v207 offset:3072
	s_add_u32 s24, s22, 0xfff80080
	s_addc_u32 s25, s23, -1
	s_cmp_eq_u32 s53, 28
	s_cselect_b32 s27, s17, s25
	s_cselect_b32 s26, s43, s24
	s_cselect_b32 s25, s15, s52
	s_cselect_b32 s24, s44, s45
	v_lshl_add_u64 v[192:193], s[22:23], 0, v[184:185]
	s_add_i32 m0, s37, 0xc000
	ds_read_b128 v[144:147], v208
	ds_read_b128 v[148:151], v208 offset:1024
	ds_read_b128 v[152:155], v208 offset:2048
	ds_read_b128 v[156:159], v208 offset:3072
	ds_read_b128 v[160:163], v208 offset:4096
	ds_read_b128 v[164:167], v208 offset:5120
	ds_read_b128 v[168:171], v208 offset:6144
	ds_read_b128 v[172:175], v208 offset:7168
	global_load_lds_dwordx4 v[192:193], off
	v_lshl_add_u64 v[192:193], s[22:23], 0, v[186:187]
	s_add_i32 m0, s37, 0xe000
	s_nop 0
	global_load_lds_dwordx4 v[192:193], off
	s_waitcnt lgkmcnt(8)
	s_barrier
	s_waitcnt lgkmcnt(0)
	s_setprio 1
	v_mfma_f32_16x16x32_bf16 v[124:127], v[128:131], v[144:147], v[124:127]
	v_mfma_f32_16x16x32_bf16 v[120:123], v[136:139], v[144:147], v[120:123]
	v_mfma_f32_16x16x32_bf16 v[108:111], v[128:131], v[152:155], v[108:111]
	v_mfma_f32_16x16x32_bf16 v[104:107], v[136:139], v[152:155], v[104:107]
	v_mfma_f32_16x16x32_bf16 v[92:95], v[128:131], v[160:163], v[92:95]
	v_mfma_f32_16x16x32_bf16 v[88:91], v[136:139], v[160:163], v[88:91]
	v_mfma_f32_16x16x32_bf16 v[76:79], v[128:131], v[168:171], v[76:79]
	v_mfma_f32_16x16x32_bf16 v[72:75], v[136:139], v[168:171], v[72:75]
	v_mfma_f32_16x16x32_bf16 v[124:127], v[132:135], v[148:151], v[124:127]
	v_mfma_f32_16x16x32_bf16 v[120:123], v[140:143], v[148:151], v[120:123]
	v_mfma_f32_16x16x32_bf16 v[108:111], v[132:135], v[156:159], v[108:111]
	v_mfma_f32_16x16x32_bf16 v[104:107], v[140:143], v[156:159], v[104:107]
	v_mfma_f32_16x16x32_bf16 v[92:95], v[132:135], v[164:167], v[92:95]
	v_mfma_f32_16x16x32_bf16 v[88:91], v[140:143], v[164:167], v[88:91]
	v_mfma_f32_16x16x32_bf16 v[76:79], v[132:135], v[172:175], v[76:79]
	v_mfma_f32_16x16x32_bf16 v[72:75], v[140:143], v[172:175], v[72:75]
	s_barrier
	s_setprio 0
	s_add_i32 s54, s50, s35
	v_lshl_add_u64 v[216:217], s[24:25], 0, v[180:181]
	s_mov_b32 m0, s54
	ds_read_b128 v[192:195], v209
	ds_read_b128 v[196:199], v209 offset:1024
	ds_read_b128 v[200:203], v209 offset:2048
	ds_read_b128 v[212:215], v209 offset:3072
	global_load_lds_dwordx4 v[216:217], off
	v_lshl_add_u64 v[218:219], s[24:25], 0, v[176:177]
	s_add_i32 m0, s54, 0x2000
	s_nop 0
	global_load_lds_dwordx4 v[218:219], off
	s_barrier
	s_waitcnt lgkmcnt(0)
	s_setprio 1
	v_mfma_f32_16x16x32_bf16 v[116:119], v[192:195], v[144:147], v[116:119]
	v_mfma_f32_16x16x32_bf16 v[112:115], v[200:203], v[144:147], v[112:115]
	v_mfma_f32_16x16x32_bf16 v[100:103], v[192:195], v[152:155], v[100:103]
	v_mfma_f32_16x16x32_bf16 v[96:99], v[200:203], v[152:155], v[96:99]
	v_mfma_f32_16x16x32_bf16 v[84:87], v[192:195], v[160:163], v[84:87]
	v_mfma_f32_16x16x32_bf16 v[80:83], v[200:203], v[160:163], v[80:83]
	v_mfma_f32_16x16x32_bf16 v[68:71], v[192:195], v[168:171], v[68:71]
	v_mfma_f32_16x16x32_bf16 v[64:67], v[200:203], v[168:171], v[64:67]
	v_mfma_f32_16x16x32_bf16 v[116:119], v[196:199], v[148:151], v[116:119]
	v_mfma_f32_16x16x32_bf16 v[112:115], v[212:215], v[148:151], v[112:115]
	v_mfma_f32_16x16x32_bf16 v[100:103], v[196:199], v[156:159], v[100:103]
	v_mfma_f32_16x16x32_bf16 v[96:99], v[212:215], v[156:159], v[96:99]
	v_mfma_f32_16x16x32_bf16 v[84:87], v[196:199], v[164:167], v[84:87]
	v_mfma_f32_16x16x32_bf16 v[80:83], v[212:215], v[164:167], v[80:83]
	v_mfma_f32_16x16x32_bf16 v[68:71], v[196:199], v[172:175], v[68:71]
	v_mfma_f32_16x16x32_bf16 v[64:67], v[212:215], v[172:175], v[64:67]
	s_barrier
	s_setprio 0
	s_mov_b32 m0, s37
	v_lshl_add_u64 v[220:221], s[26:27], 0, v[182:183]
	ds_read_b128 v[144:147], v208 offset:16384
	ds_read_b128 v[148:151], v208 offset:17408
	ds_read_b128 v[152:155], v208 offset:18432
	ds_read_b128 v[156:159], v208 offset:19456
	ds_read_b128 v[160:163], v208 offset:20480
	ds_read_b128 v[164:167], v208 offset:21504
	ds_read_b128 v[168:171], v208 offset:22528
	ds_read_b128 v[172:175], v208 offset:23552
	global_load_lds_dwordx4 v[220:221], off
	v_lshl_add_u64 v[222:223], s[26:27], 0, v[178:179]
	s_mov_b32 m0, s38
	s_nop 0
	global_load_lds_dwordx4 v[222:223], off
	s_barrier
	s_waitcnt lgkmcnt(0)
	s_setprio 1
	v_mfma_f32_16x16x32_bf16 v[60:63], v[128:131], v[144:147], v[60:63]
	v_mfma_f32_16x16x32_bf16 v[56:59], v[136:139], v[144:147], v[56:59]
	v_mfma_f32_16x16x32_bf16 v[44:47], v[128:131], v[152:155], v[44:47]
	v_mfma_f32_16x16x32_bf16 v[40:43], v[136:139], v[152:155], v[40:43]
	v_mfma_f32_16x16x32_bf16 v[28:31], v[128:131], v[160:163], v[28:31]
	v_mfma_f32_16x16x32_bf16 v[24:27], v[136:139], v[160:163], v[24:27]
	v_mfma_f32_16x16x32_bf16 v[12:15], v[128:131], v[168:171], v[12:15]
	v_mfma_f32_16x16x32_bf16 v[8:11], v[136:139], v[168:171], v[8:11]
	v_mfma_f32_16x16x32_bf16 v[60:63], v[132:135], v[148:151], v[60:63]
	v_mfma_f32_16x16x32_bf16 v[56:59], v[140:143], v[148:151], v[56:59]
	v_mfma_f32_16x16x32_bf16 v[44:47], v[132:135], v[156:159], v[44:47]
	v_mfma_f32_16x16x32_bf16 v[40:43], v[140:143], v[156:159], v[40:43]
	v_mfma_f32_16x16x32_bf16 v[28:31], v[132:135], v[164:167], v[28:31]
	v_mfma_f32_16x16x32_bf16 v[24:27], v[140:143], v[164:167], v[24:27]
	v_mfma_f32_16x16x32_bf16 v[12:15], v[132:135], v[172:175], v[12:15]
	v_mfma_f32_16x16x32_bf16 v[8:11], v[140:143], v[172:175], v[8:11]
	s_barrier
; #define PG8_STAGE(bufoff, gbase, voff) do { _Pragma("unroll") for (int _i = 0; _i < 2; ++_i) \
;     __builtin_amdgcn_global_load_lds((const unsigned*)((const char*)(gbase) + (voff)[_i]), (LAS unsigned*)(lds + (bufoff) + ldsw + _i * 8192), 16, 0, 0); } while (0)
; #define PG8_LDA(dst, b, h) do { _Pragma("unroll") for (int m = 0; m < 4; ++m) _Pragma("unroll") for (int k = 0; k < 2; ++k) dst[m][k] = *(const LAS bf16x8*)(lds + PG8_SA(b, h) + aoff + m * 2048 + k * 1024); } while (0)
; #define PG8_LDB(dst, b, h) do { _Pragma("unroll") for (int n = 0; n < 2; ++n) _Pragma("unroll") for (int k = 0; k < 2; ++k) dst[n][k] = *(const LAS bf16x8*)(lds + PG8_SB(b, h) + boff + n * 2048 + k * 1024); } while (0)
; #define PG8_MMA(ai, bj, At, Bt) do { __builtin_amdgcn_s_setprio(1); _Pragma("unroll") for (int m = 0; m < 4; ++m) _Pragma("unroll") for (int n = 0; n < 2; ++n) _Pragma("unroll") for (int k = 0; k < 2; ++k) \
;     acc[ai][bj][m][n] = __builtin_amdgcn_mfma_f32_16x16x32_bf16(Bt[n][k], At[m][k], acc[ai][bj][m][n], 0, 0, 0); __builtin_amdgcn_s_setprio(0); } while (0)
; #define PG8_WAIT_V(n) asm volatile("s_waitcnt vmcnt(" #n ")" ::: "memory")
; #define PG8_WAIT_L(n) asm volatile("s_waitcnt lgkmcnt(" #n ")" ::: "memory")
; #define PG8_BAR __builtin_amdgcn_s_barrier()
; #define PG8_SCHED __builtin_amdgcn_sched_barrier(0)
; template <class Epi, class Sched = StaticOrder>
; DI void gemm_phase(LAS unsigned char* lds, const Gemm g, const Sched& S, const Epi& E) {
;     ...
;       PG8_STAGE(PG8_SB(0, 1), b2 + hstep, voffB);
;       PG8_WAIT_V(6); PG8_BAR; PG8_MMA(1, 1, At, B1); PG8_BAR;
;       PG8_LDB(B0, 1, 0); PG8_SCHED; PG8_LDA(At, 1, 0); PG8_STAGE(PG8_SA(0, 1), a2 + hstep, voffA);
;       PG8_WAIT_L(8); PG8_BAR; PG8_WAIT_L(0); PG8_MMA(0, 0, At, B0); PG8_BAR; PG8_SCHED;
;       PG8_LDB(B1, 1, 1); PG8_STAGE(PG8_SB(1, 0), b3, voffB);
;       PG8_BAR; PG8_WAIT_L(0); PG8_MMA(0, 1, At, B1); PG8_BAR;
;       PG8_LDA(At, 1, 1); PG8_STAGE(PG8_SA(1, 0), a3, voffA);
;       PG8_BAR; PG8_WAIT_L(0); PG8_MMA(1, 0, At, B0); PG8_BAR; PG8_SCHED;
	s_setprio 0
	s_add_u32 s54, s24, 0x80000
	s_addc_u32 s55, s25, 0
	s_add_i32 s57, s51, s35
	v_lshl_add_u64 v[128:129], s[54:55], 0, v[180:181]
	s_mov_b32 m0, s57
	s_nop 0
	global_load_lds_dwordx4 v[128:129], off
	v_lshl_add_u64 v[128:129], s[54:55], 0, v[176:177]
	s_add_i32 m0, s57, 0x2000
	s_nop 0
	global_load_lds_dwordx4 v[128:129], off
	s_waitcnt vmcnt(6)
	s_barrier
	s_setprio 1
	v_mfma_f32_16x16x32_bf16 v[52:55], v[192:195], v[144:147], v[52:55]
	v_mfma_f32_16x16x32_bf16 v[48:51], v[200:203], v[144:147], v[48:51]
	v_mfma_f32_16x16x32_bf16 v[36:39], v[192:195], v[152:155], v[36:39]
	v_mfma_f32_16x16x32_bf16 v[32:35], v[200:203], v[152:155], v[32:35]
	v_mfma_f32_16x16x32_bf16 v[20:23], v[192:195], v[160:163], v[20:23]
	v_mfma_f32_16x16x32_bf16 v[16:19], v[200:203], v[160:163], v[16:19]
	v_mfma_f32_16x16x32_bf16 v[4:7], v[192:195], v[168:171], v[4:7]
	v_mfma_f32_16x16x32_bf16 v[0:3], v[200:203], v[168:171], v[0:3]
	v_mfma_f32_16x16x32_bf16 v[52:55], v[196:199], v[148:151], v[52:55]
	v_mfma_f32_16x16x32_bf16 v[48:51], v[212:215], v[148:151], v[48:51]
	v_mfma_f32_16x16x32_bf16 v[36:39], v[196:199], v[156:159], v[36:39]
	v_mfma_f32_16x16x32_bf16 v[32:35], v[212:215], v[156:159], v[32:35]
	v_mfma_f32_16x16x32_bf16 v[20:23], v[196:199], v[164:167], v[20:23]
	v_mfma_f32_16x16x32_bf16 v[16:19], v[212:215], v[164:167], v[16:19]
	v_mfma_f32_16x16x32_bf16 v[4:7], v[196:199], v[172:175], v[4:7]
	v_mfma_f32_16x16x32_bf16 v[0:3], v[212:215], v[172:175], v[0:3]
	s_barrier
	s_setprio 0
	s_add_i32 s54, 0, 0x18000
	v_add_u32_e32 v140, s54, v205
	ds_read_b128 v[128:131], v140
	ds_read_b128 v[132:135], v140 offset:1024
	ds_read_b128 v[136:139], v140 offset:2048
	ds_read_b128 v[140:143], v140 offset:3072
	s_add_u32 s26, s26, 0x80000
	s_addc_u32 s27, s27, 0
	s_mov_b32 m0, s39
	v_lshl_add_u64 v[192:193], s[26:27], 0, v[182:183]
	ds_read_b128 v[144:147], v208 offset:32768
	ds_read_b128 v[148:151], v208 offset:33792
	ds_read_b128 v[152:155], v208 offset:34816
	ds_read_b128 v[156:159], v208 offset:35840
	ds_read_b128 v[160:163], v208 offset:36864
	ds_read_b128 v[164:167], v208 offset:37888
	ds_read_b128 v[168:171], v208 offset:38912
	ds_read_b128 v[172:175], v208 offset:39936
	global_load_lds_dwordx4 v[192:193], off
	v_lshl_add_u64 v[192:193], s[26:27], 0, v[178:179]
	s_mov_b32 m0, s40
	s_nop 0
	global_load_lds_dwordx4 v[192:193], off
	s_waitcnt lgkmcnt(8)
	s_barrier
	s_waitcnt lgkmcnt(0)
	s_setprio 1
	v_mfma_f32_16x16x32_bf16 v[124:127], v[128:131], v[144:147], v[124:127]
	v_mfma_f32_16x16x32_bf16 v[120:123], v[136:139], v[144:147], v[120:123]
	v_mfma_f32_16x16x32_bf16 v[108:111], v[128:131], v[152:155], v[108:111]
	v_mfma_f32_16x16x32_bf16 v[104:107], v[136:139], v[152:155], v[104:107]
	v_mfma_f32_16x16x32_bf16 v[92:95], v[128:131], v[160:163], v[92:95]
	v_mfma_f32_16x16x32_bf16 v[88:91], v[136:139], v[160:163], v[88:91]
	v_mfma_f32_16x16x32_bf16 v[76:79], v[128:131], v[168:171], v[76:79]
	v_mfma_f32_16x16x32_bf16 v[72:75], v[136:139], v[168:171], v[72:75]
	v_mfma_f32_16x16x32_bf16 v[124:127], v[132:135], v[148:151], v[124:127]
	v_mfma_f32_16x16x32_bf16 v[120:123], v[140:143], v[148:151], v[120:123]
	v_mfma_f32_16x16x32_bf16 v[108:111], v[132:135], v[156:159], v[108:111]
	v_mfma_f32_16x16x32_bf16 v[104:107], v[140:143], v[156:159], v[104:107]
	v_mfma_f32_16x16x32_bf16 v[92:95], v[132:135], v[164:167], v[92:95]
	v_mfma_f32_16x16x32_bf16 v[88:91], v[140:143], v[164:167], v[88:91]
	v_mfma_f32_16x16x32_bf16 v[76:79], v[132:135], v[172:175], v[76:79]
	v_mfma_f32_16x16x32_bf16 v[72:75], v[140:143], v[172:175], v[72:75]
	s_barrier
	s_setprio 0
	s_add_i32 s26, 0, 0x1c000
	s_add_i32 s27, s54, s35
	v_add_u32_e32 v212, s26, v205
	v_lshl_add_u64 v[216:217], v[216:217], 0, s[10:11]
	s_mov_b32 m0, s27
	ds_read_b128 v[192:195], v212
	ds_read_b128 v[196:199], v212 offset:1024
	ds_read_b128 v[200:203], v212 offset:2048
	ds_read_b128 v[212:215], v212 offset:3072
	global_load_lds_dwordx4 v[216:217], off
	v_lshl_add_u64 v[216:217], v[218:219], 0, s[10:11]
	s_add_i32 m0, s27, 0x2000
	s_nop 0
	global_load_lds_dwordx4 v[216:217], off
	s_barrier
	s_waitcnt lgkmcnt(0)
	s_setprio 1
	v_mfma_f32_16x16x32_bf16 v[116:119], v[192:195], v[144:147], v[116:119]
	v_mfma_f32_16x16x32_bf16 v[112:115], v[200:203], v[144:147], v[112:115]
	v_mfma_f32_16x16x32_bf16 v[100:103], v[192:195], v[152:155], v[100:103]
	v_mfma_f32_16x16x32_bf16 v[96:99], v[200:203], v[152:155], v[96:99]
	v_mfma_f32_16x16x32_bf16 v[84:87], v[192:195], v[160:163], v[84:87]
	v_mfma_f32_16x16x32_bf16 v[80:83], v[200:203], v[160:163], v[80:83]
	v_mfma_f32_16x16x32_bf16 v[68:71], v[192:195], v[168:171], v[68:71]
	v_mfma_f32_16x16x32_bf16 v[64:67], v[200:203], v[168:171], v[64:67]
	v_mfma_f32_16x16x32_bf16 v[116:119], v[196:199], v[148:151], v[116:119]
	v_mfma_f32_16x16x32_bf16 v[112:115], v[212:215], v[148:151], v[112:115]
	v_mfma_f32_16x16x32_bf16 v[100:103], v[196:199], v[156:159], v[100:103]
	v_mfma_f32_16x16x32_bf16 v[96:99], v[212:215], v[156:159], v[96:99]
	v_mfma_f32_16x16x32_bf16 v[84:87], v[196:199], v[164:167], v[84:87]
	v_mfma_f32_16x16x32_bf16 v[80:83], v[212:215], v[164:167], v[80:83]
	v_mfma_f32_16x16x32_bf16 v[68:71], v[196:199], v[172:175], v[68:71]
	v_mfma_f32_16x16x32_bf16 v[64:67], v[212:215], v[172:175], v[64:67]
	s_barrier
	s_setprio 0
	s_mov_b32 m0, s46
	v_lshl_add_u64 v[216:217], v[220:221], 0, s[10:11]
	ds_read_b128 v[144:147], v208 offset:49152
	ds_read_b128 v[148:151], v208 offset:50176
	ds_read_b128 v[152:155], v208 offset:51200
	ds_read_b128 v[156:159], v208 offset:52224
	ds_read_b128 v[160:163], v208 offset:53248
	ds_read_b128 v[164:167], v208 offset:54272
	ds_read_b128 v[168:171], v208 offset:55296
	ds_read_b128 v[172:175], v208 offset:56320
	global_load_lds_dwordx4 v[216:217], off
	v_lshl_add_u64 v[216:217], v[222:223], 0, s[10:11]
	s_mov_b32 m0, s47
	s_nop 0
	global_load_lds_dwordx4 v[216:217], off
	s_barrier
; #define PG8_STAGE(bufoff, gbase, voff) do { _Pragma("unroll") for (int _i = 0; _i < 2; ++_i) \
;     __builtin_amdgcn_global_load_lds((const unsigned*)((const char*)(gbase) + (voff)[_i]), (LAS unsigned*)(lds + (bufoff) + ldsw + _i * 8192), 16, 0, 0); } while (0)
; #define PG8_MMA(ai, bj, At, Bt) do { __builtin_amdgcn_s_setprio(1); _Pragma("unroll") for (int m = 0; m < 4; ++m) _Pragma("unroll") for (int n = 0; n < 2; ++n) _Pragma("unroll") for (int k = 0; k < 2; ++k) \
;     acc[ai][bj][m][n] = __builtin_amdgcn_mfma_f32_16x16x32_bf16(Bt[n][k], At[m][k], acc[ai][bj][m][n], 0, 0, 0); __builtin_amdgcn_s_setprio(0); } while (0)
; #define PG8_WAIT_V(n) asm volatile("s_waitcnt vmcnt(" #n ")" ::: "memory")
; #define PG8_WAIT_L(n) asm volatile("s_waitcnt lgkmcnt(" #n ")" ::: "memory")
; #define PG8_BAR __builtin_amdgcn_s_barrier()
; #define PG8_SCHED __builtin_amdgcn_sched_barrier(0)
; template <class Epi, class Sched = StaticOrder>
; DI void gemm_phase(LAS unsigned char* lds, const Gemm g, const Sched& S, const Epi& E) {
;     ...
;       PG8_BAR; PG8_WAIT_L(0); PG8_MMA(1, 0, At, B0); PG8_BAR; PG8_SCHED;
;       PG8_STAGE(PG8_SB(1, 1), b3 + hstep, voffB);
;       PG8_WAIT_V(6); PG8_BAR; PG8_MMA(1, 1, At, B1); PG8_BAR;
	s_waitcnt lgkmcnt(0)
	s_setprio 1
	v_mfma_f32_16x16x32_bf16 v[60:63], v[128:131], v[144:147], v[60:63]
	v_mfma_f32_16x16x32_bf16 v[56:59], v[136:139], v[144:147], v[56:59]
	v_mfma_f32_16x16x32_bf16 v[44:47], v[128:131], v[152:155], v[44:47]
	v_mfma_f32_16x16x32_bf16 v[40:43], v[136:139], v[152:155], v[40:43]
	v_mfma_f32_16x16x32_bf16 v[28:31], v[128:131], v[160:163], v[28:31]
	v_mfma_f32_16x16x32_bf16 v[24:27], v[136:139], v[160:163], v[24:27]
	v_mfma_f32_16x16x32_bf16 v[12:15], v[128:131], v[168:171], v[12:15]
	v_mfma_f32_16x16x32_bf16 v[8:11], v[136:139], v[168:171], v[8:11]
	v_mfma_f32_16x16x32_bf16 v[60:63], v[132:135], v[148:151], v[60:63]
	v_mfma_f32_16x16x32_bf16 v[56:59], v[140:143], v[148:151], v[56:59]
	v_mfma_f32_16x16x32_bf16 v[44:47], v[132:135], v[156:159], v[44:47]
	v_mfma_f32_16x16x32_bf16 v[40:43], v[140:143], v[156:159], v[40:43]
	v_mfma_f32_16x16x32_bf16 v[28:31], v[132:135], v[164:167], v[28:31]
	v_mfma_f32_16x16x32_bf16 v[24:27], v[140:143], v[164:167], v[24:27]
	v_mfma_f32_16x16x32_bf16 v[12:15], v[132:135], v[172:175], v[12:15]
	v_mfma_f32_16x16x32_bf16 v[8:11], v[140:143], v[172:175], v[8:11]
	s_barrier
	s_setprio 0
	s_add_u32 s24, s24, 0x80080
	s_addc_u32 s25, s25, 0
	s_add_i32 s26, s26, s35
	v_lshl_add_u64 v[128:129], s[24:25], 0, v[180:181]
	s_mov_b32 m0, s26
	s_nop 0
	global_load_lds_dwordx4 v[128:129], off
	v_lshl_add_u64 v[128:129], s[24:25], 0, v[176:177]
	s_add_i32 m0, s26, 0x2000
	s_nop 0
	global_load_lds_dwordx4 v[128:129], off
	s_waitcnt vmcnt(6)
	s_barrier
	s_setprio 1
	v_mfma_f32_16x16x32_bf16 v[52:55], v[192:195], v[144:147], v[52:55]
	v_mfma_f32_16x16x32_bf16 v[48:51], v[200:203], v[144:147], v[48:51]
	v_mfma_f32_16x16x32_bf16 v[36:39], v[192:195], v[152:155], v[36:39]
	v_mfma_f32_16x16x32_bf16 v[32:35], v[200:203], v[152:155], v[32:35]
	v_mfma_f32_16x16x32_bf16 v[20:23], v[192:195], v[160:163], v[20:23]
	v_mfma_f32_16x16x32_bf16 v[16:19], v[200:203], v[160:163], v[16:19]
	v_mfma_f32_16x16x32_bf16 v[4:7], v[192:195], v[168:171], v[4:7]
	v_mfma_f32_16x16x32_bf16 v[0:3], v[200:203], v[168:171], v[0:3]
	v_mfma_f32_16x16x32_bf16 v[52:55], v[196:199], v[148:151], v[52:55]
	v_mfma_f32_16x16x32_bf16 v[48:51], v[212:215], v[148:151], v[48:51]
	v_mfma_f32_16x16x32_bf16 v[36:39], v[196:199], v[156:159], v[36:39]
	v_mfma_f32_16x16x32_bf16 v[32:35], v[212:215], v[156:159], v[32:35]
	v_mfma_f32_16x16x32_bf16 v[20:23], v[196:199], v[164:167], v[20:23]
	v_mfma_f32_16x16x32_bf16 v[16:19], v[212:215], v[164:167], v[16:19]
	v_mfma_f32_16x16x32_bf16 v[4:7], v[196:199], v[172:175], v[4:7]
	v_mfma_f32_16x16x32_bf16 v[0:3], v[212:215], v[172:175], v[0:3]
	s_add_i32 s53, s53, 2
	s_add_u32 s22, s22, 0x100
	s_addc_u32 s23, s23, 0
	s_add_u32 s45, s45, 0x100
	s_addc_u32 s52, s52, 0
	s_cmp_gt_u32 s53, 29
	s_barrier
	s_setprio 0
	s_cbranch_scc0 .LBB0_728
; DI unsigned pack2(float lo, float hi) { f32x2 v = {lo, hi}; bf16v2 r = __builtin_convertvector(v, bf16v2); return __builtin_bit_cast(unsigned, r); }
;   DI void operator()(const f32x4 (&acc)[2][2][4][2], const Unit& u, int wr, int wc, int fr, int fq) const {
;     const int row0 = u.pm * BM + wr * 64 + fr, col0 = u.pn * BM + wc * 32 + 8 * fq;
; #pragma unroll
;     for (int ai = 0; ai < 2; ++ai) {
;       f32x4 bv[4][2][2];
; #pragma unroll
;       for (int m = 0; m < 4; ++m)
; #pragma unroll
;         for (int bj = 0; bj < 2; ++bj) {
;           const float* bp = base + (size_t)(row0 + ai * HALF + m * 16) * 2048 + col0 + bj * HALF;
;           bv[m][bj][0] = *(const f32x4*)bp; bv[m][bj][1] = *(const f32x4*)(bp + 4);
;         }
; #pragma unroll
;       for (int m = 0; m < 4; ++m) {
;         const int row = row0 + ai * HALF + m * 16;
;         const size_t off = (size_t)row * 2048 + col0;
;         float ss = 0.f;
; #pragma unroll
;         for (int bj = 0; bj < 2; ++bj) {
;           const f32x4 v0 = acc[ai][bj][m][0] + bv[m][bj][0], v1 = acc[ai][bj][m][1] + bv[m][bj][1];
;           *(f32x4*)(C + off + bj * HALF) = v0; *(f32x4*)(C + off + bj * HALF + 4) = v1;
;           if (xb) {
;             u32x4 w; w.x = pack2(v0[0], v0[1]); w.y = pack2(v0[2], v0[3]); w.z = pack2(v1[0], v1[1]); w.w = pack2(v1[2], v1[3]);
;             *(u32x4*)(xb + off + bj * HALF) = w;
;             ss += v0[0] * v0[0] + v0[1] * v0[1] + v0[2] * v0[2] + v0[3] * v0[3] + v1[0] * v1[0] + v1[1] * v1[1] + v1[2] * v1[2] + v1[3] * v1[3];
;           }
;         }
;         if (xb) {
;           ss += __shfl_xor(ss, 16); ss += __shfl_xor(ss, 32);
;           if (fq == 0) ssq[(size_t)row * 32 + u.pn * 4 + wc] = ss;
;         }
	v_lshl_add_u32 v196, s12, 8, v204
	v_lshl_or_b32 v192, s42, 8, v206
	v_ashrrev_i32_e32 v193, 31, v192
	v_ashrrev_i32_e32 v197, 31, v196
	v_lshl_add_u64 v[194:195], v[192:193], 2, s[60:61]
	v_lshlrev_b64 v[128:129], 13, v[196:197]
	v_lshl_add_u64 v[128:129], v[194:195], 0, v[128:129]
	global_load_dwordx4 v[214:217], v[128:129], off
	global_load_dwordx4 v[218:221], v[128:129], off offset:16
	global_load_dwordx4 v[222:225], v[128:129], off offset:512
	global_load_dwordx4 v[226:229], v[128:129], off offset:528
	v_or_b32_e32 v202, 16, v196
	v_or_b32_e32 v200, 32, v196
	v_or_b32_e32 v198, 48, v196
	v_ashrrev_i32_e32 v203, 31, v202
	v_ashrrev_i32_e32 v201, 31, v200
	v_ashrrev_i32_e32 v199, 31, v198
	v_lshlrev_b64 v[128:129], 13, v[202:203]
	v_lshlrev_b64 v[130:131], 13, v[200:201]
	v_lshlrev_b64 v[132:133], 13, v[198:199]
	v_lshl_add_u64 v[128:129], v[194:195], 0, v[128:129]
	v_lshl_add_u64 v[130:131], v[194:195], 0, v[130:131]
	v_lshl_add_u64 v[132:133], v[194:195], 0, v[132:133]
	global_load_dwordx4 v[168:171], v[128:129], off offset:16
	global_load_dwordx4 v[172:175], v[128:129], off
	global_load_dwordx4 v[160:163], v[128:129], off offset:528
	global_load_dwordx4 v[164:167], v[128:129], off offset:512
	global_load_dwordx4 v[152:155], v[130:131], off offset:16
	global_load_dwordx4 v[156:159], v[130:131], off
	global_load_dwordx4 v[144:147], v[130:131], off offset:528
	global_load_dwordx4 v[148:151], v[130:131], off offset:512
	global_load_dwordx4 v[136:139], v[132:133], off offset:16
	global_load_dwordx4 v[140:143], v[132:133], off
	s_nop 0
	global_load_dwordx4 v[128:131], v[132:133], off offset:528
	s_nop 0
	global_load_dwordx4 v[132:135], v[132:133], off offset:512
	v_and_b32_e32 v212, 64, v211
	v_xor_b32_e32 v230, 16, v211
	v_add_u32_e32 v232, 64, v212
	v_xor_b32_e32 v231, 32, v211
	v_cmp_lt_i32_e32 vcc, v230, v232
	v_lshlrev_b64 v[212:213], 11, v[196:197]
	v_readlane_b32 s64, v243, 3
	v_cndmask_b32_e32 v233, v211, v230, vcc
	v_cmp_lt_i32_e32 vcc, v231, v232
	v_readlane_b32 s78, v243, 17
	v_readlane_b32 s79, v243, 18
	v_cndmask_b32_e32 v234, v211, v231, vcc
	v_lshl_add_u64 v[230:231], v[212:213], 0, v[192:193]
	v_lshlrev_b32_e32 v212, 2, v233
	v_lshl_add_u64 v[232:233], v[230:231], 2, s[78:79]
	v_lshl_add_u64 v[230:231], v[230:231], 1, s[2:3]
	s_lshl_b32 s22, s42, 2
	s_ashr_i32 s23, s22, 31
	v_readlane_b32 s65, v243, 4
	v_readlane_b32 s66, v243, 5
	v_readlane_b32 s67, v243, 6
	v_readlane_b32 s68, v243, 7
	v_readlane_b32 s69, v243, 8
	v_readlane_b32 s70, v243, 9
	v_readlane_b32 s71, v243, 10
	v_readlane_b32 s72, v243, 11
	v_readlane_b32 s73, v243, 12
	v_readlane_b32 s74, v243, 13
	v_readlane_b32 s75, v243, 14
	v_readlane_b32 s76, v243, 15
	v_readlane_b32 s77, v243, 16
	s_waitcnt vmcnt(0)
	v_pk_add_f32 v[126:127], v[126:127], v[216:217]
	v_pk_add_f32 v[124:125], v[124:125], v[214:215]
	v_pk_add_f32 v[116:117], v[116:117], v[222:223]
	v_pk_add_f32 v[122:123], v[122:123], v[220:221]
	v_pk_add_f32 v[120:121], v[120:121], v[218:219]
	v_pk_add_f32 v[214:215], v[112:113], v[226:227]
	global_store_dwordx4 v[232:233], v[124:127], off
	global_store_dwordx4 v[232:233], v[120:123], off offset:16
	v_cvt_pk_bf16_f32 v112, v124, v125
	v_mul_f32_e32 v125, v125, v125
	v_mul_f32_e32 v213, v117, v117
	v_pk_add_f32 v[118:119], v[118:119], v[224:225]
	v_fmac_f32_e32 v125, v124, v124
	v_fmac_f32_e32 v213, v116, v116
	v_fmac_f32_e32 v125, v126, v126
	v_fmac_f32_e32 v213, v118, v118
	v_fmac_f32_e32 v125, v127, v127
	v_fmac_f32_e32 v213, v119, v119
	v_fmac_f32_e32 v125, v120, v120
	v_fmac_f32_e32 v213, v214, v214
	v_pk_add_f32 v[216:217], v[114:115], v[228:229]
	v_fmac_f32_e32 v125, v121, v121
	v_fmac_f32_e32 v213, v215, v215
	v_fmac_f32_e32 v125, v122, v122
	v_fmac_f32_e32 v213, v216, v216
	v_fmac_f32_e32 v125, v123, v123
	v_fmac_f32_e32 v213, v217, v217
	v_cvt_pk_bf16_f32 v114, v120, v121
	v_add_f32_e32 v120, v125, v213
	ds_bpermute_b32 v121, v212, v120
	v_cvt_pk_bf16_f32 v113, v126, v127
	v_cvt_pk_bf16_f32 v115, v122, v123
	global_store_dwordx4 v[230:231], v[112:115], off
	global_store_dwordx4 v[232:233], v[116:119], off offset:512
	global_store_dwordx4 v[232:233], v[214:217], off offset:528
	v_cvt_pk_bf16_f32 v122, v116, v117
	s_waitcnt lgkmcnt(0)
	v_add_f32_e32 v112, v120, v121
	v_lshlrev_b32_e32 v120, 2, v234
	ds_bpermute_b32 v113, v120, v112
	v_cvt_pk_bf16_f32 v123, v118, v119
	v_cvt_pk_bf16_f32 v124, v214, v215
	v_cvt_pk_bf16_f32 v125, v216, v217
	global_store_dwordx4 v[230:231], v[122:125], off offset:256
	s_and_saveexec_b64 s[24:25], s[0:1]
	s_cbranch_execz .LBB0_731
	s_waitcnt lgkmcnt(0)
	v_add_f32_e32 v114, v112, v113
	v_lshlrev_b64 v[112:113], 7, v[196:197]
	v_lshl_add_u64 v[112:113], s[8:9], 0, v[112:113]
	v_lshl_add_u64 v[112:113], s[22:23], 2, v[112:113]
	s_lshl_b32 s12, s41, 2
	v_lshl_add_u64 v[112:113], v[112:113], 0, s[12:13]
	global_store_dword v[112:113], v114, off

; #define PG8_STAGE(bufoff, gbase, voff) do { _Pragma("unroll") for (int _i = 0; _i < 2; ++_i) \
;     __builtin_amdgcn_global_load_lds((const unsigned*)((const char*)(gbase) + (voff)[_i]), (LAS unsigned*)(lds + (bufoff) + ldsw + _i * 8192), 16, 0, 0); } while (0)
; #define PG8_LDA(dst, b, h) do { _Pragma("unroll") for (int m = 0; m < 4; ++m) _Pragma("unroll") for (int k = 0; k < 2; ++k) dst[m][k] = *(const LAS bf16x8*)(lds + PG8_SA(b, h) + aoff + m * 2048 + k * 1024); } while (0)
; #define PG8_LDB(dst, b, h) do { _Pragma("unroll") for (int n = 0; n < 2; ++n) _Pragma("unroll") for (int k = 0; k < 2; ++k) dst[n][k] = *(const LAS bf16x8*)(lds + PG8_SB(b, h) + boff + n * 2048 + k * 1024); } while (0)
; #define PG8_MMA(ai, bj, At, Bt) do { __builtin_amdgcn_s_setprio(1); _Pragma("unroll") for (int m = 0; m < 4; ++m) _Pragma("unroll") for (int n = 0; n < 2; ++n) _Pragma("unroll") for (int k = 0; k < 2; ++k) \
;     acc[ai][bj][m][n] = __builtin_amdgcn_mfma_f32_16x16x32_bf16(Bt[n][k], At[m][k], acc[ai][bj][m][n], 0, 0, 0); __builtin_amdgcn_s_setprio(0); } while (0)
; #define PG8_WAIT_V(n) asm volatile("s_waitcnt vmcnt(" #n ")" ::: "memory")
; #define PG8_WAIT_L(n) asm volatile("s_waitcnt lgkmcnt(" #n ")" ::: "memory")
; #define PG8_BAR __builtin_amdgcn_s_barrier()
; #define PG8_SCHED __builtin_amdgcn_sched_barrier(0)
; template <class Epi, class Sched = StaticOrder>
; DI void gemm_phase(LAS unsigned char* lds, const Gemm g, const Sched& S, const Epi& E) {
;     ...
;     for (int t = 0; t < nt; t += 2) {
;       const bool last = (t == nt - 2);
;       const char* a1 = cA + (size_t)(t + 1) * kstep;
;       const char* a2 = last ? nA : cA + (size_t)(t + 2) * kstep; const char* b2 = last ? nB : cB + (size_t)(t + 2) * kstep;
;       const char* a3 = a2 + kstep; const char* b3 = b2 + kstep;
;       PG8_LDB(B0, 0, 0); PG8_SCHED; PG8_LDA(At, 0, 0); PG8_STAGE(PG8_SA(1, 1), a1 + hstep, voffA);
;       PG8_WAIT_L(8); PG8_BAR; PG8_WAIT_L(0); PG8_MMA(0, 0, At, B0); PG8_BAR; PG8_SCHED;
;       PG8_LDB(B1, 0, 1); PG8_STAGE(PG8_SB(0, 0), b2, voffB);
;       PG8_BAR; PG8_WAIT_L(0); PG8_MMA(0, 1, At, B1); PG8_BAR;
;       PG8_LDA(At, 0, 1); PG8_STAGE(PG8_SA(0, 0), a2, voffA);
;       PG8_BAR; PG8_WAIT_L(0); PG8_MMA(1, 0, At, B0); PG8_BAR; PG8_SCHED;
;       PG8_STAGE(PG8_SB(0, 1), b2 + hstep, voffB);
;       PG8_WAIT_V(6); PG8_BAR; PG8_MMA(1, 1, At, B1); PG8_BAR;
.LBB0_811:
	ds_read_b128 v[64:67], v201
	ds_read_b128 v[68:71], v201 offset:1024
	ds_read_b128 v[72:75], v201 offset:2048
	ds_read_b128 v[76:79], v201 offset:3072
	s_add_u32 s46, s14, 0xfff80080
	s_addc_u32 s47, s15, -1
	s_cmp_eq_u32 s52, 28
	s_cselect_b32 s49, s37, s47
	s_cselect_b32 s48, s42, s46
	s_cselect_b32 s47, s35, s45
	s_cselect_b32 s46, s43, s44
	v_lshl_add_u64 v[196:197], s[14:15], 0, v[170:171]
	s_add_i32 m0, s62, 0xc000
	ds_read_b128 v[80:83], v202
	ds_read_b128 v[84:87], v202 offset:1024
	ds_read_b128 v[92:95], v202 offset:2048
	ds_read_b128 v[96:99], v202 offset:3072
	ds_read_b128 v[180:183], v202 offset:4096
	ds_read_b128 v[184:187], v202 offset:5120
	ds_read_b128 v[188:191], v202 offset:6144
	ds_read_b128 v[192:195], v202 offset:7168
	global_load_lds_dwordx4 v[196:197], off
	v_lshl_add_u64 v[196:197], s[14:15], 0, v[172:173]
	s_add_i32 m0, s62, 0xe000
	s_nop 0
	global_load_lds_dwordx4 v[196:197], off
	s_waitcnt lgkmcnt(8)
	s_barrier
	s_waitcnt lgkmcnt(0)
	s_setprio 1
	v_mfma_f32_16x16x32_bf16 v[156:159], v[64:67], v[80:83], v[156:159]
	v_mfma_f32_16x16x32_bf16 v[144:147], v[72:75], v[80:83], v[144:147]
	v_mfma_f32_16x16x32_bf16 v[140:143], v[64:67], v[92:95], v[140:143]
	v_mfma_f32_16x16x32_bf16 v[132:135], v[72:75], v[92:95], v[132:135]
	v_mfma_f32_16x16x32_bf16 v[124:127], v[64:67], v[180:183], v[124:127]
	v_mfma_f32_16x16x32_bf16 v[116:119], v[72:75], v[180:183], v[116:119]
	v_mfma_f32_16x16x32_bf16 v[112:115], v[64:67], v[188:191], v[112:115]
	v_mfma_f32_16x16x32_bf16 v[108:111], v[72:75], v[188:191], v[108:111]
	v_mfma_f32_16x16x32_bf16 v[156:159], v[68:71], v[84:87], v[156:159]
	v_mfma_f32_16x16x32_bf16 v[144:147], v[76:79], v[84:87], v[144:147]
	v_mfma_f32_16x16x32_bf16 v[140:143], v[68:71], v[96:99], v[140:143]
	v_mfma_f32_16x16x32_bf16 v[132:135], v[76:79], v[96:99], v[132:135]
	v_mfma_f32_16x16x32_bf16 v[124:127], v[68:71], v[184:187], v[124:127]
	v_mfma_f32_16x16x32_bf16 v[116:119], v[76:79], v[184:187], v[116:119]
	v_mfma_f32_16x16x32_bf16 v[112:115], v[68:71], v[192:195], v[112:115]
	v_mfma_f32_16x16x32_bf16 v[108:111], v[76:79], v[192:195], v[108:111]
	s_barrier
	s_setprio 0
	s_add_i32 s53, s72, s60
	v_lshl_add_u64 v[196:197], s[46:47], 0, v[164:165]
	s_mov_b32 m0, s53
	ds_read_b128 v[206:209], v203
	ds_read_b128 v[212:215], v203 offset:1024
	ds_read_b128 v[216:219], v203 offset:2048
	ds_read_b128 v[220:223], v203 offset:3072
	global_load_lds_dwordx4 v[196:197], off
	v_lshl_add_u64 v[232:233], s[46:47], 0, v[160:161]
	s_add_i32 m0, s53, 0x2000
	s_nop 0
	global_load_lds_dwordx4 v[232:233], off
	s_barrier
	s_waitcnt lgkmcnt(0)
	s_setprio 1
	v_mfma_f32_16x16x32_bf16 v[152:155], v[206:209], v[80:83], v[152:155]
	v_mfma_f32_16x16x32_bf16 v[80:83], v[216:219], v[80:83], v[148:151]
	v_mfma_f32_16x16x32_bf16 v[152:155], v[212:215], v[84:87], v[152:155]
	v_mfma_f32_16x16x32_bf16 v[80:83], v[220:223], v[84:87], v[80:83]
	v_mfma_f32_16x16x32_bf16 v[84:87], v[206:209], v[92:95], v[136:139]
	v_mfma_f32_16x16x32_bf16 v[92:95], v[216:219], v[92:95], v[128:131]
	v_mfma_f32_16x16x32_bf16 v[104:107], v[216:219], v[180:183], v[104:107]
	v_mfma_f32_16x16x32_bf16 v[100:103], v[206:209], v[188:191], v[100:103]
	v_mfma_f32_16x16x32_bf16 v[88:91], v[216:219], v[188:191], v[88:91]
	v_mfma_f32_16x16x32_bf16 v[84:87], v[212:215], v[96:99], v[84:87]
	v_mfma_f32_16x16x32_bf16 v[92:95], v[220:223], v[96:99], v[92:95]
	v_mfma_f32_16x16x32_bf16 v[96:99], v[206:209], v[180:183], v[120:123]
	v_mfma_f32_16x16x32_bf16 v[104:107], v[220:223], v[184:187], v[104:107]
	v_mfma_f32_16x16x32_bf16 v[100:103], v[212:215], v[192:195], v[100:103]
	v_mfma_f32_16x16x32_bf16 v[88:91], v[220:223], v[192:195], v[88:91]
	v_mfma_f32_16x16x32_bf16 v[96:99], v[212:215], v[184:187], v[96:99]
	s_barrier
	s_setprio 0
	s_mov_b32 m0, s62
	v_lshl_add_u64 v[234:235], s[48:49], 0, v[166:167]
	ds_read_b128 v[120:123], v202 offset:16384
	ds_read_b128 v[128:131], v202 offset:17408
	ds_read_b128 v[136:139], v202 offset:18432
	ds_read_b128 v[148:151], v202 offset:19456
	ds_read_b128 v[180:183], v202 offset:20480
	ds_read_b128 v[184:187], v202 offset:21504
	ds_read_b128 v[188:191], v202 offset:22528
	ds_read_b128 v[192:195], v202 offset:23552
	global_load_lds_dwordx4 v[234:235], off
	v_lshl_add_u64 v[236:237], s[48:49], 0, v[162:163]
	s_mov_b32 m0, s63
	s_nop 0
	global_load_lds_dwordx4 v[236:237], off
	s_barrier
	s_waitcnt lgkmcnt(0)
	s_setprio 1
	v_mfma_f32_16x16x32_bf16 v[60:63], v[64:67], v[120:123], v[60:63]
	v_mfma_f32_16x16x32_bf16 v[48:51], v[72:75], v[120:123], v[48:51]
	v_mfma_f32_16x16x32_bf16 v[44:47], v[64:67], v[136:139], v[44:47]
	v_mfma_f32_16x16x32_bf16 v[36:39], v[72:75], v[136:139], v[36:39]
	v_mfma_f32_16x16x32_bf16 v[28:31], v[64:67], v[180:183], v[28:31]
	v_mfma_f32_16x16x32_bf16 v[20:23], v[72:75], v[180:183], v[20:23]
	v_mfma_f32_16x16x32_bf16 v[16:19], v[64:67], v[188:191], v[16:19]
	v_mfma_f32_16x16x32_bf16 v[12:15], v[72:75], v[188:191], v[12:15]
	v_mfma_f32_16x16x32_bf16 v[60:63], v[68:71], v[128:131], v[60:63]
	v_mfma_f32_16x16x32_bf16 v[48:51], v[76:79], v[128:131], v[48:51]
	v_mfma_f32_16x16x32_bf16 v[44:47], v[68:71], v[148:151], v[44:47]
	v_mfma_f32_16x16x32_bf16 v[36:39], v[76:79], v[148:151], v[36:39]
	v_mfma_f32_16x16x32_bf16 v[28:31], v[68:71], v[184:187], v[28:31]
	v_mfma_f32_16x16x32_bf16 v[20:23], v[76:79], v[184:187], v[20:23]
	v_mfma_f32_16x16x32_bf16 v[16:19], v[68:71], v[192:195], v[16:19]
	v_mfma_f32_16x16x32_bf16 v[12:15], v[76:79], v[192:195], v[12:15]
	s_barrier
; #define PG8_STAGE(bufoff, gbase, voff) do { _Pragma("unroll") for (int _i = 0; _i < 2; ++_i) \
;     __builtin_amdgcn_global_load_lds((const unsigned*)((const char*)(gbase) + (voff)[_i]), (LAS unsigned*)(lds + (bufoff) + ldsw + _i * 8192), 16, 0, 0); } while (0)
; #define PG8_LDA(dst, b, h) do { _Pragma("unroll") for (int m = 0; m < 4; ++m) _Pragma("unroll") for (int k = 0; k < 2; ++k) dst[m][k] = *(const LAS bf16x8*)(lds + PG8_SA(b, h) + aoff + m * 2048 + k * 1024); } while (0)
; #define PG8_LDB(dst, b, h) do { _Pragma("unroll") for (int n = 0; n < 2; ++n) _Pragma("unroll") for (int k = 0; k < 2; ++k) dst[n][k] = *(const LAS bf16x8*)(lds + PG8_SB(b, h) + boff + n * 2048 + k * 1024); } while (0)
; #define PG8_MMA(ai, bj, At, Bt) do { __builtin_amdgcn_s_setprio(1); _Pragma("unroll") for (int m = 0; m < 4; ++m) _Pragma("unroll") for (int n = 0; n < 2; ++n) _Pragma("unroll") for (int k = 0; k < 2; ++k) \
;     acc[ai][bj][m][n] = __builtin_amdgcn_mfma_f32_16x16x32_bf16(Bt[n][k], At[m][k], acc[ai][bj][m][n], 0, 0, 0); __builtin_amdgcn_s_setprio(0); } while (0)
; #define PG8_WAIT_V(n) asm volatile("s_waitcnt vmcnt(" #n ")" ::: "memory")
; #define PG8_WAIT_L(n) asm volatile("s_waitcnt lgkmcnt(" #n ")" ::: "memory")
; #define PG8_BAR __builtin_amdgcn_s_barrier()
; #define PG8_SCHED __builtin_amdgcn_sched_barrier(0)
; template <class Epi, class Sched = StaticOrder>
; DI void gemm_phase(LAS unsigned char* lds, const Gemm g, const Sched& S, const Epi& E) {
;     ...
;       PG8_STAGE(PG8_SB(0, 1), b2 + hstep, voffB);
;       PG8_WAIT_V(6); PG8_BAR; PG8_MMA(1, 1, At, B1); PG8_BAR;
;       PG8_LDB(B0, 1, 0); PG8_SCHED; PG8_LDA(At, 1, 0); PG8_STAGE(PG8_SA(0, 1), a2 + hstep, voffA);
;       PG8_WAIT_L(8); PG8_BAR; PG8_WAIT_L(0); PG8_MMA(0, 0, At, B0); PG8_BAR; PG8_SCHED;
;       PG8_LDB(B1, 1, 1); PG8_STAGE(PG8_SB(1, 0), b3, voffB);
;       PG8_BAR; PG8_WAIT_L(0); PG8_MMA(0, 1, At, B1); PG8_BAR;
;       PG8_LDA(At, 1, 1); PG8_STAGE(PG8_SA(1, 0), a3, voffA);
;       PG8_BAR; PG8_WAIT_L(0); PG8_MMA(1, 0, At, B0); PG8_BAR; PG8_SCHED;
	s_setprio 0
	s_add_u32 s54, s46, 0x80000
	s_addc_u32 s55, s47, 0
	s_add_i32 s53, s73, s60
	v_lshl_add_u64 v[64:65], s[54:55], 0, v[164:165]
	s_mov_b32 m0, s53
	s_nop 0
	global_load_lds_dwordx4 v[64:65], off
	v_lshl_add_u64 v[64:65], s[54:55], 0, v[160:161]
	s_add_i32 m0, s53, 0x2000
	s_nop 0
	global_load_lds_dwordx4 v[64:65], off
	s_waitcnt vmcnt(6)
	s_barrier
	s_setprio 1
	v_mfma_f32_16x16x32_bf16 v[56:59], v[206:209], v[120:123], v[56:59]
	v_mfma_f32_16x16x32_bf16 v[52:55], v[216:219], v[120:123], v[52:55]
	v_mfma_f32_16x16x32_bf16 v[40:43], v[206:209], v[136:139], v[40:43]
	v_mfma_f32_16x16x32_bf16 v[32:35], v[216:219], v[136:139], v[32:35]
	v_mfma_f32_16x16x32_bf16 v[24:27], v[206:209], v[180:183], v[24:27]
	v_mfma_f32_16x16x32_bf16 v[8:11], v[216:219], v[180:183], v[8:11]
	v_mfma_f32_16x16x32_bf16 v[4:7], v[206:209], v[188:191], v[4:7]
	v_mfma_f32_16x16x32_bf16 v[0:3], v[216:219], v[188:191], v[0:3]
	v_mfma_f32_16x16x32_bf16 v[56:59], v[212:215], v[128:131], v[56:59]
	v_mfma_f32_16x16x32_bf16 v[52:55], v[220:223], v[128:131], v[52:55]
	v_mfma_f32_16x16x32_bf16 v[40:43], v[212:215], v[148:151], v[40:43]
	v_mfma_f32_16x16x32_bf16 v[32:35], v[220:223], v[148:151], v[32:35]
	v_mfma_f32_16x16x32_bf16 v[24:27], v[212:215], v[184:187], v[24:27]
	v_mfma_f32_16x16x32_bf16 v[8:11], v[220:223], v[184:187], v[8:11]
	v_mfma_f32_16x16x32_bf16 v[4:7], v[212:215], v[192:195], v[4:7]
	v_mfma_f32_16x16x32_bf16 v[0:3], v[220:223], v[192:195], v[0:3]
	s_barrier
	s_setprio 0
	s_add_i32 s53, 0, 0x18000
	v_add_u32_e32 v76, s53, v198
	ds_read_b128 v[64:67], v76
	ds_read_b128 v[68:71], v76 offset:1024
	ds_read_b128 v[72:75], v76 offset:2048
	ds_read_b128 v[76:79], v76 offset:3072
	s_add_u32 s48, s48, 0x80000
	s_addc_u32 s49, s49, 0
	s_mov_b32 m0, s64
	v_lshl_add_u64 v[136:137], s[48:49], 0, v[166:167]
	ds_read_b128 v[120:123], v202 offset:32768
	ds_read_b128 v[128:131], v202 offset:33792
	ds_read_b128 v[180:183], v202 offset:34816
	ds_read_b128 v[184:187], v202 offset:35840
	ds_read_b128 v[188:191], v202 offset:36864
	ds_read_b128 v[192:195], v202 offset:37888
	ds_read_b128 v[206:209], v202 offset:38912
	ds_read_b128 v[212:215], v202 offset:39936
	global_load_lds_dwordx4 v[136:137], off
	v_lshl_add_u64 v[136:137], s[48:49], 0, v[162:163]
	s_mov_b32 m0, s65
	s_nop 0
	global_load_lds_dwordx4 v[136:137], off
	s_waitcnt lgkmcnt(8)
	s_barrier
	s_waitcnt lgkmcnt(0)
	s_setprio 1
	v_mfma_f32_16x16x32_bf16 v[136:139], v[64:67], v[120:123], v[156:159]
	v_mfma_f32_16x16x32_bf16 v[156:159], v[68:71], v[128:131], v[136:139]
	v_mfma_f32_16x16x32_bf16 v[136:139], v[72:75], v[120:123], v[144:147]
	v_mfma_f32_16x16x32_bf16 v[144:147], v[76:79], v[128:131], v[136:139]
	v_mfma_f32_16x16x32_bf16 v[136:139], v[64:67], v[180:183], v[140:143]
	v_mfma_f32_16x16x32_bf16 v[132:135], v[72:75], v[180:183], v[132:135]
	v_mfma_f32_16x16x32_bf16 v[124:127], v[64:67], v[188:191], v[124:127]
	v_mfma_f32_16x16x32_bf16 v[116:119], v[72:75], v[188:191], v[116:119]
	v_mfma_f32_16x16x32_bf16 v[112:115], v[64:67], v[206:209], v[112:115]
	v_mfma_f32_16x16x32_bf16 v[108:111], v[72:75], v[206:209], v[108:111]
	v_mfma_f32_16x16x32_bf16 v[140:143], v[68:71], v[184:187], v[136:139]
	v_mfma_f32_16x16x32_bf16 v[132:135], v[76:79], v[184:187], v[132:135]
	v_mfma_f32_16x16x32_bf16 v[124:127], v[68:71], v[192:195], v[124:127]
	v_mfma_f32_16x16x32_bf16 v[116:119], v[76:79], v[192:195], v[116:119]
	v_mfma_f32_16x16x32_bf16 v[112:115], v[68:71], v[212:215], v[112:115]
	v_mfma_f32_16x16x32_bf16 v[108:111], v[76:79], v[212:215], v[108:111]
	s_barrier
	s_setprio 0
	s_add_i32 s48, 0, 0x1c000
	v_add_u32_e32 v136, s48, v198
	s_add_i32 s49, s53, s60
	ds_read_b128 v[216:219], v136
	ds_read_b128 v[220:223], v136 offset:1024
	ds_read_b128 v[224:227], v136 offset:2048
	ds_read_b128 v[228:231], v136 offset:3072
	v_lshl_add_u64 v[136:137], v[196:197], 0, s[24:25]
	s_mov_b32 m0, s49
	s_nop 0
	global_load_lds_dwordx4 v[136:137], off
	v_lshl_add_u64 v[136:137], v[232:233], 0, s[24:25]
	s_add_i32 m0, s49, 0x2000
	s_nop 0
	global_load_lds_dwordx4 v[136:137], off
	s_barrier
	s_waitcnt lgkmcnt(0)
	s_setprio 1
	v_mfma_f32_16x16x32_bf16 v[80:83], v[224:227], v[120:123], v[80:83]
	v_mfma_f32_16x16x32_bf16 v[136:139], v[216:219], v[120:123], v[152:155]
	v_mfma_f32_16x16x32_bf16 v[148:151], v[228:231], v[128:131], v[80:83]
	v_mfma_f32_16x16x32_bf16 v[80:83], v[216:219], v[180:183], v[84:87]
	v_mfma_f32_16x16x32_bf16 v[152:155], v[220:223], v[128:131], v[136:139]
	v_mfma_f32_16x16x32_bf16 v[136:139], v[220:223], v[184:187], v[80:83]
	v_mfma_f32_16x16x32_bf16 v[80:83], v[224:227], v[180:183], v[92:95]
	v_mfma_f32_16x16x32_bf16 v[128:131], v[228:231], v[184:187], v[80:83]
	v_mfma_f32_16x16x32_bf16 v[80:83], v[216:219], v[188:191], v[96:99]
	v_mfma_f32_16x16x32_bf16 v[120:123], v[220:223], v[192:195], v[80:83]
	v_mfma_f32_16x16x32_bf16 v[80:83], v[224:227], v[188:191], v[104:107]
	v_mfma_f32_16x16x32_bf16 v[104:107], v[228:231], v[192:195], v[80:83]
	v_mfma_f32_16x16x32_bf16 v[80:83], v[216:219], v[206:209], v[100:103]
	v_mfma_f32_16x16x32_bf16 v[100:103], v[220:223], v[212:215], v[80:83]
	v_mfma_f32_16x16x32_bf16 v[80:83], v[224:227], v[206:209], v[88:91]
	v_mfma_f32_16x16x32_bf16 v[88:91], v[228:231], v[212:215], v[80:83]
	s_barrier
	s_setprio 0
	s_mov_b32 m0, s67
	v_lshl_add_u64 v[196:197], v[234:235], 0, s[24:25]
	s_nop 2
	ds_read_b128 v[80:83], v202 offset:49152
	ds_read_b128 v[84:87], v202 offset:50176
	ds_read_b128 v[92:95], v202 offset:51200
	ds_read_b128 v[96:99], v202 offset:52224
	ds_read_b128 v[180:183], v202 offset:53248
	ds_read_b128 v[184:187], v202 offset:54272
	ds_read_b128 v[188:191], v202 offset:55296
	ds_read_b128 v[192:195], v202 offset:56320
	global_load_lds_dwordx4 v[196:197], off
	v_lshl_add_u64 v[196:197], v[236:237], 0, s[24:25]
	s_mov_b32 m0, s68
	s_nop 0
	global_load_lds_dwordx4 v[196:197], off
	s_barrier
; #define PG8_STAGE(bufoff, gbase, voff) do { _Pragma("unroll") for (int _i = 0; _i < 2; ++_i) \
;     __builtin_amdgcn_global_load_lds((const unsigned*)((const char*)(gbase) + (voff)[_i]), (LAS unsigned*)(lds + (bufoff) + ldsw + _i * 8192), 16, 0, 0); } while (0)
; #define PG8_MMA(ai, bj, At, Bt) do { __builtin_amdgcn_s_setprio(1); _Pragma("unroll") for (int m = 0; m < 4; ++m) _Pragma("unroll") for (int n = 0; n < 2; ++n) _Pragma("unroll") for (int k = 0; k < 2; ++k) \
;     acc[ai][bj][m][n] = __builtin_amdgcn_mfma_f32_16x16x32_bf16(Bt[n][k], At[m][k], acc[ai][bj][m][n], 0, 0, 0); __builtin_amdgcn_s_setprio(0); } while (0)
; #define PG8_WAIT_V(n) asm volatile("s_waitcnt vmcnt(" #n ")" ::: "memory")
; #define PG8_WAIT_L(n) asm volatile("s_waitcnt lgkmcnt(" #n ")" ::: "memory")
; #define PG8_BAR __builtin_amdgcn_s_barrier()
; #define PG8_SCHED __builtin_amdgcn_sched_barrier(0)
;   DI void operator()(const f32x4 (&acc)[2][2][4][2], const Unit& u, int wr, int wc, int fr, int fq) const {
;     const int col = u.pn * 128 + wc * 32 + 8 * fq;
;     float w0[8], w1[8], w2[8], bb[8];
; #pragma unroll
;     for (int e = 0; e < 8; ++e) { w0[e] = cw[col + e]; w1[e] = cw[5632 + col + e]; w2[e] = cw[2 * 5632 + col + e]; bb[e] = cb[col + e]; }
; #pragma unroll
;     for (int ai = 0; ai < 2; ++ai) {
;       const int row0 = u.pm * BM + ai * HALF + wr * 64, span = row0 >> 6;
;       float rsv[4];
; #pragma unroll
;       for (int m = 0; m < 4; ++m) rsv[m] = row_rstd(ssq, row0 + 16 * m + fr, fq);
; template <class Epi, class Sched = StaticOrder>
; DI void gemm_phase(LAS unsigned char* lds, const Gemm g, const Sched& S, const Epi& E) {
;     ...
;       PG8_BAR; PG8_WAIT_L(0); PG8_MMA(1, 0, At, B0); PG8_BAR; PG8_SCHED;
;       PG8_STAGE(PG8_SB(1, 1), b3 + hstep, voffB);
;       PG8_WAIT_V(6); PG8_BAR; PG8_MMA(1, 1, At, B1); PG8_BAR;
;     }
	s_waitcnt lgkmcnt(0)
	s_setprio 1
	v_mfma_f32_16x16x32_bf16 v[60:63], v[64:67], v[80:83], v[60:63]
	v_mfma_f32_16x16x32_bf16 v[48:51], v[72:75], v[80:83], v[48:51]
	v_mfma_f32_16x16x32_bf16 v[44:47], v[64:67], v[92:95], v[44:47]
	v_mfma_f32_16x16x32_bf16 v[36:39], v[72:75], v[92:95], v[36:39]
	v_mfma_f32_16x16x32_bf16 v[28:31], v[64:67], v[180:183], v[28:31]
	v_mfma_f32_16x16x32_bf16 v[20:23], v[72:75], v[180:183], v[20:23]
	v_mfma_f32_16x16x32_bf16 v[16:19], v[64:67], v[188:191], v[16:19]
	v_mfma_f32_16x16x32_bf16 v[12:15], v[72:75], v[188:191], v[12:15]
	v_mfma_f32_16x16x32_bf16 v[60:63], v[68:71], v[84:87], v[60:63]
	v_mfma_f32_16x16x32_bf16 v[48:51], v[76:79], v[84:87], v[48:51]
	v_mfma_f32_16x16x32_bf16 v[44:47], v[68:71], v[96:99], v[44:47]
	v_mfma_f32_16x16x32_bf16 v[36:39], v[76:79], v[96:99], v[36:39]
	v_mfma_f32_16x16x32_bf16 v[28:31], v[68:71], v[184:187], v[28:31]
	v_mfma_f32_16x16x32_bf16 v[20:23], v[76:79], v[184:187], v[20:23]
	v_mfma_f32_16x16x32_bf16 v[16:19], v[68:71], v[192:195], v[16:19]
	v_mfma_f32_16x16x32_bf16 v[12:15], v[76:79], v[192:195], v[12:15]
	s_barrier
	s_setprio 0
	s_add_u32 s46, s46, 0x80080
	s_addc_u32 s47, s47, 0
	s_add_i32 s48, s48, s60
	v_lshl_add_u64 v[64:65], s[46:47], 0, v[164:165]
	s_mov_b32 m0, s48
	s_nop 0
	global_load_lds_dwordx4 v[64:65], off
	v_lshl_add_u64 v[64:65], s[46:47], 0, v[160:161]
	s_add_i32 m0, s48, 0x2000
	s_nop 0
	global_load_lds_dwordx4 v[64:65], off
	s_waitcnt vmcnt(6)
	s_barrier
	s_setprio 1
	v_mfma_f32_16x16x32_bf16 v[56:59], v[216:219], v[80:83], v[56:59]
	v_mfma_f32_16x16x32_bf16 v[52:55], v[224:227], v[80:83], v[52:55]
	v_mfma_f32_16x16x32_bf16 v[40:43], v[216:219], v[92:95], v[40:43]
	v_mfma_f32_16x16x32_bf16 v[32:35], v[224:227], v[92:95], v[32:35]
	v_mfma_f32_16x16x32_bf16 v[24:27], v[216:219], v[180:183], v[24:27]
	v_mfma_f32_16x16x32_bf16 v[8:11], v[224:227], v[180:183], v[8:11]
	v_mfma_f32_16x16x32_bf16 v[4:7], v[216:219], v[188:191], v[4:7]
	v_mfma_f32_16x16x32_bf16 v[0:3], v[224:227], v[188:191], v[0:3]
	v_mfma_f32_16x16x32_bf16 v[56:59], v[220:223], v[84:87], v[56:59]
	v_mfma_f32_16x16x32_bf16 v[52:55], v[228:231], v[84:87], v[52:55]
	v_mfma_f32_16x16x32_bf16 v[40:43], v[220:223], v[96:99], v[40:43]
	v_mfma_f32_16x16x32_bf16 v[32:35], v[228:231], v[96:99], v[32:35]
	v_mfma_f32_16x16x32_bf16 v[24:27], v[220:223], v[184:187], v[24:27]
	v_mfma_f32_16x16x32_bf16 v[8:11], v[228:231], v[184:187], v[8:11]
	v_mfma_f32_16x16x32_bf16 v[4:7], v[220:223], v[192:195], v[4:7]
	v_mfma_f32_16x16x32_bf16 v[0:3], v[228:231], v[192:195], v[0:3]
	s_add_i32 s52, s52, 2
	s_add_u32 s14, s14, 0x100
	s_addc_u32 s15, s15, 0
	s_add_u32 s44, s44, 0x100
	s_addc_u32 s45, s45, 0
	s_cmp_gt_u32 s52, 29
	s_barrier
	s_setprio 0
	s_cbranch_scc0 .LBB0_811
	s_lshl_b32 s35, s12, 8
	s_add_i32 s35, s35, s66
	v_or_b32_e32 v190, s35, v179
	v_ashrrev_i32_e32 v191, 31, v190
	v_lshlrev_b64 v[64:65], 7, v[190:191]
	v_or_b32_e32 v188, 16, v190
	v_lshl_add_u64 v[64:65], v[168:169], 0, v[64:65]
	v_ashrrev_i32_e32 v189, 31, v188
	global_load_dwordx4 v[192:195], v[64:65], off
	global_load_dwordx4 v[206:209], v[64:65], off offset:16
	v_lshlrev_b64 v[64:65], 7, v[188:189]
	v_lshl_add_u64 v[64:65], v[168:169], 0, v[64:65]
	global_load_dwordx4 v[212:215], v[64:65], off
	global_load_dwordx4 v[216:219], v[64:65], off offset:16
	v_or_b32_e32 v186, 32, v190
	v_ashrrev_i32_e32 v187, 31, v186
	v_lshlrev_b64 v[64:65], 7, v[186:187]
	v_or_b32_e32 v184, 48, v190
	v_lshl_add_u64 v[64:65], v[168:169], 0, v[64:65]
	v_ashrrev_i32_e32 v185, 31, v184
	global_load_dwordx4 v[220:223], v[64:65], off
	global_load_dwordx4 v[224:227], v[64:65], off offset:16
	v_lshlrev_b64 v[64:65], 7, v[184:185]
	v_lshl_add_u64 v[64:65], v[168:169], 0, v[64:65]
	global_load_dwordx4 v[228:231], v[64:65], off
	global_load_dwordx4 v[232:235], v[64:65], off offset:16
	v_lshl_or_b32 v180, s13, 7, v200
	v_and_b32_e32 v65, 64, v204
	v_xor_b32_e32 v64, 16, v204
	v_ashrrev_i32_e32 v181, 31, v180
	v_add_u32_e32 v65, 64, v65
	v_readlane_b32 s44, v243, 3
	v_xor_b32_e32 v66, 32, v204
	v_lshlrev_b64 v[182:183], 2, v[180:181]
	v_cmp_lt_i32_e32 vcc, v64, v65
	v_readlane_b32 s52, v243, 11
	v_readlane_b32 s53, v243, 12
	v_cndmask_b32_e32 v64, v204, v64, vcc
	v_cmp_lt_i32_e32 vcc, v66, v65
	v_lshl_add_u64 v[92:93], s[52:53], 0, v[182:183]
	v_readlane_b32 s54, v243, 13
	v_cndmask_b32_e32 v65, v204, v66, vcc
	v_add_co_u32_e32 v94, vcc, 0x5000, v92
	v_readlane_b32 s55, v243, 14
	s_nop 0
	v_addc_co_u32_e32 v95, vcc, 0, v93, vcc
	v_add_co_u32_e32 v96, vcc, 0xb000, v92
	v_lshl_add_u64 v[72:73], s[54:55], 0, v[182:183]
	v_lshl_add_u64 v[74:75], v[92:93], 0, s[26:27]
	v_lshl_add_u64 v[76:77], v[92:93], 0, s[28:29]
	v_addc_co_u32_e32 v97, vcc, 0, v93, vcc
	v_lshlrev_b32_e32 v187, 2, v64
	v_lshlrev_b32_e32 v185, 2, v65
	global_load_dwordx4 v[64:67], v[92:93], off offset:16
	global_load_dwordx4 v[80:83], v[92:93], off
	global_load_dwordx4 v[68:71], v[72:73], off offset:16
	global_load_dwordx4 v[84:87], v[72:73], off
	s_nop 0
	global_load_dwordx4 v[72:75], v[74:75], off offset:16
	s_nop 0
	global_load_dwordx4 v[76:79], v[76:77], off offset:16
	s_nop 0
	global_load_dwordx4 v[92:95], v[94:95], off offset:2048
	s_nop 0
	global_load_dwordx4 v[96:99], v[96:97], off
	v_mov_b32_e32 v211, 0
	v_mov_b32_e32 v205, 0
	v_readlane_b32 s45, v243, 4
	v_readlane_b32 s46, v243, 5
	v_readlane_b32 s47, v243, 6
	v_readlane_b32 s48, v243, 7
	v_readlane_b32 s49, v243, 8
	v_readlane_b32 s50, v243, 9
	v_readlane_b32 s51, v243, 10
	v_readlane_b32 s56, v243, 15
	v_readlane_b32 s57, v243, 16
	v_readlane_b32 s58, v243, 17
	v_readlane_b32 s59, v243, 18
	s_waitcnt vmcnt(0)
; DI float dpp_ror1(float v) { return __int_as_float(__builtin_amdgcn_update_dpp(0, __float_as_int(v), 0x121, 0xf, 0xf, false)); }
; DI float dpp_ror2(float v) { return __int_as_float(__builtin_amdgcn_update_dpp(0, __float_as_int(v), 0x122, 0xf, 0xf, false)); }
;   DI void operator()(const f32x4 (&acc)[2][2][4][2], const Unit& u, int wr, int wc, int fr, int fq) const {
;     ...
;       for (int m = 0; m < 4; ++m) rsv[m] = row_rstd(ssq, row0 + 16 * m + fr, fq);
;       float p1[8], p2[8];
; #pragma unroll
;       for (int e = 0; e < 8; ++e) { p1[e] = 0.f; p2[e] = 0.f; }
; #pragma unroll
;       for (int m = 0; m < 4; ++m) {
;         float g[8], uu[8], a[8];
;         const float rs = rsv[m];
; #pragma unroll
;         for (int e = 0; e < 4; ++e) { g[e] = acc[ai][0][m][0][e] * rs; g[4 + e] = acc[ai][0][m][1][e] * rs; uu[e] = acc[ai][1][m][0][e] * rs; uu[4 + e] = acc[ai][1][m][1][e] * rs; }
; #pragma unroll
;         for (int e = 0; e < 8; ++e) {
;           const float x1 = dpp_ror1(g[e]), x2 = dpp_ror2(g[e]);
;           const float pr1 = (fr == 0) ? p1[e] : x1, pr2 = (fr < 2) ? p2[e] : x2;
;           a[e] = w2[e] * g[e] + w1[e] * pr1 + w0[e] * pr2 + bb[e];
;           p1[e] = x1; p2[e] = x2;
;         }
	v_mov_b32_e32 v196, v192
	v_mov_b32_e32 v197, v206
	v_mov_b32_e32 v206, v193
	v_mov_b32_e32 v192, v194
	v_mov_b32_e32 v193, v208
	v_mov_b32_e32 v208, v195
	v_pk_add_f32 v[194:195], v[196:197], v[206:207]
	v_pk_add_f32 v[192:193], v[192:193], v[208:209]
	v_mov_b32_e32 v196, v212
	v_mov_b32_e32 v197, v216
	v_mov_b32_e32 v216, v213
	v_mov_b32_e32 v206, v214
	v_mov_b32_e32 v207, v218
	v_mov_b32_e32 v218, v215
	v_pk_add_f32 v[192:193], v[194:195], v[192:193]
	v_pk_add_f32 v[194:195], v[196:197], v[216:217]
	v_pk_add_f32 v[196:197], v[206:207], v[218:219]
	v_mov_b32_e32 v208, v220
	v_pk_add_f32 v[194:195], v[194:195], v[196:197]
	v_mov_b32_e32 v197, v192
	v_mov_b32_e32 v196, v194
	v_mov_b32_e32 v192, v195
	v_pk_add_f32 v[192:193], v[196:197], v[192:193]
	ds_bpermute_b32 v195, v187, v193
	ds_bpermute_b32 v194, v187, v192
	v_mov_b32_e32 v209, v224
	v_mov_b32_e32 v224, v221
	v_mov_b32_e32 v212, v222
	v_mov_b32_e32 v213, v226
	s_waitcnt lgkmcnt(0)
	v_pk_add_f32 v[192:193], v[192:193], v[194:195]
	ds_bpermute_b32 v195, v185, v193
	ds_bpermute_b32 v194, v185, v192
	v_mov_b32_e32 v226, v223
	v_mov_b32_e32 v196, v228
	v_mov_b32_e32 v197, v232
	v_mov_b32_e32 v232, v229
	s_waitcnt lgkmcnt(0)
	v_pk_add_f32 v[192:193], v[192:193], v[194:195]
	v_mov_b32_e32 v206, v230
	v_pk_fma_f32 v[192:193], v[192:193], s[30:31], v[178:179] op_sel_hi:[1,0,0]
	v_mov_b32_e32 v207, v234
	v_mul_f32_e32 v189, 0x4b800000, v193
	v_cmp_gt_f32_e64 s[12:13], s74, v193
	v_mov_b32_e32 v234, v231
	v_pk_add_f32 v[208:209], v[208:209], v[224:225]
	v_cndmask_b32_e64 v189, v193, v189, s[12:13]
	v_rsq_f32_e32 v189, v189
	v_pk_add_f32 v[212:213], v[212:213], v[226:227]
	v_pk_add_f32 v[196:197], v[196:197], v[232:233]
	v_pk_add_f32 v[194:195], v[206:207], v[234:235]
	v_mul_f32_e32 v191, 0x45800000, v189
	v_cndmask_b32_e64 v220, v189, v191, s[12:13]
	v_pk_add_f32 v[208:209], v[208:209], v[212:213]
	v_pk_add_f32 v[194:195], v[196:197], v[194:195]
	v_pk_mul_f32 v[156:157], v[156:157], v[220:221] op_sel_hi:[1,0]
	v_mov_b32_e32 v216, 0
	v_mov_b32_e32 v218, 0
	v_mov_b32_e32 v196, v194
	v_mov_b32_e32 v197, v208
	v_mov_b32_e32 v208, v195
	v_mov_b32_dpp v216, v156 row_ror:1 row_mask:0xf bank_mask:0xf
	v_mov_b32_dpp v218, v157 row_ror:1 row_mask:0xf bank_mask:0xf
	v_pk_add_f32 v[194:195], v[196:197], v[208:209]
	v_cndmask_b32_e64 v207, v218, 0, s[0:1]
	v_cndmask_b32_e64 v206, v216, 0, s[0:1]
	v_pk_mul_f32 v[158:159], v[158:159], v[220:221] op_sel_hi:[1,0]
	v_mov_b32_e32 v212, 0
	v_mov_b32_e32 v214, 0
	ds_bpermute_b32 v197, v187, v195
	ds_bpermute_b32 v196, v187, v194
	v_mov_b32_e32 v215, 0
	v_mov_b32_e32 v217, 0
	v_pk_mul_f32 v[206:207], v[92:93], v[206:207]
	v_mov_b32_dpp v212, v158 row_ror:1 row_mask:0xf bank_mask:0xf
	v_mov_b32_dpp v214, v159 row_ror:1 row_mask:0xf bank_mask:0xf
	v_mov_b32_dpp v215, v156 row_ror:2 row_mask:0xf bank_mask:0xf
	v_mov_b32_dpp v217, v157 row_ror:2 row_mask:0xf bank_mask:0xf
	v_pk_fma_f32 v[156:157], v[96:97], v[156:157], v[206:207]
	v_mov_b32_e32 v213, 0
	v_cndmask_b32_e64 v207, v214, 0, s[0:1]
	v_cndmask_b32_e64 v206, v212, 0, s[0:1]
	v_cndmask_b32_e64 v209, v217, 0, s[4:5]
	v_cndmask_b32_e64 v208, v215, 0, s[4:5]
	v_mov_b32_dpp v211, v158 row_ror:2 row_mask:0xf bank_mask:0xf
	v_mov_b32_dpp v213, v159 row_ror:2 row_mask:0xf bank_mask:0xf
	v_pk_mul_f32 v[206:207], v[94:95], v[206:207]
	v_pk_fma_f32 v[156:157], v[80:81], v[208:209], v[156:157]
	v_cndmask_b32_e64 v209, v213, 0, s[4:5]
	v_cndmask_b32_e64 v208, v211, 0, s[4:5]
	v_pk_fma_f32 v[158:159], v[98:99], v[158:159], v[206:207]
	v_pk_mul_f32 v[144:145], v[144:145], v[220:221] op_sel_hi:[1,0]
	v_pk_fma_f32 v[158:159], v[82:83], v[208:209], v[158:159]
	v_mov_b32_e32 v207, 0
	v_mov_b32_e32 v209, 0
	v_pk_mul_f32 v[146:147], v[146:147], v[220:221] op_sel_hi:[1,0]
	v_mov_b32_e32 v191, 0
	s_waitcnt lgkmcnt(0)
	v_pk_add_f32 v[194:195], v[194:195], v[196:197]
	v_mov_b32_dpp v207, v144 row_ror:1 row_mask:0xf bank_mask:0xf
	v_mov_b32_dpp v209, v145 row_ror:1 row_mask:0xf bank_mask:0xf
	v_mov_b32_dpp v191, v146 row_ror:1 row_mask:0xf bank_mask:0xf
	v_mov_b32_dpp v205, v147 row_ror:1 row_mask:0xf bank_mask:0xf
	ds_bpermute_b32 v197, v185, v195
	ds_bpermute_b32 v196, v185, v194
	v_pk_mul_f32 v[152:153], v[152:153], v[220:221] op_sel_hi:[1,0]
	v_pk_mul_f32 v[148:149], v[148:149], v[220:221] op_sel_hi:[1,0]
	v_pk_mul_f32 v[154:155], v[154:155], v[220:221] op_sel_hi:[1,0]
	v_pk_mul_f32 v[150:151], v[150:151], v[220:221] op_sel_hi:[1,0]
	v_mov_b32_e32 v206, 0
	v_mov_b32_e32 v208, 0
	v_cndmask_b32_e64 v223, v209, 0, s[0:1]
	v_cndmask_b32_e64 v222, v207, 0, s[0:1]
	v_mov_b32_e32 v189, 0
	v_mov_b32_e32 v193, 0
	v_cndmask_b32_e64 v221, v205, 0, s[0:1]
	v_cndmask_b32_e64 v220, v191, 0, s[0:1]
	v_mov_b32_dpp v206, v144 row_ror:2 row_mask:0xf bank_mask:0xf
	v_mov_b32_dpp v208, v145 row_ror:2 row_mask:0xf bank_mask:0xf
	v_pk_mul_f32 v[222:223], v[72:73], v[222:223]
	v_mov_b32_dpp v189, v146 row_ror:2 row_mask:0xf bank_mask:0xf
	v_mov_b32_dpp v193, v147 row_ror:2 row_mask:0xf bank_mask:0xf
	v_pk_mul_f32 v[220:221], v[74:75], v[220:221]
	v_cndmask_b32_e64 v225, v208, 0, s[4:5]
	v_cndmask_b32_e64 v224, v206, 0, s[4:5]
	v_pk_fma_f32 v[144:145], v[76:77], v[144:145], v[222:223]
	v_cndmask_b32_e64 v223, v193, 0, s[4:5]
	v_cndmask_b32_e64 v222, v189, 0, s[4:5]
	v_pk_fma_f32 v[146:147], v[78:79], v[146:147], v[220:221]
	v_pk_fma_f32 v[144:145], v[64:65], v[224:225], v[144:145]
	v_pk_fma_f32 v[146:147], v[66:67], v[222:223], v[146:147]
	v_cmp_gt_f32_e32 vcc, s74, v192
	v_pk_add_f32 v[156:157], v[84:85], v[156:157]
	v_pk_add_f32 v[158:159], v[86:87], v[158:159]
	v_pk_add_f32 v[144:145], v[68:69], v[144:145]
	v_pk_add_f32 v[146:147], v[70:71], v[146:147]
	s_and_saveexec_b64 s[12:13], s[10:11]
	s_xor_b64 s[12:13], exec, s[12:13]
	s_cbranch_execz .LBB0_814
; DI unsigned pack2(float lo, float hi) { f32x2 v = {lo, hi}; bf16v2 r = __builtin_convertvector(v, bf16v2); return __builtin_bit_cast(unsigned, r); }
; DI float silu_f(float x) { return x * sigmoid_f(x); }
;   DI void operator()(const f32x4 (&acc)[2][2][4][2], const Unit& u, int wr, int wc, int fr, int fq) const {
;     ...
;           u32x4 w;
;           w.x = pack2(silu_f(a[0]) * uu[0], silu_f(a[1]) * uu[1]);
;           w.y = pack2(silu_f(a[2]) * uu[2], silu_f(a[3]) * uu[3]);
;           w.z = pack2(silu_f(a[4]) * uu[4], silu_f(a[5]) * uu[5]);
;           w.w = pack2(silu_f(a[6]) * uu[6], silu_f(a[7]) * uu[7]);
;           *(u32x4*)(H + (size_t)(row0 + 16 * m + fr) * 5632 + col) = w;
	v_mul_f32_e32 v219, 0xbfb8aa3b, v156
	v_exp_f32_e32 v219, v219
	v_mul_f32_e32 v220, 0xbfb8aa3b, v157
	v_exp_f32_e32 v220, v220
	v_mul_f32_e32 v222, 0xbfb8aa3b, v159
	v_add_f32_e32 v219, 1.0, v219
	v_exp_f32_e32 v223, v222
	v_add_f32_e32 v221, 1.0, v220
	v_rcp_f32_e32 v220, v219
	v_mul_f32_e32 v219, 0xbfb8aa3b, v158
	v_exp_f32_e32 v219, v219
	v_rcp_f32_e32 v221, v221
	v_add_f32_e32 v219, 1.0, v219
	v_rcp_f32_e32 v222, v219
	v_add_f32_e32 v219, 1.0, v223
	v_rcp_f32_e32 v223, v219
	v_pk_mul_f32 v[156:157], v[156:157], v[220:221]
	s_nop 0
	v_pk_mul_f32 v[152:153], v[152:153], v[156:157]
	v_pk_mul_f32 v[156:157], v[158:159], v[222:223]
	v_cvt_pk_bf16_f32 v152, v152, v153
	v_mul_f32_e32 v153, 0xbfb8aa3b, v144
	v_pk_mul_f32 v[154:155], v[154:155], v[156:157]
	v_exp_f32_e32 v156, v153
	v_mul_f32_e32 v153, 0xbfb8aa3b, v145
	v_exp_f32_e32 v157, v153
	v_cvt_pk_bf16_f32 v153, v154, v155
	v_add_f32_e32 v154, 1.0, v156
	v_mul_f32_e32 v156, 0xbfb8aa3b, v146
	v_add_f32_e32 v155, 1.0, v157
	v_mul_f32_e32 v157, 0xbfb8aa3b, v147
	v_exp_f32_e32 v156, v156
	v_exp_f32_e32 v157, v157
	v_rcp_f32_e32 v154, v154
	v_rcp_f32_e32 v155, v155
	v_add_f32_e32 v156, 1.0, v156
	v_add_f32_e32 v157, 1.0, v157
	v_rcp_f32_e32 v156, v156
	v_rcp_f32_e32 v157, v157
	v_pk_mul_f32 v[144:145], v[144:145], v[154:155]
	s_nop 0
	v_pk_mul_f32 v[144:145], v[148:149], v[144:145]
	s_nop 0
	v_cvt_pk_bf16_f32 v154, v144, v145
	v_pk_mul_f32 v[144:145], v[146:147], v[156:157]
	s_nop 0
	v_pk_mul_f32 v[144:145], v[150:151], v[144:145]
	s_nop 0
	v_cvt_pk_bf16_f32 v155, v144, v145
	v_mov_b64_e32 v[144:145], s[16:17]
	v_mad_i64_i32 v[144:145], s[14:15], v190, s75, v[144:145]
	v_lshl_add_u64 v[144:145], v[180:181], 1, v[144:145]
	global_store_dwordx4 v[144:145], v[152:155], off

; #define PG8_STAGE(bufoff, gbase, voff) do { _Pragma("unroll") for (int _i = 0; _i < 2; ++_i) \
;     __builtin_amdgcn_global_load_lds((const unsigned*)((const char*)(gbase) + (voff)[_i]), (LAS unsigned*)(lds + (bufoff) + ldsw + _i * 8192), 16, 0, 0); } while (0)
; #define PG8_LDA(dst, b, h) do { _Pragma("unroll") for (int m = 0; m < 4; ++m) _Pragma("unroll") for (int k = 0; k < 2; ++k) dst[m][k] = *(const LAS bf16x8*)(lds + PG8_SA(b, h) + aoff + m * 2048 + k * 1024); } while (0)
; #define PG8_LDB(dst, b, h) do { _Pragma("unroll") for (int n = 0; n < 2; ++n) _Pragma("unroll") for (int k = 0; k < 2; ++k) dst[n][k] = *(const LAS bf16x8*)(lds + PG8_SB(b, h) + boff + n * 2048 + k * 1024); } while (0)
; #define PG8_MMA(ai, bj, At, Bt) do { __builtin_amdgcn_s_setprio(1); _Pragma("unroll") for (int m = 0; m < 4; ++m) _Pragma("unroll") for (int n = 0; n < 2; ++n) _Pragma("unroll") for (int k = 0; k < 2; ++k) \
;     acc[ai][bj][m][n] = __builtin_amdgcn_mfma_f32_16x16x32_bf16(Bt[n][k], At[m][k], acc[ai][bj][m][n], 0, 0, 0); __builtin_amdgcn_s_setprio(0); } while (0)
; #define PG8_WAIT_V(n) asm volatile("s_waitcnt vmcnt(" #n ")" ::: "memory")
; #define PG8_WAIT_L(n) asm volatile("s_waitcnt lgkmcnt(" #n ")" ::: "memory")
; #define PG8_BAR __builtin_amdgcn_s_barrier()
; #define PG8_SCHED __builtin_amdgcn_sched_barrier(0)
; template <class Epi, class Sched = StaticOrder>
; DI void gemm_phase(LAS unsigned char* lds, const Gemm g, const Sched& S, const Epi& E) {
;     ...
;     for (int t = 0; t < nt; t += 2) {
;       const bool last = (t == nt - 2);
;       const char* a1 = cA + (size_t)(t + 1) * kstep;
;       const char* a2 = last ? nA : cA + (size_t)(t + 2) * kstep; const char* b2 = last ? nB : cB + (size_t)(t + 2) * kstep;
;       const char* a3 = a2 + kstep; const char* b3 = b2 + kstep;
;       PG8_LDB(B0, 0, 0); PG8_SCHED; PG8_LDA(At, 0, 0); PG8_STAGE(PG8_SA(1, 1), a1 + hstep, voffA);
;       PG8_WAIT_L(8); PG8_BAR; PG8_WAIT_L(0); PG8_MMA(0, 0, At, B0); PG8_BAR; PG8_SCHED;
;       PG8_LDB(B1, 0, 1); PG8_STAGE(PG8_SB(0, 0), b2, voffB);
;       PG8_BAR; PG8_WAIT_L(0); PG8_MMA(0, 1, At, B1); PG8_BAR;
;       PG8_LDA(At, 0, 1); PG8_STAGE(PG8_SA(0, 0), a2, voffA);
;       PG8_BAR; PG8_WAIT_L(0); PG8_MMA(1, 0, At, B0); PG8_BAR; PG8_SCHED;
;       PG8_STAGE(PG8_SB(0, 1), b2 + hstep, voffB);
;       PG8_WAIT_V(6); PG8_BAR; PG8_MMA(1, 1, At, B1); PG8_BAR;
.LBB0_961:
	ds_read_b128 v[128:131], v214
	ds_read_b128 v[132:135], v214 offset:1024
	ds_read_b128 v[136:139], v214 offset:2048
	ds_read_b128 v[140:143], v214 offset:3072
	s_add_u32 s20, s18, 0xffea0080
	s_addc_u32 s21, s19, -1
	s_cmpk_eq_i32 s44, 0x54
	s_cselect_b32 s23, s5, s21
	s_cselect_b32 s22, s4, s20
	s_cselect_b32 s21, s7, s43
	s_cselect_b32 s20, s6, s42
	v_lshl_add_u64 v[192:193], s[18:19], 0, v[184:185]
	s_add_i32 m0, s31, 0xc000
	ds_read_b128 v[144:147], v215
	ds_read_b128 v[148:151], v215 offset:1024
	ds_read_b128 v[152:155], v215 offset:2048
	ds_read_b128 v[156:159], v215 offset:3072
	ds_read_b128 v[160:163], v215 offset:4096
	ds_read_b128 v[164:167], v215 offset:5120
	ds_read_b128 v[168:171], v215 offset:6144
	ds_read_b128 v[172:175], v215 offset:7168
	global_load_lds_dwordx4 v[192:193], off
	v_lshl_add_u64 v[192:193], s[18:19], 0, v[186:187]
	s_add_i32 m0, s31, 0xe000
	s_nop 0
	global_load_lds_dwordx4 v[192:193], off
	s_waitcnt lgkmcnt(8)
	s_barrier
	s_waitcnt lgkmcnt(0)
	s_setprio 1
	v_mfma_f32_16x16x32_bf16 v[124:127], v[128:131], v[144:147], v[124:127]
	v_mfma_f32_16x16x32_bf16 v[120:123], v[136:139], v[144:147], v[120:123]
	v_mfma_f32_16x16x32_bf16 v[108:111], v[128:131], v[152:155], v[108:111]
	v_mfma_f32_16x16x32_bf16 v[104:107], v[136:139], v[152:155], v[104:107]
	v_mfma_f32_16x16x32_bf16 v[92:95], v[128:131], v[160:163], v[92:95]
	v_mfma_f32_16x16x32_bf16 v[88:91], v[136:139], v[160:163], v[88:91]
	v_mfma_f32_16x16x32_bf16 v[76:79], v[128:131], v[168:171], v[76:79]
	v_mfma_f32_16x16x32_bf16 v[72:75], v[136:139], v[168:171], v[72:75]
	v_mfma_f32_16x16x32_bf16 v[124:127], v[132:135], v[148:151], v[124:127]
	v_mfma_f32_16x16x32_bf16 v[120:123], v[140:143], v[148:151], v[120:123]
	v_mfma_f32_16x16x32_bf16 v[108:111], v[132:135], v[156:159], v[108:111]
	v_mfma_f32_16x16x32_bf16 v[104:107], v[140:143], v[156:159], v[104:107]
	v_mfma_f32_16x16x32_bf16 v[92:95], v[132:135], v[164:167], v[92:95]
	v_mfma_f32_16x16x32_bf16 v[88:91], v[140:143], v[164:167], v[88:91]
	v_mfma_f32_16x16x32_bf16 v[76:79], v[132:135], v[172:175], v[76:79]
	v_mfma_f32_16x16x32_bf16 v[72:75], v[140:143], v[172:175], v[72:75]
	s_barrier
	s_setprio 0
	s_add_i32 s45, s46, s30
	v_lshl_add_u64 v[208:209], s[20:21], 0, v[178:179]
	s_mov_b32 m0, s45
	ds_read_b128 v[192:195], v216
	ds_read_b128 v[196:199], v216 offset:1024
	ds_read_b128 v[200:203], v216 offset:2048
	ds_read_b128 v[204:207], v216 offset:3072
	global_load_lds_dwordx4 v[208:209], off
	v_lshl_add_u64 v[218:219], s[20:21], 0, v[182:183]
	s_add_i32 m0, s45, 0x2000
	s_nop 0
	global_load_lds_dwordx4 v[218:219], off
	s_barrier
	s_waitcnt lgkmcnt(0)
	s_setprio 1
	v_mfma_f32_16x16x32_bf16 v[116:119], v[192:195], v[144:147], v[116:119]
	v_mfma_f32_16x16x32_bf16 v[112:115], v[200:203], v[144:147], v[112:115]
	v_mfma_f32_16x16x32_bf16 v[100:103], v[192:195], v[152:155], v[100:103]
	v_mfma_f32_16x16x32_bf16 v[96:99], v[200:203], v[152:155], v[96:99]
	v_mfma_f32_16x16x32_bf16 v[84:87], v[192:195], v[160:163], v[84:87]
	v_mfma_f32_16x16x32_bf16 v[80:83], v[200:203], v[160:163], v[80:83]
	v_mfma_f32_16x16x32_bf16 v[68:71], v[192:195], v[168:171], v[68:71]
	v_mfma_f32_16x16x32_bf16 v[64:67], v[200:203], v[168:171], v[64:67]
	v_mfma_f32_16x16x32_bf16 v[116:119], v[196:199], v[148:151], v[116:119]
	v_mfma_f32_16x16x32_bf16 v[112:115], v[204:207], v[148:151], v[112:115]
	v_mfma_f32_16x16x32_bf16 v[100:103], v[196:199], v[156:159], v[100:103]
	v_mfma_f32_16x16x32_bf16 v[96:99], v[204:207], v[156:159], v[96:99]
	v_mfma_f32_16x16x32_bf16 v[84:87], v[196:199], v[164:167], v[84:87]
	v_mfma_f32_16x16x32_bf16 v[80:83], v[204:207], v[164:167], v[80:83]
	v_mfma_f32_16x16x32_bf16 v[68:71], v[196:199], v[172:175], v[68:71]
	v_mfma_f32_16x16x32_bf16 v[64:67], v[204:207], v[172:175], v[64:67]
	s_barrier
	s_setprio 0
	s_mov_b32 m0, s31
	v_lshl_add_u64 v[220:221], s[22:23], 0, v[176:177]
	ds_read_b128 v[144:147], v215 offset:16384
	ds_read_b128 v[148:151], v215 offset:17408
	ds_read_b128 v[152:155], v215 offset:18432
	ds_read_b128 v[156:159], v215 offset:19456
	ds_read_b128 v[160:163], v215 offset:20480
	ds_read_b128 v[164:167], v215 offset:21504
	ds_read_b128 v[168:171], v215 offset:22528
	ds_read_b128 v[172:175], v215 offset:23552
	global_load_lds_dwordx4 v[220:221], off
	v_lshl_add_u64 v[222:223], s[22:23], 0, v[180:181]
	s_mov_b32 m0, s33
	s_nop 0
	global_load_lds_dwordx4 v[222:223], off
	s_barrier
	s_waitcnt lgkmcnt(0)
	s_setprio 1
	v_mfma_f32_16x16x32_bf16 v[60:63], v[128:131], v[144:147], v[60:63]
	v_mfma_f32_16x16x32_bf16 v[56:59], v[136:139], v[144:147], v[56:59]
	v_mfma_f32_16x16x32_bf16 v[44:47], v[128:131], v[152:155], v[44:47]
	v_mfma_f32_16x16x32_bf16 v[40:43], v[136:139], v[152:155], v[40:43]
	v_mfma_f32_16x16x32_bf16 v[28:31], v[128:131], v[160:163], v[28:31]
	v_mfma_f32_16x16x32_bf16 v[24:27], v[136:139], v[160:163], v[24:27]
	v_mfma_f32_16x16x32_bf16 v[12:15], v[128:131], v[168:171], v[12:15]
	v_mfma_f32_16x16x32_bf16 v[8:11], v[136:139], v[168:171], v[8:11]
	v_mfma_f32_16x16x32_bf16 v[60:63], v[132:135], v[148:151], v[60:63]
	v_mfma_f32_16x16x32_bf16 v[56:59], v[140:143], v[148:151], v[56:59]
	v_mfma_f32_16x16x32_bf16 v[44:47], v[132:135], v[156:159], v[44:47]
	v_mfma_f32_16x16x32_bf16 v[40:43], v[140:143], v[156:159], v[40:43]
	v_mfma_f32_16x16x32_bf16 v[28:31], v[132:135], v[164:167], v[28:31]
	v_mfma_f32_16x16x32_bf16 v[24:27], v[140:143], v[164:167], v[24:27]
	v_mfma_f32_16x16x32_bf16 v[12:15], v[132:135], v[172:175], v[12:15]
	v_mfma_f32_16x16x32_bf16 v[8:11], v[140:143], v[172:175], v[8:11]
	s_barrier
; #define PG8_STAGE(bufoff, gbase, voff) do { _Pragma("unroll") for (int _i = 0; _i < 2; ++_i) \
;     __builtin_amdgcn_global_load_lds((const unsigned*)((const char*)(gbase) + (voff)[_i]), (LAS unsigned*)(lds + (bufoff) + ldsw + _i * 8192), 16, 0, 0); } while (0)
; #define PG8_LDA(dst, b, h) do { _Pragma("unroll") for (int m = 0; m < 4; ++m) _Pragma("unroll") for (int k = 0; k < 2; ++k) dst[m][k] = *(const LAS bf16x8*)(lds + PG8_SA(b, h) + aoff + m * 2048 + k * 1024); } while (0)
; #define PG8_LDB(dst, b, h) do { _Pragma("unroll") for (int n = 0; n < 2; ++n) _Pragma("unroll") for (int k = 0; k < 2; ++k) dst[n][k] = *(const LAS bf16x8*)(lds + PG8_SB(b, h) + boff + n * 2048 + k * 1024); } while (0)
; #define PG8_MMA(ai, bj, At, Bt) do { __builtin_amdgcn_s_setprio(1); _Pragma("unroll") for (int m = 0; m < 4; ++m) _Pragma("unroll") for (int n = 0; n < 2; ++n) _Pragma("unroll") for (int k = 0; k < 2; ++k) \
;     acc[ai][bj][m][n] = __builtin_amdgcn_mfma_f32_16x16x32_bf16(Bt[n][k], At[m][k], acc[ai][bj][m][n], 0, 0, 0); __builtin_amdgcn_s_setprio(0); } while (0)
; #define PG8_WAIT_V(n) asm volatile("s_waitcnt vmcnt(" #n ")" ::: "memory")
; #define PG8_WAIT_L(n) asm volatile("s_waitcnt lgkmcnt(" #n ")" ::: "memory")
; #define PG8_BAR __builtin_amdgcn_s_barrier()
; #define PG8_SCHED __builtin_amdgcn_sched_barrier(0)
; template <class Epi, class Sched = StaticOrder>
; DI void gemm_phase(LAS unsigned char* lds, const Gemm g, const Sched& S, const Epi& E) {
;     ...
;       PG8_STAGE(PG8_SB(0, 1), b2 + hstep, voffB);
;       PG8_WAIT_V(6); PG8_BAR; PG8_MMA(1, 1, At, B1); PG8_BAR;
;       PG8_LDB(B0, 1, 0); PG8_SCHED; PG8_LDA(At, 1, 0); PG8_STAGE(PG8_SA(0, 1), a2 + hstep, voffA);
;       PG8_WAIT_L(8); PG8_BAR; PG8_WAIT_L(0); PG8_MMA(0, 0, At, B0); PG8_BAR; PG8_SCHED;
;       PG8_LDB(B1, 1, 1); PG8_STAGE(PG8_SB(1, 0), b3, voffB);
;       PG8_BAR; PG8_WAIT_L(0); PG8_MMA(0, 1, At, B1); PG8_BAR;
;       PG8_LDA(At, 1, 1); PG8_STAGE(PG8_SA(1, 0), a3, voffA);
;       PG8_BAR; PG8_WAIT_L(0); PG8_MMA(1, 0, At, B0); PG8_BAR; PG8_SCHED;
	s_setprio 0
	s_add_u32 s52, s20, 0x160000
	s_addc_u32 s53, s21, 0
	s_add_i32 s45, s47, s30
	v_lshl_add_u64 v[128:129], s[52:53], 0, v[178:179]
	s_mov_b32 m0, s45
	s_nop 0
	global_load_lds_dwordx4 v[128:129], off
	v_lshl_add_u64 v[128:129], s[52:53], 0, v[182:183]
	s_add_i32 m0, s45, 0x2000
	s_nop 0
	global_load_lds_dwordx4 v[128:129], off
	s_waitcnt vmcnt(6)
	s_barrier
	s_setprio 1
	v_mfma_f32_16x16x32_bf16 v[52:55], v[192:195], v[144:147], v[52:55]
	v_mfma_f32_16x16x32_bf16 v[48:51], v[200:203], v[144:147], v[48:51]
	v_mfma_f32_16x16x32_bf16 v[36:39], v[192:195], v[152:155], v[36:39]
	v_mfma_f32_16x16x32_bf16 v[32:35], v[200:203], v[152:155], v[32:35]
	v_mfma_f32_16x16x32_bf16 v[20:23], v[192:195], v[160:163], v[20:23]
	v_mfma_f32_16x16x32_bf16 v[16:19], v[200:203], v[160:163], v[16:19]
	v_mfma_f32_16x16x32_bf16 v[4:7], v[192:195], v[168:171], v[4:7]
	v_mfma_f32_16x16x32_bf16 v[0:3], v[200:203], v[168:171], v[0:3]
	v_mfma_f32_16x16x32_bf16 v[52:55], v[196:199], v[148:151], v[52:55]
	v_mfma_f32_16x16x32_bf16 v[48:51], v[204:207], v[148:151], v[48:51]
	v_mfma_f32_16x16x32_bf16 v[36:39], v[196:199], v[156:159], v[36:39]
	v_mfma_f32_16x16x32_bf16 v[32:35], v[204:207], v[156:159], v[32:35]
	v_mfma_f32_16x16x32_bf16 v[20:23], v[196:199], v[164:167], v[20:23]
	v_mfma_f32_16x16x32_bf16 v[16:19], v[204:207], v[164:167], v[16:19]
	v_mfma_f32_16x16x32_bf16 v[4:7], v[196:199], v[172:175], v[4:7]
	v_mfma_f32_16x16x32_bf16 v[0:3], v[204:207], v[172:175], v[0:3]
	s_barrier
	s_setprio 0
	s_add_i32 s45, 0, 0x18000
	v_add_u32_e32 v140, s45, v212
	ds_read_b128 v[128:131], v140
	ds_read_b128 v[132:135], v140 offset:1024
	ds_read_b128 v[136:139], v140 offset:2048
	ds_read_b128 v[140:143], v140 offset:3072
	s_add_u32 s22, s22, 0x160000
	s_addc_u32 s23, s23, 0
	s_mov_b32 m0, s34
	v_lshl_add_u64 v[192:193], s[22:23], 0, v[176:177]
	ds_read_b128 v[144:147], v215 offset:32768
	ds_read_b128 v[148:151], v215 offset:33792
	ds_read_b128 v[152:155], v215 offset:34816
	ds_read_b128 v[156:159], v215 offset:35840
	ds_read_b128 v[160:163], v215 offset:36864
	ds_read_b128 v[164:167], v215 offset:37888
	ds_read_b128 v[168:171], v215 offset:38912
	ds_read_b128 v[172:175], v215 offset:39936
	global_load_lds_dwordx4 v[192:193], off
	v_lshl_add_u64 v[192:193], s[22:23], 0, v[180:181]
	s_mov_b32 m0, s35
	s_nop 0
	global_load_lds_dwordx4 v[192:193], off
	s_waitcnt lgkmcnt(8)
	s_barrier
	s_waitcnt lgkmcnt(0)
	s_setprio 1
	v_mfma_f32_16x16x32_bf16 v[124:127], v[128:131], v[144:147], v[124:127]
	v_mfma_f32_16x16x32_bf16 v[120:123], v[136:139], v[144:147], v[120:123]
	v_mfma_f32_16x16x32_bf16 v[108:111], v[128:131], v[152:155], v[108:111]
	v_mfma_f32_16x16x32_bf16 v[104:107], v[136:139], v[152:155], v[104:107]
	v_mfma_f32_16x16x32_bf16 v[92:95], v[128:131], v[160:163], v[92:95]
	v_mfma_f32_16x16x32_bf16 v[88:91], v[136:139], v[160:163], v[88:91]
	v_mfma_f32_16x16x32_bf16 v[76:79], v[128:131], v[168:171], v[76:79]
	v_mfma_f32_16x16x32_bf16 v[72:75], v[136:139], v[168:171], v[72:75]
	v_mfma_f32_16x16x32_bf16 v[124:127], v[132:135], v[148:151], v[124:127]
	v_mfma_f32_16x16x32_bf16 v[120:123], v[140:143], v[148:151], v[120:123]
	v_mfma_f32_16x16x32_bf16 v[108:111], v[132:135], v[156:159], v[108:111]
	v_mfma_f32_16x16x32_bf16 v[104:107], v[140:143], v[156:159], v[104:107]
	v_mfma_f32_16x16x32_bf16 v[92:95], v[132:135], v[164:167], v[92:95]
	v_mfma_f32_16x16x32_bf16 v[88:91], v[140:143], v[164:167], v[88:91]
	v_mfma_f32_16x16x32_bf16 v[76:79], v[132:135], v[172:175], v[76:79]
	v_mfma_f32_16x16x32_bf16 v[72:75], v[140:143], v[172:175], v[72:75]
	s_barrier
	s_setprio 0
	s_add_i32 s22, 0, 0x1c000
	s_add_i32 s23, s45, s30
	v_add_u32_e32 v204, s22, v212
	v_lshl_add_u64 v[208:209], v[208:209], 0, s[16:17]
	s_mov_b32 m0, s23
	ds_read_b128 v[192:195], v204
	ds_read_b128 v[196:199], v204 offset:1024
	ds_read_b128 v[200:203], v204 offset:2048
	ds_read_b128 v[204:207], v204 offset:3072
	global_load_lds_dwordx4 v[208:209], off
	v_lshl_add_u64 v[208:209], v[218:219], 0, s[16:17]
	s_add_i32 m0, s23, 0x2000
	s_nop 0
	global_load_lds_dwordx4 v[208:209], off
	s_barrier
	s_waitcnt lgkmcnt(0)
	s_setprio 1
	v_mfma_f32_16x16x32_bf16 v[116:119], v[192:195], v[144:147], v[116:119]
	v_mfma_f32_16x16x32_bf16 v[112:115], v[200:203], v[144:147], v[112:115]
	v_mfma_f32_16x16x32_bf16 v[100:103], v[192:195], v[152:155], v[100:103]
	v_mfma_f32_16x16x32_bf16 v[96:99], v[200:203], v[152:155], v[96:99]
	v_mfma_f32_16x16x32_bf16 v[84:87], v[192:195], v[160:163], v[84:87]
	v_mfma_f32_16x16x32_bf16 v[80:83], v[200:203], v[160:163], v[80:83]
	v_mfma_f32_16x16x32_bf16 v[68:71], v[192:195], v[168:171], v[68:71]
	v_mfma_f32_16x16x32_bf16 v[64:67], v[200:203], v[168:171], v[64:67]
	v_mfma_f32_16x16x32_bf16 v[116:119], v[196:199], v[148:151], v[116:119]
	v_mfma_f32_16x16x32_bf16 v[112:115], v[204:207], v[148:151], v[112:115]
	v_mfma_f32_16x16x32_bf16 v[100:103], v[196:199], v[156:159], v[100:103]
	v_mfma_f32_16x16x32_bf16 v[96:99], v[204:207], v[156:159], v[96:99]
	v_mfma_f32_16x16x32_bf16 v[84:87], v[196:199], v[164:167], v[84:87]
	v_mfma_f32_16x16x32_bf16 v[80:83], v[204:207], v[164:167], v[80:83]
	v_mfma_f32_16x16x32_bf16 v[68:71], v[196:199], v[172:175], v[68:71]
	v_mfma_f32_16x16x32_bf16 v[64:67], v[204:207], v[172:175], v[64:67]
	s_barrier
	s_setprio 0
	s_mov_b32 m0, s37
	v_lshl_add_u64 v[208:209], v[220:221], 0, s[16:17]
	ds_read_b128 v[144:147], v215 offset:49152
	ds_read_b128 v[148:151], v215 offset:50176
	ds_read_b128 v[152:155], v215 offset:51200
	ds_read_b128 v[156:159], v215 offset:52224
	ds_read_b128 v[160:163], v215 offset:53248
	ds_read_b128 v[164:167], v215 offset:54272
	ds_read_b128 v[168:171], v215 offset:55296
	ds_read_b128 v[172:175], v215 offset:56320
	global_load_lds_dwordx4 v[208:209], off
	v_lshl_add_u64 v[208:209], v[222:223], 0, s[16:17]
	s_mov_b32 m0, s38
	s_nop 0
	global_load_lds_dwordx4 v[208:209], off
	s_barrier
; #define PG8_STAGE(bufoff, gbase, voff) do { _Pragma("unroll") for (int _i = 0; _i < 2; ++_i) \
;     __builtin_amdgcn_global_load_lds((const unsigned*)((const char*)(gbase) + (voff)[_i]), (LAS unsigned*)(lds + (bufoff) + ldsw + _i * 8192), 16, 0, 0); } while (0)
; #define PG8_MMA(ai, bj, At, Bt) do { __builtin_amdgcn_s_setprio(1); _Pragma("unroll") for (int m = 0; m < 4; ++m) _Pragma("unroll") for (int n = 0; n < 2; ++n) _Pragma("unroll") for (int k = 0; k < 2; ++k) \
;     acc[ai][bj][m][n] = __builtin_amdgcn_mfma_f32_16x16x32_bf16(Bt[n][k], At[m][k], acc[ai][bj][m][n], 0, 0, 0); __builtin_amdgcn_s_setprio(0); } while (0)
; #define PG8_WAIT_V(n) asm volatile("s_waitcnt vmcnt(" #n ")" ::: "memory")
; #define PG8_WAIT_L(n) asm volatile("s_waitcnt lgkmcnt(" #n ")" ::: "memory")
; #define PG8_BAR __builtin_amdgcn_s_barrier()
; #define PG8_SCHED __builtin_amdgcn_sched_barrier(0)
; template <class Epi, class Sched = StaticOrder>
; DI void gemm_phase(LAS unsigned char* lds, const Gemm g, const Sched& S, const Epi& E) {
;     ...
;       PG8_BAR; PG8_WAIT_L(0); PG8_MMA(1, 0, At, B0); PG8_BAR; PG8_SCHED;
;       PG8_STAGE(PG8_SB(1, 1), b3 + hstep, voffB);
;       PG8_WAIT_V(6); PG8_BAR; PG8_MMA(1, 1, At, B1); PG8_BAR;
	s_waitcnt lgkmcnt(0)
	s_setprio 1
	v_mfma_f32_16x16x32_bf16 v[60:63], v[128:131], v[144:147], v[60:63]
	v_mfma_f32_16x16x32_bf16 v[56:59], v[136:139], v[144:147], v[56:59]
	v_mfma_f32_16x16x32_bf16 v[44:47], v[128:131], v[152:155], v[44:47]
	v_mfma_f32_16x16x32_bf16 v[40:43], v[136:139], v[152:155], v[40:43]
	v_mfma_f32_16x16x32_bf16 v[28:31], v[128:131], v[160:163], v[28:31]
	v_mfma_f32_16x16x32_bf16 v[24:27], v[136:139], v[160:163], v[24:27]
	v_mfma_f32_16x16x32_bf16 v[12:15], v[128:131], v[168:171], v[12:15]
	v_mfma_f32_16x16x32_bf16 v[8:11], v[136:139], v[168:171], v[8:11]
	v_mfma_f32_16x16x32_bf16 v[60:63], v[132:135], v[148:151], v[60:63]
	v_mfma_f32_16x16x32_bf16 v[56:59], v[140:143], v[148:151], v[56:59]
	v_mfma_f32_16x16x32_bf16 v[44:47], v[132:135], v[156:159], v[44:47]
	v_mfma_f32_16x16x32_bf16 v[40:43], v[140:143], v[156:159], v[40:43]
	v_mfma_f32_16x16x32_bf16 v[28:31], v[132:135], v[164:167], v[28:31]
	v_mfma_f32_16x16x32_bf16 v[24:27], v[140:143], v[164:167], v[24:27]
	v_mfma_f32_16x16x32_bf16 v[12:15], v[132:135], v[172:175], v[12:15]
	v_mfma_f32_16x16x32_bf16 v[8:11], v[140:143], v[172:175], v[8:11]
	s_barrier
	s_setprio 0
	s_add_u32 s20, s20, 0x160080
	s_addc_u32 s21, s21, 0
	s_add_i32 s22, s22, s30
	v_lshl_add_u64 v[128:129], s[20:21], 0, v[178:179]
	s_mov_b32 m0, s22
	s_nop 0
	global_load_lds_dwordx4 v[128:129], off
	v_lshl_add_u64 v[128:129], s[20:21], 0, v[182:183]
	s_add_i32 m0, s22, 0x2000
	s_nop 0
	global_load_lds_dwordx4 v[128:129], off
	s_waitcnt vmcnt(6)
	s_barrier
	s_setprio 1
	v_mfma_f32_16x16x32_bf16 v[52:55], v[192:195], v[144:147], v[52:55]
	v_mfma_f32_16x16x32_bf16 v[48:51], v[200:203], v[144:147], v[48:51]
	v_mfma_f32_16x16x32_bf16 v[36:39], v[192:195], v[152:155], v[36:39]
	v_mfma_f32_16x16x32_bf16 v[32:35], v[200:203], v[152:155], v[32:35]
	v_mfma_f32_16x16x32_bf16 v[20:23], v[192:195], v[160:163], v[20:23]
	v_mfma_f32_16x16x32_bf16 v[16:19], v[200:203], v[160:163], v[16:19]
	v_mfma_f32_16x16x32_bf16 v[4:7], v[192:195], v[168:171], v[4:7]
	v_mfma_f32_16x16x32_bf16 v[0:3], v[200:203], v[168:171], v[0:3]
	v_mfma_f32_16x16x32_bf16 v[52:55], v[196:199], v[148:151], v[52:55]
	v_mfma_f32_16x16x32_bf16 v[48:51], v[204:207], v[148:151], v[48:51]
	v_mfma_f32_16x16x32_bf16 v[36:39], v[196:199], v[156:159], v[36:39]
	v_mfma_f32_16x16x32_bf16 v[32:35], v[204:207], v[156:159], v[32:35]
	v_mfma_f32_16x16x32_bf16 v[20:23], v[196:199], v[164:167], v[20:23]
	v_mfma_f32_16x16x32_bf16 v[16:19], v[204:207], v[164:167], v[16:19]
	v_mfma_f32_16x16x32_bf16 v[4:7], v[196:199], v[172:175], v[4:7]
	v_mfma_f32_16x16x32_bf16 v[0:3], v[204:207], v[172:175], v[0:3]
	s_add_i32 s44, s44, 2
	s_add_u32 s18, s18, 0x100
	s_addc_u32 s19, s19, 0
	s_add_u32 s42, s42, 0x100
	s_addc_u32 s43, s43, 0
	s_cmpk_gt_u32 s44, 0x55
	s_barrier
	s_setprio 0
	s_cbranch_scc0 .LBB0_961
; DI unsigned pack2(float lo, float hi) { f32x2 v = {lo, hi}; bf16v2 r = __builtin_convertvector(v, bf16v2); return __builtin_bit_cast(unsigned, r); }
;   DI void operator()(const f32x4 (&acc)[2][2][4][2], const Unit& u, int wr, int wc, int fr, int fq) const {
;     const int row0 = u.pm * BM + wr * 64 + fr, col0 = u.pn * BM + wc * 32 + 8 * fq;
; #pragma unroll
;     for (int ai = 0; ai < 2; ++ai) {
;       f32x4 bv[4][2][2];
; #pragma unroll
;       for (int m = 0; m < 4; ++m)
; #pragma unroll
;         for (int bj = 0; bj < 2; ++bj) {
;           const float* bp = base + (size_t)(row0 + ai * HALF + m * 16) * 2048 + col0 + bj * HALF;
;           bv[m][bj][0] = *(const f32x4*)bp; bv[m][bj][1] = *(const f32x4*)(bp + 4);
;         }
; #pragma unroll
;       for (int m = 0; m < 4; ++m) {
;         const int row = row0 + ai * HALF + m * 16;
;         const size_t off = (size_t)row * 2048 + col0;
;         float ss = 0.f;
; #pragma unroll
;         for (int bj = 0; bj < 2; ++bj) {
;           const f32x4 v0 = acc[ai][bj][m][0] + bv[m][bj][0], v1 = acc[ai][bj][m][1] + bv[m][bj][1];
;           *(f32x4*)(C + off + bj * HALF) = v0; *(f32x4*)(C + off + bj * HALF + 4) = v1;
;           if (xb) {
;             u32x4 w; w.x = pack2(v0[0], v0[1]); w.y = pack2(v0[2], v0[3]); w.z = pack2(v1[0], v1[1]); w.w = pack2(v1[2], v1[3]);
;             *(u32x4*)(xb + off + bj * HALF) = w;
;             ss += v0[0] * v0[0] + v0[1] * v0[1] + v0[2] * v0[2] + v0[3] * v0[3] + v1[0] * v1[0] + v1[1] * v1[1] + v1[2] * v1[2] + v1[3] * v1[3];
;           }
;         }
;         if (xb) {
;           ss += __shfl_xor(ss, 16); ss += __shfl_xor(ss, 32);
;           if (fq == 0) ssq[(size_t)row * 32 + u.pn * 4 + wc] = ss;
;         }
	v_lshl_add_u32 v194, s51, 8, v211
	v_lshl_or_b32 v192, s2, 8, v213
	v_readlane_b32 s52, v243, 3
	v_ashrrev_i32_e32 v193, 31, v192
	v_readlane_b32 s66, v243, 17
	v_readlane_b32 s67, v243, 18
	v_ashrrev_i32_e32 v195, 31, v194
	v_lshlrev_b64 v[128:129], 13, v[194:195]
	v_lshl_add_u64 v[196:197], v[192:193], 2, s[66:67]
	v_lshl_add_u64 v[236:237], v[196:197], 0, v[128:129]
	global_load_dwordx4 v[220:223], v[236:237], off
	global_load_dwordx4 v[224:227], v[236:237], off offset:16
	global_load_dwordx4 v[228:231], v[236:237], off offset:512
	global_load_dwordx4 v[232:235], v[236:237], off offset:528
	v_or_b32_e32 v206, 16, v194
	v_or_b32_e32 v202, 32, v194
	v_or_b32_e32 v198, 48, v194
	v_ashrrev_i32_e32 v207, 31, v206
	v_ashrrev_i32_e32 v203, 31, v202
	v_ashrrev_i32_e32 v199, 31, v198
	v_lshlrev_b64 v[128:129], 13, v[206:207]
	v_lshlrev_b64 v[130:131], 13, v[202:203]
	v_lshlrev_b64 v[132:133], 13, v[198:199]
	v_lshl_add_u64 v[208:209], v[196:197], 0, v[128:129]
	v_lshl_add_u64 v[204:205], v[196:197], 0, v[130:131]
	v_lshl_add_u64 v[200:201], v[196:197], 0, v[132:133]
	global_load_dwordx4 v[168:171], v[208:209], off offset:16
	global_load_dwordx4 v[172:175], v[208:209], off
	global_load_dwordx4 v[160:163], v[208:209], off offset:528
	global_load_dwordx4 v[164:167], v[208:209], off offset:512
	global_load_dwordx4 v[152:155], v[204:205], off offset:16
	global_load_dwordx4 v[156:159], v[204:205], off
	global_load_dwordx4 v[144:147], v[204:205], off offset:528
	global_load_dwordx4 v[148:151], v[204:205], off offset:512
	global_load_dwordx4 v[136:139], v[200:201], off offset:16
	global_load_dwordx4 v[140:143], v[200:201], off
	global_load_dwordx4 v[128:131], v[200:201], off offset:528
	global_load_dwordx4 v[132:135], v[200:201], off offset:512
	v_and_b32_e32 v218, 64, v217
	v_xor_b32_e32 v238, 16, v217
	v_add_u32_e32 v240, 64, v218
	v_xor_b32_e32 v239, 32, v217
	v_cmp_lt_i32_e32 vcc, v238, v240
	v_lshlrev_b64 v[218:219], 11, v[194:195]
	s_lshl_b32 s18, s2, 2
	v_cndmask_b32_e32 v241, v217, v238, vcc
	v_cmp_lt_i32_e32 vcc, v239, v240
	s_ashr_i32 s19, s18, 31
	v_readlane_b32 s53, v243, 4
	v_cndmask_b32_e32 v240, v217, v239, vcc
	v_lshl_add_u64 v[238:239], v[218:219], 0, v[192:193]
	v_lshlrev_b32_e32 v218, 2, v241
	v_lshl_add_u64 v[238:239], v[238:239], 1, s[12:13]
	v_readlane_b32 s54, v243, 5
	v_readlane_b32 s55, v243, 6
	v_readlane_b32 s56, v243, 7
	v_readlane_b32 s57, v243, 8
	v_readlane_b32 s58, v243, 9
	v_readlane_b32 s59, v243, 10
	v_readlane_b32 s60, v243, 11
	v_readlane_b32 s61, v243, 12
	v_readlane_b32 s62, v243, 13
	v_readlane_b32 s63, v243, 14
	v_readlane_b32 s64, v243, 15
	v_readlane_b32 s65, v243, 16
	s_waitcnt vmcnt(0)
	v_pk_add_f32 v[126:127], v[126:127], v[222:223]
	v_pk_add_f32 v[124:125], v[124:125], v[220:221]
	v_pk_add_f32 v[116:117], v[116:117], v[228:229]
	v_pk_add_f32 v[122:123], v[122:123], v[226:227]
	v_pk_add_f32 v[120:121], v[120:121], v[224:225]
	v_pk_add_f32 v[220:221], v[112:113], v[232:233]
	global_store_dwordx4 v[236:237], v[124:127], off
	global_store_dwordx4 v[236:237], v[120:123], off offset:16
	v_cvt_pk_bf16_f32 v112, v124, v125
	v_mul_f32_e32 v125, v125, v125
	v_mul_f32_e32 v219, v117, v117
	v_pk_add_f32 v[118:119], v[118:119], v[230:231]
	v_fmac_f32_e32 v125, v124, v124
	v_fmac_f32_e32 v219, v116, v116
	v_fmac_f32_e32 v125, v126, v126
	v_fmac_f32_e32 v219, v118, v118
	v_fmac_f32_e32 v125, v127, v127
	v_fmac_f32_e32 v219, v119, v119
	v_fmac_f32_e32 v125, v120, v120
	v_fmac_f32_e32 v219, v220, v220
	v_pk_add_f32 v[222:223], v[114:115], v[234:235]
	v_fmac_f32_e32 v125, v121, v121
	v_fmac_f32_e32 v219, v221, v221
	v_fmac_f32_e32 v125, v122, v122
	v_fmac_f32_e32 v219, v222, v222
	v_fmac_f32_e32 v125, v123, v123
	v_fmac_f32_e32 v219, v223, v223
	v_cvt_pk_bf16_f32 v114, v120, v121
	v_add_f32_e32 v121, v125, v219
	v_cvt_pk_bf16_f32 v115, v122, v123
	ds_bpermute_b32 v122, v218, v121
	v_cvt_pk_bf16_f32 v113, v126, v127
	global_store_dwordx4 v[238:239], v[112:115], off
	global_store_dwordx4 v[236:237], v[116:119], off offset:512
	global_store_dwordx4 v[236:237], v[220:223], off offset:528
	v_lshlrev_b32_e32 v126, 2, v240
	v_cvt_pk_bf16_f32 v120, v116, v117
	s_waitcnt lgkmcnt(0)
	v_add_f32_e32 v112, v121, v122
	ds_bpermute_b32 v113, v126, v112
	v_cvt_pk_bf16_f32 v121, v118, v119
	v_cvt_pk_bf16_f32 v122, v220, v221
	v_cvt_pk_bf16_f32 v123, v222, v223
	global_store_dwordx4 v[238:239], v[120:123], off offset:256
	s_and_saveexec_b64 s[20:21], s[0:1]
	s_cbranch_execz .LBB0_964
	s_waitcnt lgkmcnt(0)
	v_add_f32_e32 v114, v112, v113
	v_lshlrev_b64 v[112:113], 7, v[194:195]
	v_lshl_add_u64 v[112:113], s[14:15], 0, v[112:113]
	v_lshl_add_u64 v[112:113], s[18:19], 2, v[112:113]
	s_lshl_b32 s2, s36, 2
	v_lshl_add_u64 v[112:113], v[112:113], 0, s[2:3]
	global_store_dword v[112:113], v114, off

; #define PG8_STAGE(bufoff, gbase, voff) do { _Pragma("unroll") for (int _i = 0; _i < 2; ++_i) \
;     __builtin_amdgcn_global_load_lds((const unsigned*)((const char*)(gbase) + (voff)[_i]), (LAS unsigned*)(lds + (bufoff) + ldsw + _i * 8192), 16, 0, 0); } while (0)
; #define PG8_LDA(dst, b, h) do { _Pragma("unroll") for (int m = 0; m < 4; ++m) _Pragma("unroll") for (int k = 0; k < 2; ++k) dst[m][k] = *(const LAS bf16x8*)(lds + PG8_SA(b, h) + aoff + m * 2048 + k * 1024); } while (0)
; #define PG8_LDB(dst, b, h) do { _Pragma("unroll") for (int n = 0; n < 2; ++n) _Pragma("unroll") for (int k = 0; k < 2; ++k) dst[n][k] = *(const LAS bf16x8*)(lds + PG8_SB(b, h) + boff + n * 2048 + k * 1024); } while (0)
; #define PG8_MMA(ai, bj, At, Bt) do { __builtin_amdgcn_s_setprio(1); _Pragma("unroll") for (int m = 0; m < 4; ++m) _Pragma("unroll") for (int n = 0; n < 2; ++n) _Pragma("unroll") for (int k = 0; k < 2; ++k) \
;     acc[ai][bj][m][n] = __builtin_amdgcn_mfma_f32_16x16x32_bf16(Bt[n][k], At[m][k], acc[ai][bj][m][n], 0, 0, 0); __builtin_amdgcn_s_setprio(0); } while (0)
; #define PG8_WAIT_V(n) asm volatile("s_waitcnt vmcnt(" #n ")" ::: "memory")
; #define PG8_WAIT_L(n) asm volatile("s_waitcnt lgkmcnt(" #n ")" ::: "memory")
; #define PG8_BAR __builtin_amdgcn_s_barrier()
; #define PG8_SCHED __builtin_amdgcn_sched_barrier(0)
; template <class Epi, class Sched = StaticOrder>
; DI void gemm_phase(LAS unsigned char* lds, const Gemm g, const Sched& S, const Epi& E) {
;     ...
;     for (int t = 0; t < nt; t += 2) {
;       const bool last = (t == nt - 2);
;       const char* a1 = cA + (size_t)(t + 1) * kstep;
;       const char* a2 = last ? nA : cA + (size_t)(t + 2) * kstep; const char* b2 = last ? nB : cB + (size_t)(t + 2) * kstep;
;       const char* a3 = a2 + kstep; const char* b3 = b2 + kstep;
;       PG8_LDB(B0, 0, 0); PG8_SCHED; PG8_LDA(At, 0, 0); PG8_STAGE(PG8_SA(1, 1), a1 + hstep, voffA);
;       PG8_WAIT_L(8); PG8_BAR; PG8_WAIT_L(0); PG8_MMA(0, 0, At, B0); PG8_BAR; PG8_SCHED;
;       PG8_LDB(B1, 0, 1); PG8_STAGE(PG8_SB(0, 0), b2, voffB);
;       PG8_BAR; PG8_WAIT_L(0); PG8_MMA(0, 1, At, B1); PG8_BAR;
;       PG8_LDA(At, 0, 1); PG8_STAGE(PG8_SA(0, 0), a2, voffA);
;       PG8_BAR; PG8_WAIT_L(0); PG8_MMA(1, 0, At, B0); PG8_BAR; PG8_SCHED;
;       PG8_STAGE(PG8_SB(0, 1), b2 + hstep, voffB);
;       PG8_WAIT_V(6); PG8_BAR; PG8_MMA(1, 1, At, B1); PG8_BAR;
.LBB0_1052:
	ds_read_b128 v[128:131], v203
	ds_read_b128 v[132:135], v203 offset:1024
	ds_read_b128 v[136:139], v203 offset:2048
	ds_read_b128 v[140:143], v203 offset:3072
	s_add_u32 s12, s10, 0xfff80080
	s_addc_u32 s13, s11, -1
	s_cmp_eq_u32 s52, 28
	s_cselect_b32 s65, s41, s13
	s_cselect_b32 s64, s42, s12
	s_cselect_b32 s13, s43, s49
	s_cselect_b32 s12, s44, s45
	v_lshl_add_u64 v[194:195], s[10:11], 0, v[172:173]
	s_add_i32 m0, s61, 0xc000
	ds_read_b128 v[144:147], v204
	ds_read_b128 v[148:151], v204 offset:1024
	ds_read_b128 v[152:155], v204 offset:2048
	ds_read_b128 v[156:159], v204 offset:3072
	ds_read_b128 v[178:181], v204 offset:4096
	ds_read_b128 v[182:185], v204 offset:5120
	ds_read_b128 v[186:189], v204 offset:6144
	ds_read_b128 v[190:193], v204 offset:7168
	global_load_lds_dwordx4 v[194:195], off
	v_lshl_add_u64 v[194:195], s[10:11], 0, v[174:175]
	s_add_i32 m0, s61, 0xe000
	s_nop 0
	global_load_lds_dwordx4 v[194:195], off
	s_waitcnt lgkmcnt(8)
	s_barrier
	s_waitcnt lgkmcnt(0)
	s_setprio 1
	v_mfma_f32_16x16x32_bf16 v[124:127], v[128:131], v[144:147], v[124:127]
	v_mfma_f32_16x16x32_bf16 v[120:123], v[136:139], v[144:147], v[120:123]
	v_mfma_f32_16x16x32_bf16 v[116:119], v[128:131], v[152:155], v[116:119]
	v_mfma_f32_16x16x32_bf16 v[104:107], v[136:139], v[152:155], v[104:107]
	v_mfma_f32_16x16x32_bf16 v[92:95], v[128:131], v[178:181], v[92:95]
	v_mfma_f32_16x16x32_bf16 v[88:91], v[136:139], v[178:181], v[88:91]
	v_mfma_f32_16x16x32_bf16 v[84:87], v[128:131], v[186:189], v[84:87]
	v_mfma_f32_16x16x32_bf16 v[72:75], v[136:139], v[186:189], v[72:75]
	v_mfma_f32_16x16x32_bf16 v[124:127], v[132:135], v[148:151], v[124:127]
	v_mfma_f32_16x16x32_bf16 v[120:123], v[140:143], v[148:151], v[120:123]
	v_mfma_f32_16x16x32_bf16 v[116:119], v[132:135], v[156:159], v[116:119]
	v_mfma_f32_16x16x32_bf16 v[104:107], v[140:143], v[156:159], v[104:107]
	v_mfma_f32_16x16x32_bf16 v[92:95], v[132:135], v[182:185], v[92:95]
	v_mfma_f32_16x16x32_bf16 v[88:91], v[140:143], v[182:185], v[88:91]
	v_mfma_f32_16x16x32_bf16 v[84:87], v[132:135], v[190:193], v[84:87]
	v_mfma_f32_16x16x32_bf16 v[72:75], v[140:143], v[190:193], v[72:75]
	s_barrier
	s_setprio 0
	s_add_i32 s53, s80, s70
	v_lshl_add_u64 v[208:209], s[12:13], 0, v[162:163]
	s_mov_b32 m0, s53
	ds_read_b128 v[194:197], v205
	ds_read_b128 v[212:215], v205 offset:1024
	ds_read_b128 v[216:219], v205 offset:2048
	ds_read_b128 v[220:223], v205 offset:3072
	global_load_lds_dwordx4 v[208:209], off
	v_lshl_add_u64 v[224:225], s[12:13], 0, v[166:167]
	s_add_i32 m0, s53, 0x2000
	s_nop 0
	global_load_lds_dwordx4 v[224:225], off
	s_barrier
	s_waitcnt lgkmcnt(0)
	s_setprio 1
	v_mfma_f32_16x16x32_bf16 v[112:115], v[194:197], v[144:147], v[112:115]
	v_mfma_f32_16x16x32_bf16 v[108:111], v[216:219], v[144:147], v[108:111]
	v_mfma_f32_16x16x32_bf16 v[100:103], v[194:197], v[152:155], v[100:103]
	v_mfma_f32_16x16x32_bf16 v[96:99], v[216:219], v[152:155], v[96:99]
	v_mfma_f32_16x16x32_bf16 v[80:83], v[194:197], v[178:181], v[80:83]
	v_mfma_f32_16x16x32_bf16 v[76:79], v[216:219], v[178:181], v[76:79]
	v_mfma_f32_16x16x32_bf16 v[68:71], v[194:197], v[186:189], v[68:71]
	v_mfma_f32_16x16x32_bf16 v[64:67], v[216:219], v[186:189], v[64:67]
	v_mfma_f32_16x16x32_bf16 v[112:115], v[212:215], v[148:151], v[112:115]
	v_mfma_f32_16x16x32_bf16 v[108:111], v[220:223], v[148:151], v[108:111]
	v_mfma_f32_16x16x32_bf16 v[100:103], v[212:215], v[156:159], v[100:103]
	v_mfma_f32_16x16x32_bf16 v[96:99], v[220:223], v[156:159], v[96:99]
	v_mfma_f32_16x16x32_bf16 v[80:83], v[212:215], v[182:185], v[80:83]
	v_mfma_f32_16x16x32_bf16 v[76:79], v[220:223], v[182:185], v[76:79]
	v_mfma_f32_16x16x32_bf16 v[68:71], v[212:215], v[190:193], v[68:71]
	v_mfma_f32_16x16x32_bf16 v[64:67], v[220:223], v[190:193], v[64:67]
	s_barrier
	s_setprio 0
	s_mov_b32 m0, s61
	v_lshl_add_u64 v[226:227], s[64:65], 0, v[160:161]
	ds_read_b128 v[144:147], v204 offset:16384
	ds_read_b128 v[148:151], v204 offset:17408
	ds_read_b128 v[152:155], v204 offset:18432
	ds_read_b128 v[156:159], v204 offset:19456
	ds_read_b128 v[178:181], v204 offset:20480
	ds_read_b128 v[182:185], v204 offset:21504
	ds_read_b128 v[186:189], v204 offset:22528
	ds_read_b128 v[190:193], v204 offset:23552
	global_load_lds_dwordx4 v[226:227], off
	v_lshl_add_u64 v[228:229], s[64:65], 0, v[164:165]
	s_mov_b32 m0, s63
	s_nop 0
	global_load_lds_dwordx4 v[228:229], off
	s_barrier
	s_waitcnt lgkmcnt(0)
	s_setprio 1
	v_mfma_f32_16x16x32_bf16 v[60:63], v[128:131], v[144:147], v[60:63]
	v_mfma_f32_16x16x32_bf16 v[56:59], v[136:139], v[144:147], v[56:59]
	v_mfma_f32_16x16x32_bf16 v[48:51], v[128:131], v[152:155], v[48:51]
	v_mfma_f32_16x16x32_bf16 v[40:43], v[136:139], v[152:155], v[40:43]
	v_mfma_f32_16x16x32_bf16 v[28:31], v[128:131], v[178:181], v[28:31]
	v_mfma_f32_16x16x32_bf16 v[24:27], v[136:139], v[178:181], v[24:27]
	v_mfma_f32_16x16x32_bf16 v[12:15], v[128:131], v[186:189], v[12:15]
	v_mfma_f32_16x16x32_bf16 v[8:11], v[136:139], v[186:189], v[8:11]
	v_mfma_f32_16x16x32_bf16 v[60:63], v[132:135], v[148:151], v[60:63]
	v_mfma_f32_16x16x32_bf16 v[56:59], v[140:143], v[148:151], v[56:59]
	v_mfma_f32_16x16x32_bf16 v[48:51], v[132:135], v[156:159], v[48:51]
	v_mfma_f32_16x16x32_bf16 v[40:43], v[140:143], v[156:159], v[40:43]
	v_mfma_f32_16x16x32_bf16 v[28:31], v[132:135], v[182:185], v[28:31]
	v_mfma_f32_16x16x32_bf16 v[24:27], v[140:143], v[182:185], v[24:27]
	v_mfma_f32_16x16x32_bf16 v[12:15], v[132:135], v[190:193], v[12:15]
	v_mfma_f32_16x16x32_bf16 v[8:11], v[140:143], v[190:193], v[8:11]
	s_barrier
; #define PG8_STAGE(bufoff, gbase, voff) do { _Pragma("unroll") for (int _i = 0; _i < 2; ++_i) \
;     __builtin_amdgcn_global_load_lds((const unsigned*)((const char*)(gbase) + (voff)[_i]), (LAS unsigned*)(lds + (bufoff) + ldsw + _i * 8192), 16, 0, 0); } while (0)
; #define PG8_LDA(dst, b, h) do { _Pragma("unroll") for (int m = 0; m < 4; ++m) _Pragma("unroll") for (int k = 0; k < 2; ++k) dst[m][k] = *(const LAS bf16x8*)(lds + PG8_SA(b, h) + aoff + m * 2048 + k * 1024); } while (0)
; #define PG8_LDB(dst, b, h) do { _Pragma("unroll") for (int n = 0; n < 2; ++n) _Pragma("unroll") for (int k = 0; k < 2; ++k) dst[n][k] = *(const LAS bf16x8*)(lds + PG8_SB(b, h) + boff + n * 2048 + k * 1024); } while (0)
; #define PG8_MMA(ai, bj, At, Bt) do { __builtin_amdgcn_s_setprio(1); _Pragma("unroll") for (int m = 0; m < 4; ++m) _Pragma("unroll") for (int n = 0; n < 2; ++n) _Pragma("unroll") for (int k = 0; k < 2; ++k) \
;     acc[ai][bj][m][n] = __builtin_amdgcn_mfma_f32_16x16x32_bf16(Bt[n][k], At[m][k], acc[ai][bj][m][n], 0, 0, 0); __builtin_amdgcn_s_setprio(0); } while (0)
; #define PG8_WAIT_V(n) asm volatile("s_waitcnt vmcnt(" #n ")" ::: "memory")
; #define PG8_WAIT_L(n) asm volatile("s_waitcnt lgkmcnt(" #n ")" ::: "memory")
; #define PG8_BAR __builtin_amdgcn_s_barrier()
; #define PG8_SCHED __builtin_amdgcn_sched_barrier(0)
; template <class Epi, class Sched = StaticOrder>
; DI void gemm_phase(LAS unsigned char* lds, const Gemm g, const Sched& S, const Epi& E) {
;     ...
;       PG8_STAGE(PG8_SB(0, 1), b2 + hstep, voffB);
;       PG8_WAIT_V(6); PG8_BAR; PG8_MMA(1, 1, At, B1); PG8_BAR;
;       PG8_LDB(B0, 1, 0); PG8_SCHED; PG8_LDA(At, 1, 0); PG8_STAGE(PG8_SA(0, 1), a2 + hstep, voffA);
;       PG8_WAIT_L(8); PG8_BAR; PG8_WAIT_L(0); PG8_MMA(0, 0, At, B0); PG8_BAR; PG8_SCHED;
;       PG8_LDB(B1, 1, 1); PG8_STAGE(PG8_SB(1, 0), b3, voffB);
;       PG8_BAR; PG8_WAIT_L(0); PG8_MMA(0, 1, At, B1); PG8_BAR;
;       PG8_LDA(At, 1, 1); PG8_STAGE(PG8_SA(1, 0), a3, voffA);
;       PG8_BAR; PG8_WAIT_L(0); PG8_MMA(1, 0, At, B0); PG8_BAR; PG8_SCHED;
	s_setprio 0
	s_add_u32 s54, s12, 0x80000
	s_addc_u32 s55, s13, 0
	s_add_i32 s53, s81, s70
	v_lshl_add_u64 v[128:129], s[54:55], 0, v[162:163]
	s_mov_b32 m0, s53
	s_nop 0
	global_load_lds_dwordx4 v[128:129], off
	v_lshl_add_u64 v[128:129], s[54:55], 0, v[166:167]
	s_add_i32 m0, s53, 0x2000
	s_nop 0
	global_load_lds_dwordx4 v[128:129], off
	s_waitcnt vmcnt(6)
	s_barrier
	s_setprio 1
	v_mfma_f32_16x16x32_bf16 v[52:55], v[194:197], v[144:147], v[52:55]
	v_mfma_f32_16x16x32_bf16 v[44:47], v[216:219], v[144:147], v[44:47]
	v_mfma_f32_16x16x32_bf16 v[36:39], v[194:197], v[152:155], v[36:39]
	v_mfma_f32_16x16x32_bf16 v[32:35], v[216:219], v[152:155], v[32:35]
	v_mfma_f32_16x16x32_bf16 v[20:23], v[194:197], v[178:181], v[20:23]
	v_mfma_f32_16x16x32_bf16 v[16:19], v[216:219], v[178:181], v[16:19]
	v_mfma_f32_16x16x32_bf16 v[4:7], v[194:197], v[186:189], v[4:7]
	v_mfma_f32_16x16x32_bf16 v[0:3], v[216:219], v[186:189], v[0:3]
	v_mfma_f32_16x16x32_bf16 v[52:55], v[212:215], v[148:151], v[52:55]
	v_mfma_f32_16x16x32_bf16 v[44:47], v[220:223], v[148:151], v[44:47]
	v_mfma_f32_16x16x32_bf16 v[36:39], v[212:215], v[156:159], v[36:39]
	v_mfma_f32_16x16x32_bf16 v[32:35], v[220:223], v[156:159], v[32:35]
	v_mfma_f32_16x16x32_bf16 v[20:23], v[212:215], v[182:185], v[20:23]
	v_mfma_f32_16x16x32_bf16 v[16:19], v[220:223], v[182:185], v[16:19]
	v_mfma_f32_16x16x32_bf16 v[4:7], v[212:215], v[190:193], v[4:7]
	v_mfma_f32_16x16x32_bf16 v[0:3], v[220:223], v[190:193], v[0:3]
	s_barrier
	s_setprio 0
	s_add_i32 s53, 0, 0x18000
	v_add_u32_e32 v140, s53, v199
	ds_read_b128 v[128:131], v140
	ds_read_b128 v[132:135], v140 offset:1024
	ds_read_b128 v[136:139], v140 offset:2048
	ds_read_b128 v[140:143], v140 offset:3072
	s_add_u32 s54, s64, 0x80000
	s_addc_u32 s55, s65, 0
	s_mov_b32 m0, s71
	v_lshl_add_u64 v[194:195], s[54:55], 0, v[160:161]
	ds_read_b128 v[144:147], v204 offset:32768
	ds_read_b128 v[148:151], v204 offset:33792
	ds_read_b128 v[152:155], v204 offset:34816
	ds_read_b128 v[156:159], v204 offset:35840
	ds_read_b128 v[178:181], v204 offset:36864
	ds_read_b128 v[182:185], v204 offset:37888
	ds_read_b128 v[186:189], v204 offset:38912
	ds_read_b128 v[190:193], v204 offset:39936
	global_load_lds_dwordx4 v[194:195], off
	v_lshl_add_u64 v[194:195], s[54:55], 0, v[164:165]
	s_mov_b32 m0, s72
	s_nop 0
	global_load_lds_dwordx4 v[194:195], off
	s_waitcnt lgkmcnt(8)
	s_barrier
	s_waitcnt lgkmcnt(0)
	s_setprio 1
	v_mfma_f32_16x16x32_bf16 v[124:127], v[128:131], v[144:147], v[124:127]
	v_mfma_f32_16x16x32_bf16 v[120:123], v[136:139], v[144:147], v[120:123]
	v_mfma_f32_16x16x32_bf16 v[116:119], v[128:131], v[152:155], v[116:119]
	v_mfma_f32_16x16x32_bf16 v[104:107], v[136:139], v[152:155], v[104:107]
	v_mfma_f32_16x16x32_bf16 v[92:95], v[128:131], v[178:181], v[92:95]
	v_mfma_f32_16x16x32_bf16 v[88:91], v[136:139], v[178:181], v[88:91]
	v_mfma_f32_16x16x32_bf16 v[84:87], v[128:131], v[186:189], v[84:87]
	v_mfma_f32_16x16x32_bf16 v[72:75], v[136:139], v[186:189], v[72:75]
	v_mfma_f32_16x16x32_bf16 v[124:127], v[132:135], v[148:151], v[124:127]
	v_mfma_f32_16x16x32_bf16 v[120:123], v[140:143], v[148:151], v[120:123]
	v_mfma_f32_16x16x32_bf16 v[116:119], v[132:135], v[156:159], v[116:119]
	v_mfma_f32_16x16x32_bf16 v[104:107], v[140:143], v[156:159], v[104:107]
	v_mfma_f32_16x16x32_bf16 v[92:95], v[132:135], v[182:185], v[92:95]
	v_mfma_f32_16x16x32_bf16 v[88:91], v[140:143], v[182:185], v[88:91]
	v_mfma_f32_16x16x32_bf16 v[84:87], v[132:135], v[190:193], v[84:87]
	v_mfma_f32_16x16x32_bf16 v[72:75], v[140:143], v[190:193], v[72:75]
	s_barrier
	s_setprio 0
	s_add_i32 s54, 0, 0x1c000
	s_add_i32 s53, s53, s70
	v_add_u32_e32 v168, s54, v199
	v_lshl_add_u64 v[208:209], v[208:209], 0, s[24:25]
	s_mov_b32 m0, s53
	ds_read_b128 v[194:197], v168
	ds_read_b128 v[212:215], v168 offset:1024
	ds_read_b128 v[216:219], v168 offset:2048
	ds_read_b128 v[220:223], v168 offset:3072
	global_load_lds_dwordx4 v[208:209], off
	v_lshl_add_u64 v[208:209], v[224:225], 0, s[24:25]
	s_add_i32 m0, s53, 0x2000
	s_nop 0
	global_load_lds_dwordx4 v[208:209], off
	s_barrier
	s_waitcnt lgkmcnt(0)
	s_setprio 1
	v_mfma_f32_16x16x32_bf16 v[112:115], v[194:197], v[144:147], v[112:115]
	v_mfma_f32_16x16x32_bf16 v[108:111], v[216:219], v[144:147], v[108:111]
	v_mfma_f32_16x16x32_bf16 v[100:103], v[194:197], v[152:155], v[100:103]
	v_mfma_f32_16x16x32_bf16 v[96:99], v[216:219], v[152:155], v[96:99]
	v_mfma_f32_16x16x32_bf16 v[80:83], v[194:197], v[178:181], v[80:83]
	v_mfma_f32_16x16x32_bf16 v[76:79], v[216:219], v[178:181], v[76:79]
	v_mfma_f32_16x16x32_bf16 v[68:71], v[194:197], v[186:189], v[68:71]
	v_mfma_f32_16x16x32_bf16 v[64:67], v[216:219], v[186:189], v[64:67]
	v_mfma_f32_16x16x32_bf16 v[112:115], v[212:215], v[148:151], v[112:115]
	v_mfma_f32_16x16x32_bf16 v[108:111], v[220:223], v[148:151], v[108:111]
	v_mfma_f32_16x16x32_bf16 v[100:103], v[212:215], v[156:159], v[100:103]
	v_mfma_f32_16x16x32_bf16 v[96:99], v[220:223], v[156:159], v[96:99]
	v_mfma_f32_16x16x32_bf16 v[80:83], v[212:215], v[182:185], v[80:83]
	v_mfma_f32_16x16x32_bf16 v[76:79], v[220:223], v[182:185], v[76:79]
	v_mfma_f32_16x16x32_bf16 v[68:71], v[212:215], v[190:193], v[68:71]
	v_mfma_f32_16x16x32_bf16 v[64:67], v[220:223], v[190:193], v[64:67]
	s_barrier
	s_setprio 0
	s_mov_b32 m0, s76
	v_lshl_add_u64 v[208:209], v[226:227], 0, s[24:25]
	ds_read_b128 v[144:147], v204 offset:49152
	ds_read_b128 v[148:151], v204 offset:50176
	ds_read_b128 v[152:155], v204 offset:51200
	ds_read_b128 v[156:159], v204 offset:52224
	ds_read_b128 v[178:181], v204 offset:53248
	ds_read_b128 v[182:185], v204 offset:54272
	ds_read_b128 v[186:189], v204 offset:55296
	ds_read_b128 v[190:193], v204 offset:56320
	global_load_lds_dwordx4 v[208:209], off
	v_lshl_add_u64 v[208:209], v[228:229], 0, s[24:25]
	s_mov_b32 m0, s77
	s_nop 0
	global_load_lds_dwordx4 v[208:209], off
	s_barrier
; #define PG8_STAGE(bufoff, gbase, voff) do { _Pragma("unroll") for (int _i = 0; _i < 2; ++_i) \
;     __builtin_amdgcn_global_load_lds((const unsigned*)((const char*)(gbase) + (voff)[_i]), (LAS unsigned*)(lds + (bufoff) + ldsw + _i * 8192), 16, 0, 0); } while (0)
; #define PG8_MMA(ai, bj, At, Bt) do { __builtin_amdgcn_s_setprio(1); _Pragma("unroll") for (int m = 0; m < 4; ++m) _Pragma("unroll") for (int n = 0; n < 2; ++n) _Pragma("unroll") for (int k = 0; k < 2; ++k) \
;     acc[ai][bj][m][n] = __builtin_amdgcn_mfma_f32_16x16x32_bf16(Bt[n][k], At[m][k], acc[ai][bj][m][n], 0, 0, 0); __builtin_amdgcn_s_setprio(0); } while (0)
; #define PG8_WAIT_V(n) asm volatile("s_waitcnt vmcnt(" #n ")" ::: "memory")
; #define PG8_WAIT_L(n) asm volatile("s_waitcnt lgkmcnt(" #n ")" ::: "memory")
; #define PG8_BAR __builtin_amdgcn_s_barrier()
; #define PG8_SCHED __builtin_amdgcn_sched_barrier(0)
;   DI void operator()(const f32x4 (&acc)[2][2][4][2], const Unit& u, int wr, int wc, int fr, int fq) const {
;     if (u.pn >= 16) {
;       const int row0 = u.pm * BM + wr * 64 + fr, col0 = (u.pn - 16) * BM + wc * 32 + 8 * fq;
;     ...
;     const int col = u.pn * 128 + wc * 32 + 8 * fq;
;     float w0[8], w1[8], w2[8];
; #pragma unroll
;     for (int e = 0; e < 8; ++e) { w0[e] = cw[col + e]; w1[e] = cw[2048 + col + e]; w2[e] = cw[4096 + col + e]; }
; #pragma unroll
;     for (int ai = 0; ai < 2; ++ai) {
;       const int row0 = u.pm * BM + ai * HALF + wr * 64, span = row0 >> 6;
;       float rsv[4];
; #pragma unroll
;       for (int m = 0; m < 4; ++m) rsv[m] = row_rstd(ssq, row0 + 16 * m + fr, fq);
; template <class Epi, class Sched = StaticOrder>
; DI void gemm_phase(LAS unsigned char* lds, const Gemm g, const Sched& S, const Epi& E) {
;     ...
;       PG8_BAR; PG8_WAIT_L(0); PG8_MMA(1, 0, At, B0); PG8_BAR; PG8_SCHED;
;       PG8_STAGE(PG8_SB(1, 1), b3 + hstep, voffB);
;       PG8_WAIT_V(6); PG8_BAR; PG8_MMA(1, 1, At, B1); PG8_BAR;
;     }
	s_waitcnt lgkmcnt(0)
	s_setprio 1
	v_mfma_f32_16x16x32_bf16 v[60:63], v[128:131], v[144:147], v[60:63]
	v_mfma_f32_16x16x32_bf16 v[56:59], v[136:139], v[144:147], v[56:59]
	v_mfma_f32_16x16x32_bf16 v[48:51], v[128:131], v[152:155], v[48:51]
	v_mfma_f32_16x16x32_bf16 v[40:43], v[136:139], v[152:155], v[40:43]
	v_mfma_f32_16x16x32_bf16 v[28:31], v[128:131], v[178:181], v[28:31]
	v_mfma_f32_16x16x32_bf16 v[24:27], v[136:139], v[178:181], v[24:27]
	v_mfma_f32_16x16x32_bf16 v[12:15], v[128:131], v[186:189], v[12:15]
	v_mfma_f32_16x16x32_bf16 v[8:11], v[136:139], v[186:189], v[8:11]
	v_mfma_f32_16x16x32_bf16 v[60:63], v[132:135], v[148:151], v[60:63]
	v_mfma_f32_16x16x32_bf16 v[56:59], v[140:143], v[148:151], v[56:59]
	v_mfma_f32_16x16x32_bf16 v[48:51], v[132:135], v[156:159], v[48:51]
	v_mfma_f32_16x16x32_bf16 v[40:43], v[140:143], v[156:159], v[40:43]
	v_mfma_f32_16x16x32_bf16 v[28:31], v[132:135], v[182:185], v[28:31]
	v_mfma_f32_16x16x32_bf16 v[24:27], v[140:143], v[182:185], v[24:27]
	v_mfma_f32_16x16x32_bf16 v[12:15], v[132:135], v[190:193], v[12:15]
	v_mfma_f32_16x16x32_bf16 v[8:11], v[140:143], v[190:193], v[8:11]
	s_barrier
	s_setprio 0
	s_add_u32 s12, s12, 0x80080
	s_addc_u32 s13, s13, 0
	s_add_i32 s53, s54, s70
	v_lshl_add_u64 v[128:129], s[12:13], 0, v[162:163]
	s_mov_b32 m0, s53
	s_nop 0
	global_load_lds_dwordx4 v[128:129], off
	v_lshl_add_u64 v[128:129], s[12:13], 0, v[166:167]
	s_add_i32 m0, s53, 0x2000
	s_nop 0
	global_load_lds_dwordx4 v[128:129], off
	s_waitcnt vmcnt(6)
	s_barrier
	s_setprio 1
	v_mfma_f32_16x16x32_bf16 v[52:55], v[194:197], v[144:147], v[52:55]
	v_mfma_f32_16x16x32_bf16 v[44:47], v[216:219], v[144:147], v[44:47]
	v_mfma_f32_16x16x32_bf16 v[36:39], v[194:197], v[152:155], v[36:39]
	v_mfma_f32_16x16x32_bf16 v[32:35], v[216:219], v[152:155], v[32:35]
	v_mfma_f32_16x16x32_bf16 v[20:23], v[194:197], v[178:181], v[20:23]
	v_mfma_f32_16x16x32_bf16 v[16:19], v[216:219], v[178:181], v[16:19]
	v_mfma_f32_16x16x32_bf16 v[4:7], v[194:197], v[186:189], v[4:7]
	v_mfma_f32_16x16x32_bf16 v[0:3], v[216:219], v[186:189], v[0:3]
	v_mfma_f32_16x16x32_bf16 v[52:55], v[212:215], v[148:151], v[52:55]
	v_mfma_f32_16x16x32_bf16 v[44:47], v[220:223], v[148:151], v[44:47]
	v_mfma_f32_16x16x32_bf16 v[36:39], v[212:215], v[156:159], v[36:39]
	v_mfma_f32_16x16x32_bf16 v[32:35], v[220:223], v[156:159], v[32:35]
	v_mfma_f32_16x16x32_bf16 v[20:23], v[212:215], v[182:185], v[20:23]
	v_mfma_f32_16x16x32_bf16 v[16:19], v[220:223], v[182:185], v[16:19]
	v_mfma_f32_16x16x32_bf16 v[4:7], v[212:215], v[190:193], v[4:7]
	v_mfma_f32_16x16x32_bf16 v[0:3], v[220:223], v[190:193], v[0:3]
	s_add_i32 s52, s52, 2
	s_add_u32 s10, s10, 0x100
	s_addc_u32 s11, s11, 0
	s_add_u32 s45, s45, 0x100
	s_addc_u32 s49, s49, 0
	s_cmp_gt_u32 s52, 29
	s_barrier
	s_setprio 0
	s_cbranch_scc0 .LBB0_1052
	s_cmp_lt_i32 s62, 16
	s_mov_b64 s[10:11], -1
	s_cbranch_scc0 .LBB0_1067
	s_lshl_b32 s41, s60, 8
	s_add_i32 s41, s41, s75
	v_or_b32_e32 v186, s41, v177
	v_ashrrev_i32_e32 v187, 31, v186
	v_lshlrev_b64 v[128:129], 7, v[186:187]
	v_or_b32_e32 v180, 16, v186
	v_lshl_add_u64 v[128:129], v[170:171], 0, v[128:129]
	v_ashrrev_i32_e32 v181, 31, v180
	global_load_dwordx4 v[152:155], v[128:129], off
	global_load_dwordx4 v[156:159], v[128:129], off offset:16
	v_lshlrev_b64 v[128:129], 7, v[180:181]
	v_lshl_add_u64 v[128:129], v[170:171], 0, v[128:129]
	global_load_dwordx4 v[188:191], v[128:129], off
	global_load_dwordx4 v[192:195], v[128:129], off offset:16
	v_or_b32_e32 v184, 32, v186
	v_ashrrev_i32_e32 v185, 31, v184
	v_lshlrev_b64 v[128:129], 7, v[184:185]
	v_or_b32_e32 v182, 48, v186
	v_lshl_add_u64 v[128:129], v[170:171], 0, v[128:129]
	v_ashrrev_i32_e32 v183, 31, v182
	global_load_dwordx4 v[212:215], v[128:129], off
	global_load_dwordx4 v[216:219], v[128:129], off offset:16
	v_lshlrev_b64 v[128:129], 7, v[182:183]
	v_lshl_add_u64 v[128:129], v[170:171], 0, v[128:129]
	global_load_dwordx4 v[220:223], v[128:129], off
	global_load_dwordx4 v[224:227], v[128:129], off offset:16
	v_and_b32_e32 v129, 64, v206
	v_lshl_or_b32 v178, s62, 7, v200
	v_xor_b32_e32 v128, 16, v206
	v_add_u32_e32 v129, 64, v129
	v_readlane_b32 s44, v243, 3
	v_xor_b32_e32 v130, 32, v206
	v_ashrrev_i32_e32 v179, 31, v178
	v_readlane_b32 s45, v243, 4
	v_cmp_lt_i32_e32 vcc, v128, v129
	s_movk_i32 s10, 0x2000
	v_lshl_add_u64 v[144:145], v[178:179], 2, s[44:45]
	v_cndmask_b32_e32 v134, v206, v128, vcc
	v_cmp_lt_i32_e32 vcc, v130, v129
	v_lshl_add_u64 v[132:133], v[144:145], 0, s[26:27]
	v_lshl_add_u64 v[136:137], v[144:145], 0, s[28:29]
	v_cndmask_b32_e32 v135, v206, v130, vcc
	v_add_co_u32_e32 v146, vcc, s10, v144
	global_load_dwordx4 v[128:131], v[144:145], off offset:16
	global_load_dwordx4 v[140:143], v[144:145], off
	v_addc_co_u32_e32 v147, vcc, 0, v145, vcc
	v_add_co_u32_e32 v148, vcc, s74, v144
	v_lshlrev_b32_e32 v196, 2, v134
	s_nop 0
	v_addc_co_u32_e32 v149, vcc, 0, v145, vcc
	v_lshlrev_b32_e32 v207, 2, v135
	global_load_dwordx4 v[132:135], v[132:133], off offset:16
	s_nop 0
	global_load_dwordx4 v[136:139], v[136:137], off offset:16
	s_nop 0
	global_load_dwordx4 v[144:147], v[146:147], off
	s_nop 0
	global_load_dwordx4 v[148:151], v[148:149], off
	v_mov_b32_e32 v197, 0
	v_mov_b32_e32 v211, 0
	v_readlane_b32 s46, v243, 5
	v_readlane_b32 s47, v243, 6
	v_readlane_b32 s48, v243, 7
	v_readlane_b32 s49, v243, 8
	v_readlane_b32 s50, v243, 9
	v_readlane_b32 s51, v243, 10
	v_readlane_b32 s52, v243, 11
	v_readlane_b32 s53, v243, 12
	v_readlane_b32 s54, v243, 13
	v_readlane_b32 s55, v243, 14
	v_readlane_b32 s56, v243, 15
	v_readlane_b32 s57, v243, 16
	v_readlane_b32 s58, v243, 17
	v_readlane_b32 s59, v243, 18
	s_waitcnt vmcnt(0)
; DI unsigned pack2(float lo, float hi) { f32x2 v = {lo, hi}; bf16v2 r = __builtin_convertvector(v, bf16v2); return __builtin_bit_cast(unsigned, r); }
; DI float dpp_ror1(float v) { return __int_as_float(__builtin_amdgcn_update_dpp(0, __float_as_int(v), 0x121, 0xf, 0xf, false)); }
; DI float dpp_ror2(float v) { return __int_as_float(__builtin_amdgcn_update_dpp(0, __float_as_int(v), 0x122, 0xf, 0xf, false)); }
;   DI void operator()(const f32x4 (&acc)[2][2][4][2], const Unit& u, int wr, int wc, int fr, int fq) const {
;     ...
;       for (int m = 0; m < 4; ++m) rsv[m] = row_rstd(ssq, row0 + 16 * m + fr, fq);
;       float p1[8], p2[8];
; #pragma unroll
;       for (int e = 0; e < 8; ++e) { p1[e] = 0.f; p2[e] = 0.f; }
; #pragma unroll
;       for (int m = 0; m < 4; ++m) {
;         float g[8], a[8];
;         const float rs1 = rsv[m], rs2 = rs1 * rs1;
; #pragma unroll
;         for (int e = 0; e < 4; ++e) { g[e] = acc[ai][0][m][0][e] * acc[ai][1][m][0][e] * rs2; g[4 + e] = acc[ai][0][m][1][e] * acc[ai][1][m][1][e] * rs2; }
; #pragma unroll
;         for (int e = 0; e < 8; ++e) {
;           const float x1 = dpp_ror1(g[e]), x2 = dpp_ror2(g[e]);
;           const float pr1 = (fr == 0) ? p1[e] : x1, pr2 = (fr < 2) ? p2[e] : x2;
;           a[e] = w2[e] * g[e] + w1[e] * pr1 + w0[e] * pr2;
;           p1[e] = x1; p2[e] = x2;
;         }
;         if (m == 0 && fr < 2) {
;           float* hc = headC + (size_t)(span * 2 + fr) * 2048 + col;
;           *(f32x4*)hc = (f32x4){a[0], a[1], a[2], a[3]}; *(f32x4*)(hc + 4) = (f32x4){a[4], a[5], a[6], a[7]};
;         } else {
;           u32x4 w; w.x = pack2(a[0] * rs1, a[1] * rs1); w.y = pack2(a[2] * rs1, a[3] * rs1); w.z = pack2(a[4] * rs1, a[5] * rs1); w.w = pack2(a[6] * rs1, a[7] * rs1);
;           *(u32x4*)(C + (size_t)(row0 + 16 * m + fr) * 2048 + col) = w;
	v_mov_b32_e32 v208, v152
	v_mov_b32_e32 v209, v156
	v_mov_b32_e32 v156, v153
	v_mov_b32_e32 v152, v154
	v_mov_b32_e32 v153, v158
	v_mov_b32_e32 v158, v155
	v_pk_add_f32 v[154:155], v[208:209], v[156:157]
	v_pk_add_f32 v[152:153], v[152:153], v[158:159]
	v_mov_b32_e32 v156, v188
	v_mov_b32_e32 v157, v192
	v_mov_b32_e32 v192, v189
	v_mov_b32_e32 v158, v190
	v_mov_b32_e32 v159, v194
	v_mov_b32_e32 v194, v191
	v_pk_add_f32 v[152:153], v[154:155], v[152:153]
	v_pk_add_f32 v[154:155], v[156:157], v[192:193]
	v_pk_add_f32 v[156:157], v[158:159], v[194:195]
	v_mov_b32_e32 v188, v212
	v_pk_add_f32 v[154:155], v[154:155], v[156:157]
	v_mov_b32_e32 v157, v152
	v_mov_b32_e32 v156, v154
	v_mov_b32_e32 v152, v155
	v_pk_add_f32 v[152:153], v[156:157], v[152:153]
	ds_bpermute_b32 v155, v196, v153
	ds_bpermute_b32 v154, v196, v152
	v_mov_b32_e32 v189, v216
	v_mov_b32_e32 v216, v213
	v_mov_b32_e32 v190, v214
	v_mov_b32_e32 v191, v218
	s_waitcnt lgkmcnt(0)
	v_pk_add_f32 v[152:153], v[152:153], v[154:155]
	ds_bpermute_b32 v155, v207, v153
	ds_bpermute_b32 v154, v207, v152
	v_mov_b32_e32 v218, v215
	v_mov_b32_e32 v208, v220
	v_mov_b32_e32 v209, v224
	v_mov_b32_e32 v224, v221
	v_mov_b32_e32 v212, v222
	v_mov_b32_e32 v213, v226
	v_mov_b32_e32 v226, v223
	v_pk_add_f32 v[156:157], v[188:189], v[216:217]
	v_pk_add_f32 v[158:159], v[190:191], v[218:219]
	v_pk_add_f32 v[188:189], v[208:209], v[224:225]
	v_pk_add_f32 v[190:191], v[212:213], v[226:227]
	s_waitcnt lgkmcnt(0)
	v_pk_add_f32 v[152:153], v[152:153], v[154:155]
	v_pk_add_f32 v[156:157], v[156:157], v[158:159]
	v_pk_add_f32 v[158:159], v[188:189], v[190:191]
	v_pk_fma_f32 v[188:189], v[152:153], s[30:31], v[176:177] op_sel_hi:[1,0,0]
	v_mov_b32_e32 v153, v156
	v_mul_f32_e32 v152, 0x4b800000, v189
	v_cmp_gt_f32_e64 s[10:11], s84, v189
	v_mov_b32_e32 v156, v159
	v_mov_b32_e32 v194, v123
	v_cndmask_b32_e64 v152, v189, v152, s[10:11]
	v_rsq_f32_e32 v168, v152
	v_mov_b32_e32 v152, v158
	v_pk_add_f32 v[152:153], v[152:153], v[156:157]
	ds_bpermute_b32 v155, v196, v153
	ds_bpermute_b32 v154, v196, v152
	v_mul_f32_e32 v156, 0x45800000, v168
	v_cndmask_b32_e64 v195, v168, v156, s[10:11]
	v_mov_b32_e32 v217, 0
	v_mul_f32_e32 v156, v125, v113
	s_waitcnt lgkmcnt(0)
	v_pk_add_f32 v[190:191], v[152:153], v[154:155]
	v_mov_b32_e32 v152, v111
	v_mov_b32_e32 v153, v195
	v_mul_f32_e32 v154, v124, v112
	v_pk_mul_f32 v[152:153], v[194:195], v[152:153]
	v_mul_f32_e32 v155, v120, v108
	v_mul_f32_e32 v154, v154, v153
	v_pk_mul_f32 v[222:223], v[152:153], v[152:153] op_sel:[0,1] op_sel_hi:[1,0]
	v_mov_b32_e32 v213, 0
	v_mov_b32_dpp v217, v154 row_ror:1 row_mask:0xf bank_mask:0xf
	v_cndmask_b32_e64 v152, v217, 0, s[0:1]
	v_mul_f32_e32 v157, v121, v109
	v_mul_f32_e32 v158, v126, v114
	v_mul_f32_e32 v159, v122, v110
	v_mul_f32_e32 v168, v127, v115
	v_mul_f32_e32 v194, v155, v153
	v_mul_f32_e32 v155, v156, v153
	v_mov_b32_dpp v213, v154 row_ror:2 row_mask:0xf bank_mask:0xf
	v_mov_b32_e32 v221, 0
	v_mul_f32_e32 v152, v144, v152
	v_mul_f32_e32 v208, v157, v153
	v_mul_f32_e32 v156, v158, v153
	v_mul_f32_e32 v159, v159, v153
	v_mul_f32_e32 v157, v168, v153
	v_mov_b32_dpp v221, v155 row_ror:1 row_mask:0xf bank_mask:0xf
	v_cndmask_b32_e64 v153, v213, 0, s[8:9]
	v_fmac_f32_e32 v152, v148, v154
	v_mov_b32_e32 v219, 0
	v_fmac_f32_e32 v152, v140, v153
	v_cndmask_b32_e64 v153, v221, 0, s[0:1]
	v_mov_b32_dpp v219, v155 row_ror:2 row_mask:0xf bank_mask:0xf
	v_mul_f32_e32 v153, v145, v153
	v_mov_b32_e32 v216, 0
	v_cndmask_b32_e64 v154, v219, 0, s[8:9]
	v_fmac_f32_e32 v153, v149, v155
	v_mov_b32_dpp v216, v156 row_ror:1 row_mask:0xf bank_mask:0xf
	v_fmac_f32_e32 v153, v141, v154
	v_mov_b32_e32 v212, 0
	v_cndmask_b32_e64 v154, v216, 0, s[0:1]
	v_mov_b32_e32 v220, 0
	v_mov_b32_dpp v212, v156 row_ror:2 row_mask:0xf bank_mask:0xf
	v_mul_f32_e32 v154, v146, v154
	v_mov_b32_dpp v220, v157 row_ror:1 row_mask:0xf bank_mask:0xf
	v_cndmask_b32_e64 v155, v212, 0, s[8:9]
	v_fmac_f32_e32 v154, v150, v156
	v_mov_b32_e32 v218, 0
	v_fmac_f32_e32 v154, v142, v155
	v_cndmask_b32_e64 v155, v220, 0, s[0:1]
	v_mov_b32_dpp v218, v157 row_ror:2 row_mask:0xf bank_mask:0xf
	v_mul_f32_e32 v155, v147, v155
	v_cndmask_b32_e64 v156, v218, 0, s[8:9]
	v_fmac_f32_e32 v155, v151, v157
	v_mov_b32_dpp v197, v194 row_ror:1 row_mask:0xf bank_mask:0xf
	v_fmac_f32_e32 v155, v143, v156
	v_mov_b32_e32 v189, 0
	v_cndmask_b32_e64 v156, v197, 0, s[0:1]
	v_mov_b32_e32 v214, 0
	v_mov_b32_dpp v189, v194 row_ror:2 row_mask:0xf bank_mask:0xf
	v_mul_f32_e32 v156, v132, v156
	v_mov_b32_dpp v214, v208 row_ror:1 row_mask:0xf bank_mask:0xf
	v_cndmask_b32_e64 v157, v189, 0, s[8:9]
	v_fmac_f32_e32 v156, v136, v194
	v_fmac_f32_e32 v156, v128, v157
	v_cndmask_b32_e64 v157, v214, 0, s[0:1]
	v_mov_b32_e32 v209, 0
	v_mul_f32_e32 v157, v133, v157
	v_fmac_f32_e32 v157, v137, v208
	v_mov_b32_dpp v209, v208 row_ror:2 row_mask:0xf bank_mask:0xf
	v_mov_b32_e32 v208, 0
	v_cndmask_b32_e64 v158, v209, 0, s[8:9]
	v_fmac_f32_e32 v157, v129, v158
	v_mov_b32_dpp v208, v159 row_ror:1 row_mask:0xf bank_mask:0xf
	v_mov_b32_e32 v194, 0
	v_cndmask_b32_e64 v158, v208, 0, s[0:1]
	ds_bpermute_b32 v193, v207, v191
	ds_bpermute_b32 v192, v207, v190
	v_mov_b32_dpp v194, v159 row_ror:2 row_mask:0xf bank_mask:0xf
	v_mov_b32_e32 v215, 0
	v_mul_f32_e32 v158, v134, v158
	v_cndmask_b32_e64 v168, v194, 0, s[8:9]
	v_mov_b32_dpp v215, v222 row_ror:1 row_mask:0xf bank_mask:0xf
	v_fmac_f32_e32 v158, v138, v159
	v_mov_b32_dpp v211, v222 row_ror:2 row_mask:0xf bank_mask:0xf
	v_fmac_f32_e32 v158, v130, v168
	v_cndmask_b32_e64 v168, v215, 0, s[0:1]
	v_mul_f32_e32 v159, v139, v222
	v_cndmask_b32_e64 v223, v211, 0, s[8:9]
	v_fmac_f32_e32 v159, v135, v168
	v_cmp_gt_f32_e32 vcc, s84, v188
	v_fmac_f32_e32 v159, v131, v223
	s_and_saveexec_b64 s[10:11], s[4:5]
	s_xor_b64 s[10:11], exec, s[10:11]
	s_cbranch_execz .LBB0_1056
	v_mul_f32_e32 v152, v195, v152
	v_mul_f32_e32 v153, v195, v153
	v_cvt_pk_bf16_f32 v152, v152, v153
	v_mul_f32_e32 v153, v195, v154
	v_mul_f32_e32 v154, v195, v155
	v_cvt_pk_bf16_f32 v153, v153, v154
	v_mul_f32_e32 v154, v195, v156
	v_mul_f32_e32 v155, v195, v157
	v_cvt_pk_bf16_f32 v154, v154, v155
	v_mul_f32_e32 v155, v195, v158
	v_mul_f32_e32 v156, v195, v159
	v_cvt_pk_bf16_f32 v155, v155, v156
	v_lshlrev_b64 v[156:157], 12, v[186:187]
	v_lshl_add_u64 v[156:157], s[18:19], 0, v[156:157]
	v_lshl_add_u64 v[156:157], v[178:179], 1, v[156:157]
	global_store_dwordx4 v[156:157], v[152:155], off

; #define PG8_STAGE(bufoff, gbase, voff) do { _Pragma("unroll") for (int _i = 0; _i < 2; ++_i) \
;     __builtin_amdgcn_global_load_lds((const unsigned*)((const char*)(gbase) + (voff)[_i]), (LAS unsigned*)(lds + (bufoff) + ldsw + _i * 8192), 16, 0, 0); } while (0)
; #define PG8_LDA(dst, b, h) do { _Pragma("unroll") for (int m = 0; m < 4; ++m) _Pragma("unroll") for (int k = 0; k < 2; ++k) dst[m][k] = *(const LAS bf16x8*)(lds + PG8_SA(b, h) + aoff + m * 2048 + k * 1024); } while (0)
; #define PG8_LDB(dst, b, h) do { _Pragma("unroll") for (int n = 0; n < 2; ++n) _Pragma("unroll") for (int k = 0; k < 2; ++k) dst[n][k] = *(const LAS bf16x8*)(lds + PG8_SB(b, h) + boff + n * 2048 + k * 1024); } while (0)
; #define PG8_MMA(ai, bj, At, Bt) do { __builtin_amdgcn_s_setprio(1); _Pragma("unroll") for (int m = 0; m < 4; ++m) _Pragma("unroll") for (int n = 0; n < 2; ++n) _Pragma("unroll") for (int k = 0; k < 2; ++k) \
;     acc[ai][bj][m][n] = __builtin_amdgcn_mfma_f32_16x16x32_bf16(Bt[n][k], At[m][k], acc[ai][bj][m][n], 0, 0, 0); __builtin_amdgcn_s_setprio(0); } while (0)
; #define PG8_WAIT_L(n) asm volatile("s_waitcnt lgkmcnt(" #n ")" ::: "memory")
; #define PG8_BAR __builtin_amdgcn_s_barrier()
; #define PG8_SCHED __builtin_amdgcn_sched_barrier(0)
; template <class Epi, class Sched = StaticOrder>
; DI void gemm_phase(LAS unsigned char* lds, const Gemm g, const Sched& S, const Epi& E) {
;     ...
;       PG8_LDB(B0, 0, 0); PG8_SCHED; PG8_LDA(At, 0, 0); PG8_STAGE(PG8_SA(1, 1), a1 + hstep, voffA);
;       PG8_WAIT_L(8); PG8_BAR; PG8_WAIT_L(0); PG8_MMA(0, 0, At, B0); PG8_BAR; PG8_SCHED;
;       PG8_LDB(B1, 0, 1); PG8_STAGE(PG8_SB(0, 0), b2, voffB);
;       PG8_BAR; PG8_WAIT_L(0); PG8_MMA(0, 1, At, B1); PG8_BAR;
;       PG8_LDA(At, 0, 1); PG8_STAGE(PG8_SA(0, 0), a2, voffA);
;       PG8_BAR; PG8_WAIT_L(0); PG8_MMA(1, 0, At, B0); PG8_BAR; PG8_SCHED;
.LBB0_1194:
	ds_read_b128 v[128:131], v214
	ds_read_b128 v[132:135], v214 offset:1024
	ds_read_b128 v[136:139], v214 offset:2048
	ds_read_b128 v[140:143], v214 offset:3072
	s_add_u32 s24, s22, 0xfff80080
	s_addc_u32 s25, s23, -1
	s_cmp_eq_u32 s54, 28
	s_cselect_b32 s27, s17, s25
	s_cselect_b32 s26, s43, s24
	s_cselect_b32 s25, s15, s53
	s_cselect_b32 s24, s51, s52
	v_lshl_add_u64 v[192:193], s[22:23], 0, v[184:185]
	s_add_i32 m0, s37, 0xc000
	ds_read_b128 v[144:147], v215
	ds_read_b128 v[148:151], v215 offset:1024
	ds_read_b128 v[152:155], v215 offset:2048
	ds_read_b128 v[156:159], v215 offset:3072
	ds_read_b128 v[160:163], v215 offset:4096
	ds_read_b128 v[164:167], v215 offset:5120
	ds_read_b128 v[168:171], v215 offset:6144
	ds_read_b128 v[172:175], v215 offset:7168
	global_load_lds_dwordx4 v[192:193], off
	v_lshl_add_u64 v[192:193], s[22:23], 0, v[186:187]
	s_add_i32 m0, s37, 0xe000
	s_nop 0
	global_load_lds_dwordx4 v[192:193], off
	s_waitcnt lgkmcnt(8)
	s_barrier
	s_waitcnt lgkmcnt(0)
	s_setprio 1
	v_mfma_f32_16x16x32_bf16 v[124:127], v[128:131], v[144:147], v[124:127]
	v_mfma_f32_16x16x32_bf16 v[120:123], v[136:139], v[144:147], v[120:123]
	v_mfma_f32_16x16x32_bf16 v[108:111], v[128:131], v[152:155], v[108:111]
	v_mfma_f32_16x16x32_bf16 v[104:107], v[136:139], v[152:155], v[104:107]
	v_mfma_f32_16x16x32_bf16 v[92:95], v[128:131], v[160:163], v[92:95]
	v_mfma_f32_16x16x32_bf16 v[88:91], v[136:139], v[160:163], v[88:91]
	v_mfma_f32_16x16x32_bf16 v[76:79], v[128:131], v[168:171], v[76:79]
	v_mfma_f32_16x16x32_bf16 v[72:75], v[136:139], v[168:171], v[72:75]
	v_mfma_f32_16x16x32_bf16 v[124:127], v[132:135], v[148:151], v[124:127]
	v_mfma_f32_16x16x32_bf16 v[120:123], v[140:143], v[148:151], v[120:123]
	v_mfma_f32_16x16x32_bf16 v[108:111], v[132:135], v[156:159], v[108:111]
	v_mfma_f32_16x16x32_bf16 v[104:107], v[140:143], v[156:159], v[104:107]
	v_mfma_f32_16x16x32_bf16 v[92:95], v[132:135], v[164:167], v[92:95]
	v_mfma_f32_16x16x32_bf16 v[88:91], v[140:143], v[164:167], v[88:91]
	v_mfma_f32_16x16x32_bf16 v[76:79], v[132:135], v[172:175], v[76:79]
	v_mfma_f32_16x16x32_bf16 v[72:75], v[140:143], v[172:175], v[72:75]
	s_barrier
	s_setprio 0
	s_add_i32 s55, s48, s35
	v_lshl_add_u64 v[208:209], s[24:25], 0, v[180:181]
	s_mov_b32 m0, s55
	ds_read_b128 v[192:195], v216
	ds_read_b128 v[196:199], v216 offset:1024
	ds_read_b128 v[200:203], v216 offset:2048
	ds_read_b128 v[204:207], v216 offset:3072
	global_load_lds_dwordx4 v[208:209], off
	v_lshl_add_u64 v[218:219], s[24:25], 0, v[176:177]
	s_add_i32 m0, s55, 0x2000
	s_nop 0
	global_load_lds_dwordx4 v[218:219], off
	s_barrier
	s_waitcnt lgkmcnt(0)
	s_setprio 1
	v_mfma_f32_16x16x32_bf16 v[116:119], v[192:195], v[144:147], v[116:119]
	v_mfma_f32_16x16x32_bf16 v[112:115], v[200:203], v[144:147], v[112:115]
	v_mfma_f32_16x16x32_bf16 v[100:103], v[192:195], v[152:155], v[100:103]
	v_mfma_f32_16x16x32_bf16 v[96:99], v[200:203], v[152:155], v[96:99]
	v_mfma_f32_16x16x32_bf16 v[84:87], v[192:195], v[160:163], v[84:87]
	v_mfma_f32_16x16x32_bf16 v[80:83], v[200:203], v[160:163], v[80:83]
	v_mfma_f32_16x16x32_bf16 v[68:71], v[192:195], v[168:171], v[68:71]
	v_mfma_f32_16x16x32_bf16 v[64:67], v[200:203], v[168:171], v[64:67]
	v_mfma_f32_16x16x32_bf16 v[116:119], v[196:199], v[148:151], v[116:119]
	v_mfma_f32_16x16x32_bf16 v[112:115], v[204:207], v[148:151], v[112:115]
	v_mfma_f32_16x16x32_bf16 v[100:103], v[196:199], v[156:159], v[100:103]
	v_mfma_f32_16x16x32_bf16 v[96:99], v[204:207], v[156:159], v[96:99]
	v_mfma_f32_16x16x32_bf16 v[84:87], v[196:199], v[164:167], v[84:87]
	v_mfma_f32_16x16x32_bf16 v[80:83], v[204:207], v[164:167], v[80:83]
	v_mfma_f32_16x16x32_bf16 v[68:71], v[196:199], v[172:175], v[68:71]
	v_mfma_f32_16x16x32_bf16 v[64:67], v[204:207], v[172:175], v[64:67]
	s_barrier
	s_setprio 0
	s_mov_b32 m0, s37
	v_lshl_add_u64 v[220:221], s[26:27], 0, v[182:183]
	ds_read_b128 v[144:147], v215 offset:16384
	ds_read_b128 v[148:151], v215 offset:17408
	ds_read_b128 v[152:155], v215 offset:18432
	ds_read_b128 v[156:159], v215 offset:19456
	ds_read_b128 v[160:163], v215 offset:20480
	ds_read_b128 v[164:167], v215 offset:21504
	ds_read_b128 v[168:171], v215 offset:22528
	ds_read_b128 v[172:175], v215 offset:23552
	global_load_lds_dwordx4 v[220:221], off
	v_lshl_add_u64 v[222:223], s[26:27], 0, v[178:179]
	s_mov_b32 m0, s38
	s_nop 0
	global_load_lds_dwordx4 v[222:223], off
	s_barrier
	s_waitcnt lgkmcnt(0)
	s_setprio 1
	v_mfma_f32_16x16x32_bf16 v[60:63], v[128:131], v[144:147], v[60:63]
	v_mfma_f32_16x16x32_bf16 v[56:59], v[136:139], v[144:147], v[56:59]
	v_mfma_f32_16x16x32_bf16 v[44:47], v[128:131], v[152:155], v[44:47]
	v_mfma_f32_16x16x32_bf16 v[40:43], v[136:139], v[152:155], v[40:43]
	v_mfma_f32_16x16x32_bf16 v[28:31], v[128:131], v[160:163], v[28:31]
	v_mfma_f32_16x16x32_bf16 v[24:27], v[136:139], v[160:163], v[24:27]
	v_mfma_f32_16x16x32_bf16 v[12:15], v[128:131], v[168:171], v[12:15]
	v_mfma_f32_16x16x32_bf16 v[8:11], v[136:139], v[168:171], v[8:11]
	v_mfma_f32_16x16x32_bf16 v[60:63], v[132:135], v[148:151], v[60:63]
	v_mfma_f32_16x16x32_bf16 v[56:59], v[140:143], v[148:151], v[56:59]
	v_mfma_f32_16x16x32_bf16 v[44:47], v[132:135], v[156:159], v[44:47]
	v_mfma_f32_16x16x32_bf16 v[40:43], v[140:143], v[156:159], v[40:43]
	v_mfma_f32_16x16x32_bf16 v[28:31], v[132:135], v[164:167], v[28:31]
	v_mfma_f32_16x16x32_bf16 v[24:27], v[140:143], v[164:167], v[24:27]
	v_mfma_f32_16x16x32_bf16 v[12:15], v[132:135], v[172:175], v[12:15]
	v_mfma_f32_16x16x32_bf16 v[8:11], v[140:143], v[172:175], v[8:11]
	s_barrier
; #define PG8_STAGE(bufoff, gbase, voff) do { _Pragma("unroll") for (int _i = 0; _i < 2; ++_i) \
;     __builtin_amdgcn_global_load_lds((const unsigned*)((const char*)(gbase) + (voff)[_i]), (LAS unsigned*)(lds + (bufoff) + ldsw + _i * 8192), 16, 0, 0); } while (0)
; #define PG8_LDA(dst, b, h) do { _Pragma("unroll") for (int m = 0; m < 4; ++m) _Pragma("unroll") for (int k = 0; k < 2; ++k) dst[m][k] = *(const LAS bf16x8*)(lds + PG8_SA(b, h) + aoff + m * 2048 + k * 1024); } while (0)
; #define PG8_LDB(dst, b, h) do { _Pragma("unroll") for (int n = 0; n < 2; ++n) _Pragma("unroll") for (int k = 0; k < 2; ++k) dst[n][k] = *(const LAS bf16x8*)(lds + PG8_SB(b, h) + boff + n * 2048 + k * 1024); } while (0)
; #define PG8_MMA(ai, bj, At, Bt) do { __builtin_amdgcn_s_setprio(1); _Pragma("unroll") for (int m = 0; m < 4; ++m) _Pragma("unroll") for (int n = 0; n < 2; ++n) _Pragma("unroll") for (int k = 0; k < 2; ++k) \
;     acc[ai][bj][m][n] = __builtin_amdgcn_mfma_f32_16x16x32_bf16(Bt[n][k], At[m][k], acc[ai][bj][m][n], 0, 0, 0); __builtin_amdgcn_s_setprio(0); } while (0)
; #define PG8_WAIT_V(n) asm volatile("s_waitcnt vmcnt(" #n ")" ::: "memory")
; #define PG8_WAIT_L(n) asm volatile("s_waitcnt lgkmcnt(" #n ")" ::: "memory")
; #define PG8_BAR __builtin_amdgcn_s_barrier()
; #define PG8_SCHED __builtin_amdgcn_sched_barrier(0)
; template <class Epi, class Sched = StaticOrder>
; DI void gemm_phase(LAS unsigned char* lds, const Gemm g, const Sched& S, const Epi& E) {
;     ...
;       PG8_STAGE(PG8_SB(0, 1), b2 + hstep, voffB);
;       PG8_WAIT_V(6); PG8_BAR; PG8_MMA(1, 1, At, B1); PG8_BAR;
;       PG8_LDB(B0, 1, 0); PG8_SCHED; PG8_LDA(At, 1, 0); PG8_STAGE(PG8_SA(0, 1), a2 + hstep, voffA);
;       PG8_WAIT_L(8); PG8_BAR; PG8_WAIT_L(0); PG8_MMA(0, 0, At, B0); PG8_BAR; PG8_SCHED;
;       PG8_LDB(B1, 1, 1); PG8_STAGE(PG8_SB(1, 0), b3, voffB);
;       PG8_BAR; PG8_WAIT_L(0); PG8_MMA(0, 1, At, B1); PG8_BAR;
;       PG8_LDA(At, 1, 1); PG8_STAGE(PG8_SA(1, 0), a3, voffA);
	s_setprio 0
	s_add_u32 s56, s24, 0x80000
	s_addc_u32 s57, s25, 0
	s_add_i32 s55, s49, s35
	v_lshl_add_u64 v[128:129], s[56:57], 0, v[180:181]
	s_mov_b32 m0, s55
	s_nop 0
	global_load_lds_dwordx4 v[128:129], off
	v_lshl_add_u64 v[128:129], s[56:57], 0, v[176:177]
	s_add_i32 m0, s55, 0x2000
	s_nop 0
	global_load_lds_dwordx4 v[128:129], off
	s_waitcnt vmcnt(6)
	s_barrier
	s_setprio 1
	v_mfma_f32_16x16x32_bf16 v[52:55], v[192:195], v[144:147], v[52:55]
	v_mfma_f32_16x16x32_bf16 v[48:51], v[200:203], v[144:147], v[48:51]
	v_mfma_f32_16x16x32_bf16 v[36:39], v[192:195], v[152:155], v[36:39]
	v_mfma_f32_16x16x32_bf16 v[32:35], v[200:203], v[152:155], v[32:35]
	v_mfma_f32_16x16x32_bf16 v[20:23], v[192:195], v[160:163], v[20:23]
	v_mfma_f32_16x16x32_bf16 v[16:19], v[200:203], v[160:163], v[16:19]
	v_mfma_f32_16x16x32_bf16 v[4:7], v[192:195], v[168:171], v[4:7]
	v_mfma_f32_16x16x32_bf16 v[0:3], v[200:203], v[168:171], v[0:3]
	v_mfma_f32_16x16x32_bf16 v[52:55], v[196:199], v[148:151], v[52:55]
	v_mfma_f32_16x16x32_bf16 v[48:51], v[204:207], v[148:151], v[48:51]
	v_mfma_f32_16x16x32_bf16 v[36:39], v[196:199], v[156:159], v[36:39]
	v_mfma_f32_16x16x32_bf16 v[32:35], v[204:207], v[156:159], v[32:35]
	v_mfma_f32_16x16x32_bf16 v[20:23], v[196:199], v[164:167], v[20:23]
	v_mfma_f32_16x16x32_bf16 v[16:19], v[204:207], v[164:167], v[16:19]
	v_mfma_f32_16x16x32_bf16 v[4:7], v[196:199], v[172:175], v[4:7]
	v_mfma_f32_16x16x32_bf16 v[0:3], v[204:207], v[172:175], v[0:3]
	s_barrier
	s_setprio 0
	s_add_i32 s55, 0, 0x18000
	v_add_u32_e32 v140, s55, v212
	ds_read_b128 v[128:131], v140
	ds_read_b128 v[132:135], v140 offset:1024
	ds_read_b128 v[136:139], v140 offset:2048
	ds_read_b128 v[140:143], v140 offset:3072
	s_add_u32 s26, s26, 0x80000
	s_addc_u32 s27, s27, 0
	s_mov_b32 m0, s39
	v_lshl_add_u64 v[192:193], s[26:27], 0, v[182:183]
	ds_read_b128 v[144:147], v215 offset:32768
	ds_read_b128 v[148:151], v215 offset:33792
	ds_read_b128 v[152:155], v215 offset:34816
	ds_read_b128 v[156:159], v215 offset:35840
	ds_read_b128 v[160:163], v215 offset:36864
	ds_read_b128 v[164:167], v215 offset:37888
	ds_read_b128 v[168:171], v215 offset:38912
	ds_read_b128 v[172:175], v215 offset:39936
	global_load_lds_dwordx4 v[192:193], off
	v_lshl_add_u64 v[192:193], s[26:27], 0, v[178:179]
	s_mov_b32 m0, s40
	s_nop 0
	global_load_lds_dwordx4 v[192:193], off
	s_waitcnt lgkmcnt(8)
	s_barrier
	s_waitcnt lgkmcnt(0)
	s_setprio 1
	v_mfma_f32_16x16x32_bf16 v[124:127], v[128:131], v[144:147], v[124:127]
	v_mfma_f32_16x16x32_bf16 v[120:123], v[136:139], v[144:147], v[120:123]
	v_mfma_f32_16x16x32_bf16 v[108:111], v[128:131], v[152:155], v[108:111]
	v_mfma_f32_16x16x32_bf16 v[104:107], v[136:139], v[152:155], v[104:107]
	v_mfma_f32_16x16x32_bf16 v[92:95], v[128:131], v[160:163], v[92:95]
	v_mfma_f32_16x16x32_bf16 v[88:91], v[136:139], v[160:163], v[88:91]
	v_mfma_f32_16x16x32_bf16 v[76:79], v[128:131], v[168:171], v[76:79]
	v_mfma_f32_16x16x32_bf16 v[72:75], v[136:139], v[168:171], v[72:75]
	v_mfma_f32_16x16x32_bf16 v[124:127], v[132:135], v[148:151], v[124:127]
	v_mfma_f32_16x16x32_bf16 v[120:123], v[140:143], v[148:151], v[120:123]
	v_mfma_f32_16x16x32_bf16 v[108:111], v[132:135], v[156:159], v[108:111]
	v_mfma_f32_16x16x32_bf16 v[104:107], v[140:143], v[156:159], v[104:107]
	v_mfma_f32_16x16x32_bf16 v[92:95], v[132:135], v[164:167], v[92:95]
	v_mfma_f32_16x16x32_bf16 v[88:91], v[140:143], v[164:167], v[88:91]
	v_mfma_f32_16x16x32_bf16 v[76:79], v[132:135], v[172:175], v[76:79]
	v_mfma_f32_16x16x32_bf16 v[72:75], v[140:143], v[172:175], v[72:75]
	s_barrier
	s_setprio 0
	s_add_i32 s26, 0, 0x1c000
	s_add_i32 s27, s55, s35
	v_add_u32_e32 v204, s26, v212
	v_lshl_add_u64 v[208:209], v[208:209], 0, s[10:11]
	s_mov_b32 m0, s27
	ds_read_b128 v[192:195], v204
	ds_read_b128 v[196:199], v204 offset:1024
	ds_read_b128 v[200:203], v204 offset:2048
	ds_read_b128 v[204:207], v204 offset:3072
	global_load_lds_dwordx4 v[208:209], off
	v_lshl_add_u64 v[208:209], v[218:219], 0, s[10:11]
	s_add_i32 m0, s27, 0x2000
	s_nop 0
	global_load_lds_dwordx4 v[208:209], off
	s_barrier
	s_waitcnt lgkmcnt(0)
	s_setprio 1
	v_mfma_f32_16x16x32_bf16 v[116:119], v[192:195], v[144:147], v[116:119]
	v_mfma_f32_16x16x32_bf16 v[112:115], v[200:203], v[144:147], v[112:115]
	v_mfma_f32_16x16x32_bf16 v[100:103], v[192:195], v[152:155], v[100:103]
	v_mfma_f32_16x16x32_bf16 v[96:99], v[200:203], v[152:155], v[96:99]
	v_mfma_f32_16x16x32_bf16 v[84:87], v[192:195], v[160:163], v[84:87]
	v_mfma_f32_16x16x32_bf16 v[80:83], v[200:203], v[160:163], v[80:83]
	v_mfma_f32_16x16x32_bf16 v[68:71], v[192:195], v[168:171], v[68:71]
	v_mfma_f32_16x16x32_bf16 v[64:67], v[200:203], v[168:171], v[64:67]
	v_mfma_f32_16x16x32_bf16 v[116:119], v[196:199], v[148:151], v[116:119]
	v_mfma_f32_16x16x32_bf16 v[112:115], v[204:207], v[148:151], v[112:115]
	v_mfma_f32_16x16x32_bf16 v[100:103], v[196:199], v[156:159], v[100:103]
	v_mfma_f32_16x16x32_bf16 v[96:99], v[204:207], v[156:159], v[96:99]
	v_mfma_f32_16x16x32_bf16 v[84:87], v[196:199], v[164:167], v[84:87]
	v_mfma_f32_16x16x32_bf16 v[80:83], v[204:207], v[164:167], v[80:83]
	v_mfma_f32_16x16x32_bf16 v[68:71], v[196:199], v[172:175], v[68:71]
	v_mfma_f32_16x16x32_bf16 v[64:67], v[204:207], v[172:175], v[64:67]
	s_barrier
	s_setprio 0
	s_mov_b32 m0, s44
	v_lshl_add_u64 v[208:209], v[220:221], 0, s[10:11]
	ds_read_b128 v[144:147], v215 offset:49152
	ds_read_b128 v[148:151], v215 offset:50176
	ds_read_b128 v[152:155], v215 offset:51200
	ds_read_b128 v[156:159], v215 offset:52224
	ds_read_b128 v[160:163], v215 offset:53248
	ds_read_b128 v[164:167], v215 offset:54272
	ds_read_b128 v[168:171], v215 offset:55296
	ds_read_b128 v[172:175], v215 offset:56320
	global_load_lds_dwordx4 v[208:209], off
	v_lshl_add_u64 v[208:209], v[222:223], 0, s[10:11]
	s_mov_b32 m0, s45
	s_nop 0
	global_load_lds_dwordx4 v[208:209], off
	s_barrier
; #define PG8_STAGE(bufoff, gbase, voff) do { _Pragma("unroll") for (int _i = 0; _i < 2; ++_i) \
;     __builtin_amdgcn_global_load_lds((const unsigned*)((const char*)(gbase) + (voff)[_i]), (LAS unsigned*)(lds + (bufoff) + ldsw + _i * 8192), 16, 0, 0); } while (0)
; #define PG8_LDA(dst, b, h) do { _Pragma("unroll") for (int m = 0; m < 4; ++m) _Pragma("unroll") for (int k = 0; k < 2; ++k) dst[m][k] = *(const LAS bf16x8*)(lds + PG8_SA(b, h) + aoff + m * 2048 + k * 1024); } while (0)
; #define PG8_MMA(ai, bj, At, Bt) do { __builtin_amdgcn_s_setprio(1); _Pragma("unroll") for (int m = 0; m < 4; ++m) _Pragma("unroll") for (int n = 0; n < 2; ++n) _Pragma("unroll") for (int k = 0; k < 2; ++k) \
;     acc[ai][bj][m][n] = __builtin_amdgcn_mfma_f32_16x16x32_bf16(Bt[n][k], At[m][k], acc[ai][bj][m][n], 0, 0, 0); __builtin_amdgcn_s_setprio(0); } while (0)
; #define PG8_WAIT_V(n) asm volatile("s_waitcnt vmcnt(" #n ")" ::: "memory")
; #define PG8_WAIT_L(n) asm volatile("s_waitcnt lgkmcnt(" #n ")" ::: "memory")
; #define PG8_BAR __builtin_amdgcn_s_barrier()
; #define PG8_SCHED __builtin_amdgcn_sched_barrier(0)
; template <class Epi, class Sched = StaticOrder>
; DI void gemm_phase(LAS unsigned char* lds, const Gemm g, const Sched& S, const Epi& E) {
;     ...
;       PG8_LDA(At, 1, 1); PG8_STAGE(PG8_SA(1, 0), a3, voffA);
;       PG8_BAR; PG8_WAIT_L(0); PG8_MMA(1, 0, At, B0); PG8_BAR; PG8_SCHED;
;       PG8_STAGE(PG8_SB(1, 1), b3 + hstep, voffB);
;       PG8_WAIT_V(6); PG8_BAR; PG8_MMA(1, 1, At, B1); PG8_BAR;
	s_waitcnt lgkmcnt(0)
	s_setprio 1
	v_mfma_f32_16x16x32_bf16 v[60:63], v[128:131], v[144:147], v[60:63]
	v_mfma_f32_16x16x32_bf16 v[56:59], v[136:139], v[144:147], v[56:59]
	v_mfma_f32_16x16x32_bf16 v[44:47], v[128:131], v[152:155], v[44:47]
	v_mfma_f32_16x16x32_bf16 v[40:43], v[136:139], v[152:155], v[40:43]
	v_mfma_f32_16x16x32_bf16 v[28:31], v[128:131], v[160:163], v[28:31]
	v_mfma_f32_16x16x32_bf16 v[24:27], v[136:139], v[160:163], v[24:27]
	v_mfma_f32_16x16x32_bf16 v[12:15], v[128:131], v[168:171], v[12:15]
	v_mfma_f32_16x16x32_bf16 v[8:11], v[136:139], v[168:171], v[8:11]
	v_mfma_f32_16x16x32_bf16 v[60:63], v[132:135], v[148:151], v[60:63]
	v_mfma_f32_16x16x32_bf16 v[56:59], v[140:143], v[148:151], v[56:59]
	v_mfma_f32_16x16x32_bf16 v[44:47], v[132:135], v[156:159], v[44:47]
	v_mfma_f32_16x16x32_bf16 v[40:43], v[140:143], v[156:159], v[40:43]
	v_mfma_f32_16x16x32_bf16 v[28:31], v[132:135], v[164:167], v[28:31]
	v_mfma_f32_16x16x32_bf16 v[24:27], v[140:143], v[164:167], v[24:27]
	v_mfma_f32_16x16x32_bf16 v[12:15], v[132:135], v[172:175], v[12:15]
	v_mfma_f32_16x16x32_bf16 v[8:11], v[140:143], v[172:175], v[8:11]
	s_barrier
	s_setprio 0
	s_add_u32 s24, s24, 0x80080
	s_addc_u32 s25, s25, 0
	s_add_i32 s26, s26, s35
	v_lshl_add_u64 v[128:129], s[24:25], 0, v[180:181]
	s_mov_b32 m0, s26
	s_nop 0
	global_load_lds_dwordx4 v[128:129], off
	v_lshl_add_u64 v[128:129], s[24:25], 0, v[176:177]
	s_add_i32 m0, s26, 0x2000
	s_nop 0
	global_load_lds_dwordx4 v[128:129], off
	s_waitcnt vmcnt(6)
	s_barrier
	s_setprio 1
	v_mfma_f32_16x16x32_bf16 v[52:55], v[192:195], v[144:147], v[52:55]
	v_mfma_f32_16x16x32_bf16 v[48:51], v[200:203], v[144:147], v[48:51]
	v_mfma_f32_16x16x32_bf16 v[36:39], v[192:195], v[152:155], v[36:39]
	v_mfma_f32_16x16x32_bf16 v[32:35], v[200:203], v[152:155], v[32:35]
	v_mfma_f32_16x16x32_bf16 v[20:23], v[192:195], v[160:163], v[20:23]
	v_mfma_f32_16x16x32_bf16 v[16:19], v[200:203], v[160:163], v[16:19]
	v_mfma_f32_16x16x32_bf16 v[4:7], v[192:195], v[168:171], v[4:7]
	v_mfma_f32_16x16x32_bf16 v[0:3], v[200:203], v[168:171], v[0:3]
	v_mfma_f32_16x16x32_bf16 v[52:55], v[196:199], v[148:151], v[52:55]
	v_mfma_f32_16x16x32_bf16 v[48:51], v[204:207], v[148:151], v[48:51]
	v_mfma_f32_16x16x32_bf16 v[36:39], v[196:199], v[156:159], v[36:39]
	v_mfma_f32_16x16x32_bf16 v[32:35], v[204:207], v[156:159], v[32:35]
	v_mfma_f32_16x16x32_bf16 v[20:23], v[196:199], v[164:167], v[20:23]
	v_mfma_f32_16x16x32_bf16 v[16:19], v[204:207], v[164:167], v[16:19]
	v_mfma_f32_16x16x32_bf16 v[4:7], v[196:199], v[172:175], v[4:7]
	v_mfma_f32_16x16x32_bf16 v[0:3], v[204:207], v[172:175], v[0:3]
	s_add_i32 s54, s54, 2
	s_add_u32 s22, s22, 0x100
	s_addc_u32 s23, s23, 0
	s_add_u32 s52, s52, 0x100
	s_addc_u32 s53, s53, 0
	s_cmp_gt_u32 s54, 29
	s_barrier
	s_setprio 0
	s_cbranch_scc0 .LBB0_1194
; DI unsigned pack2(float lo, float hi) { f32x2 v = {lo, hi}; bf16v2 r = __builtin_convertvector(v, bf16v2); return __builtin_bit_cast(unsigned, r); }
;   DI void operator()(const f32x4 (&acc)[2][2][4][2], const Unit& u, int wr, int wc, int fr, int fq) const {
;     const int row0 = u.pm * BM + wr * 64 + fr, col0 = u.pn * BM + wc * 32 + 8 * fq;
; #pragma unroll
;     for (int ai = 0; ai < 2; ++ai) {
;       f32x4 bv[4][2][2];
; #pragma unroll
;       for (int m = 0; m < 4; ++m)
; #pragma unroll
;         for (int bj = 0; bj < 2; ++bj) {
;           const float* bp = base + (size_t)(row0 + ai * HALF + m * 16) * 2048 + col0 + bj * HALF;
;           bv[m][bj][0] = *(const f32x4*)bp; bv[m][bj][1] = *(const f32x4*)(bp + 4);
;         }
; #pragma unroll
;       for (int m = 0; m < 4; ++m) {
;         const int row = row0 + ai * HALF + m * 16;
;         const size_t off = (size_t)row * 2048 + col0;
;         float ss = 0.f;
; #pragma unroll
;         for (int bj = 0; bj < 2; ++bj) {
;           const f32x4 v0 = acc[ai][bj][m][0] + bv[m][bj][0], v1 = acc[ai][bj][m][1] + bv[m][bj][1];
;           *(f32x4*)(C + off + bj * HALF) = v0; *(f32x4*)(C + off + bj * HALF + 4) = v1;
;           if (xb) {
;             u32x4 w; w.x = pack2(v0[0], v0[1]); w.y = pack2(v0[2], v0[3]); w.z = pack2(v1[0], v1[1]); w.w = pack2(v1[2], v1[3]);
;             *(u32x4*)(xb + off + bj * HALF) = w;
;             ss += v0[0] * v0[0] + v0[1] * v0[1] + v0[2] * v0[2] + v0[3] * v0[3] + v1[0] * v1[0] + v1[1] * v1[1] + v1[2] * v1[2] + v1[3] * v1[3];
;           }
;         }
;         if (xb) {
;           ss += __shfl_xor(ss, 16); ss += __shfl_xor(ss, 32);
;           if (fq == 0) ssq[(size_t)row * 32 + u.pn * 4 + wc] = ss;
;         }
	v_lshl_add_u32 v194, s12, 8, v211
	v_lshl_or_b32 v192, s42, 8, v213
	v_readlane_b32 s52, v243, 3
	v_ashrrev_i32_e32 v193, 31, v192
	v_readlane_b32 s66, v243, 17
	v_readlane_b32 s67, v243, 18
	v_ashrrev_i32_e32 v195, 31, v194
	v_lshlrev_b64 v[128:129], 13, v[194:195]
	v_lshl_add_u64 v[196:197], v[192:193], 2, s[66:67]
	v_lshl_add_u64 v[236:237], v[196:197], 0, v[128:129]
	global_load_dwordx4 v[220:223], v[236:237], off
	global_load_dwordx4 v[224:227], v[236:237], off offset:16
	global_load_dwordx4 v[228:231], v[236:237], off offset:512
	global_load_dwordx4 v[232:235], v[236:237], off offset:528
	v_or_b32_e32 v206, 16, v194
	v_or_b32_e32 v202, 32, v194
	v_or_b32_e32 v198, 48, v194
	v_ashrrev_i32_e32 v207, 31, v206
	v_ashrrev_i32_e32 v203, 31, v202
	v_ashrrev_i32_e32 v199, 31, v198
	v_lshlrev_b64 v[128:129], 13, v[206:207]
	v_lshlrev_b64 v[130:131], 13, v[202:203]
	v_lshlrev_b64 v[132:133], 13, v[198:199]
	v_lshl_add_u64 v[208:209], v[196:197], 0, v[128:129]
	v_lshl_add_u64 v[204:205], v[196:197], 0, v[130:131]
	v_lshl_add_u64 v[200:201], v[196:197], 0, v[132:133]
	global_load_dwordx4 v[168:171], v[208:209], off offset:16
	global_load_dwordx4 v[172:175], v[208:209], off
	global_load_dwordx4 v[160:163], v[208:209], off offset:528
	global_load_dwordx4 v[164:167], v[208:209], off offset:512
	global_load_dwordx4 v[152:155], v[204:205], off offset:16
	global_load_dwordx4 v[156:159], v[204:205], off
	global_load_dwordx4 v[144:147], v[204:205], off offset:528
	global_load_dwordx4 v[148:151], v[204:205], off offset:512
	global_load_dwordx4 v[136:139], v[200:201], off offset:16
	global_load_dwordx4 v[140:143], v[200:201], off
	global_load_dwordx4 v[128:131], v[200:201], off offset:528
	global_load_dwordx4 v[132:135], v[200:201], off offset:512
	v_and_b32_e32 v218, 64, v217
	v_xor_b32_e32 v238, 16, v217
	v_add_u32_e32 v240, 64, v218
	v_xor_b32_e32 v239, 32, v217
	v_cmp_lt_i32_e32 vcc, v238, v240
	v_lshlrev_b64 v[218:219], 11, v[194:195]
	s_lshl_b32 s22, s42, 2
	v_cndmask_b32_e32 v241, v217, v238, vcc
	v_cmp_lt_i32_e32 vcc, v239, v240
	s_ashr_i32 s23, s22, 31
	v_readlane_b32 s53, v243, 4
	v_cndmask_b32_e32 v240, v217, v239, vcc
	v_lshl_add_u64 v[238:239], v[218:219], 0, v[192:193]
	v_lshlrev_b32_e32 v218, 2, v241
	v_lshl_add_u64 v[238:239], v[238:239], 1, s[2:3]
	v_readlane_b32 s54, v243, 5
	v_readlane_b32 s55, v243, 6
	v_readlane_b32 s56, v243, 7
	v_readlane_b32 s57, v243, 8
	v_readlane_b32 s58, v243, 9
	v_readlane_b32 s59, v243, 10
	v_readlane_b32 s60, v243, 11
	v_readlane_b32 s61, v243, 12
	v_readlane_b32 s62, v243, 13
	v_readlane_b32 s63, v243, 14
	v_readlane_b32 s64, v243, 15
	v_readlane_b32 s65, v243, 16
	s_waitcnt vmcnt(0)
	v_pk_add_f32 v[126:127], v[126:127], v[222:223]
	v_pk_add_f32 v[124:125], v[124:125], v[220:221]
	v_pk_add_f32 v[116:117], v[116:117], v[228:229]
	v_pk_add_f32 v[122:123], v[122:123], v[226:227]
	v_pk_add_f32 v[120:121], v[120:121], v[224:225]
	v_pk_add_f32 v[220:221], v[112:113], v[232:233]
	global_store_dwordx4 v[236:237], v[124:127], off
	global_store_dwordx4 v[236:237], v[120:123], off offset:16
	v_cvt_pk_bf16_f32 v112, v124, v125
	v_mul_f32_e32 v125, v125, v125
	v_mul_f32_e32 v219, v117, v117
	v_pk_add_f32 v[118:119], v[118:119], v[230:231]
	v_fmac_f32_e32 v125, v124, v124
	v_fmac_f32_e32 v219, v116, v116
	v_fmac_f32_e32 v125, v126, v126
	v_fmac_f32_e32 v219, v118, v118
	v_fmac_f32_e32 v125, v127, v127
	v_fmac_f32_e32 v219, v119, v119
	v_fmac_f32_e32 v125, v120, v120
	v_fmac_f32_e32 v219, v220, v220
	v_pk_add_f32 v[222:223], v[114:115], v[234:235]
	v_fmac_f32_e32 v125, v121, v121
	v_fmac_f32_e32 v219, v221, v221
	v_fmac_f32_e32 v125, v122, v122
	v_fmac_f32_e32 v219, v222, v222
	v_fmac_f32_e32 v125, v123, v123
	v_fmac_f32_e32 v219, v223, v223
	v_cvt_pk_bf16_f32 v114, v120, v121
	v_add_f32_e32 v121, v125, v219
	v_cvt_pk_bf16_f32 v115, v122, v123
	ds_bpermute_b32 v122, v218, v121
	v_cvt_pk_bf16_f32 v113, v126, v127
	global_store_dwordx4 v[238:239], v[112:115], off
	global_store_dwordx4 v[236:237], v[116:119], off offset:512
	global_store_dwordx4 v[236:237], v[220:223], off offset:528
	v_lshlrev_b32_e32 v126, 2, v240
	v_cvt_pk_bf16_f32 v120, v116, v117
	s_waitcnt lgkmcnt(0)
	v_add_f32_e32 v112, v121, v122
	ds_bpermute_b32 v113, v126, v112
	v_cvt_pk_bf16_f32 v121, v118, v119
	v_cvt_pk_bf16_f32 v122, v220, v221
	v_cvt_pk_bf16_f32 v123, v222, v223
	global_store_dwordx4 v[238:239], v[120:123], off offset:256
	s_and_saveexec_b64 s[24:25], s[0:1]
	s_cbranch_execz .LBB0_1197
	s_waitcnt lgkmcnt(0)
	v_add_f32_e32 v114, v112, v113
	v_lshlrev_b64 v[112:113], 7, v[194:195]
	v_lshl_add_u64 v[112:113], s[8:9], 0, v[112:113]
	v_lshl_add_u64 v[112:113], s[22:23], 2, v[112:113]
	s_lshl_b32 s12, s41, 2
	v_lshl_add_u64 v[112:113], v[112:113], 0, s[12:13]
	global_store_dword v[112:113], v114, off

; #define PG8_STAGE(bufoff, gbase, voff) do { _Pragma("unroll") for (int _i = 0; _i < 2; ++_i) \
;     __builtin_amdgcn_global_load_lds((const unsigned*)((const char*)(gbase) + (voff)[_i]), (LAS unsigned*)(lds + (bufoff) + ldsw + _i * 8192), 16, 0, 0); } while (0)
; #define PG8_LDA(dst, b, h) do { _Pragma("unroll") for (int m = 0; m < 4; ++m) _Pragma("unroll") for (int k = 0; k < 2; ++k) dst[m][k] = *(const LAS bf16x8*)(lds + PG8_SA(b, h) + aoff + m * 2048 + k * 1024); } while (0)
; #define PG8_LDB(dst, b, h) do { _Pragma("unroll") for (int n = 0; n < 2; ++n) _Pragma("unroll") for (int k = 0; k < 2; ++k) dst[n][k] = *(const LAS bf16x8*)(lds + PG8_SB(b, h) + boff + n * 2048 + k * 1024); } while (0)
; #define PG8_MMA(ai, bj, At, Bt) do { __builtin_amdgcn_s_setprio(1); _Pragma("unroll") for (int m = 0; m < 4; ++m) _Pragma("unroll") for (int n = 0; n < 2; ++n) _Pragma("unroll") for (int k = 0; k < 2; ++k) \
;     acc[ai][bj][m][n] = __builtin_amdgcn_mfma_f32_16x16x32_bf16(Bt[n][k], At[m][k], acc[ai][bj][m][n], 0, 0, 0); __builtin_amdgcn_s_setprio(0); } while (0)
; #define PG8_WAIT_V(n) asm volatile("s_waitcnt vmcnt(" #n ")" ::: "memory")
; #define PG8_WAIT_L(n) asm volatile("s_waitcnt lgkmcnt(" #n ")" ::: "memory")
; #define PG8_BAR __builtin_amdgcn_s_barrier()
; #define PG8_SCHED __builtin_amdgcn_sched_barrier(0)
; template <class Epi, class Sched = StaticOrder>
; DI void gemm_phase(LAS unsigned char* lds, const Gemm g, const Sched& S, const Epi& E) {
;     ...
;       PG8_LDB(B0, 0, 0); PG8_SCHED; PG8_LDA(At, 0, 0); PG8_STAGE(PG8_SA(1, 1), a1 + hstep, voffA);
;       PG8_WAIT_L(8); PG8_BAR; PG8_WAIT_L(0); PG8_MMA(0, 0, At, B0); PG8_BAR; PG8_SCHED;
;       PG8_LDB(B1, 0, 1); PG8_STAGE(PG8_SB(0, 0), b2, voffB);
;       PG8_BAR; PG8_WAIT_L(0); PG8_MMA(0, 1, At, B1); PG8_BAR;
;       PG8_LDA(At, 0, 1); PG8_STAGE(PG8_SA(0, 0), a2, voffA);
;       PG8_BAR; PG8_WAIT_L(0); PG8_MMA(1, 0, At, B0); PG8_BAR; PG8_SCHED;
;       PG8_STAGE(PG8_SB(0, 1), b2 + hstep, voffB);
;       PG8_WAIT_V(6); PG8_BAR; PG8_MMA(1, 1, At, B1); PG8_BAR;
.LBB0_1277:
	ds_read_b128 v[64:67], v201
	ds_read_b128 v[68:71], v201 offset:1024
	ds_read_b128 v[72:75], v201 offset:2048
	ds_read_b128 v[76:79], v201 offset:3072
	s_add_u32 s48, s14, 0xfff80080
	s_addc_u32 s49, s15, -1
	s_cmp_eq_u32 s58, 28
	s_cselect_b32 s51, s41, s49
	s_cselect_b32 s50, s42, s48
	s_cselect_b32 s49, s39, s53
	s_cselect_b32 s48, s43, s52
	v_lshl_add_u64 v[196:197], s[14:15], 0, v[170:171]
	s_add_i32 m0, s64, 0xc000
	ds_read_b128 v[80:83], v202
	ds_read_b128 v[84:87], v202 offset:1024
	ds_read_b128 v[88:91], v202 offset:2048
	ds_read_b128 v[92:95], v202 offset:3072
	ds_read_b128 v[180:183], v202 offset:4096
	ds_read_b128 v[184:187], v202 offset:5120
	ds_read_b128 v[188:191], v202 offset:6144
	ds_read_b128 v[192:195], v202 offset:7168
	global_load_lds_dwordx4 v[196:197], off
	v_lshl_add_u64 v[196:197], s[14:15], 0, v[172:173]
	s_add_i32 m0, s64, 0xe000
	s_nop 0
	global_load_lds_dwordx4 v[196:197], off
	s_waitcnt lgkmcnt(8)
	s_barrier
	s_waitcnt lgkmcnt(0)
	s_setprio 1
	v_mfma_f32_16x16x32_bf16 v[156:159], v[64:67], v[80:83], v[156:159]
	v_mfma_f32_16x16x32_bf16 v[144:147], v[72:75], v[80:83], v[144:147]
	v_mfma_f32_16x16x32_bf16 v[140:143], v[64:67], v[88:91], v[140:143]
	v_mfma_f32_16x16x32_bf16 v[132:135], v[72:75], v[88:91], v[132:135]
	v_mfma_f32_16x16x32_bf16 v[124:127], v[64:67], v[180:183], v[124:127]
	v_mfma_f32_16x16x32_bf16 v[116:119], v[72:75], v[180:183], v[116:119]
	v_mfma_f32_16x16x32_bf16 v[112:115], v[64:67], v[188:191], v[112:115]
	v_mfma_f32_16x16x32_bf16 v[108:111], v[72:75], v[188:191], v[108:111]
	v_mfma_f32_16x16x32_bf16 v[156:159], v[68:71], v[84:87], v[156:159]
	v_mfma_f32_16x16x32_bf16 v[144:147], v[76:79], v[84:87], v[144:147]
	v_mfma_f32_16x16x32_bf16 v[140:143], v[68:71], v[92:95], v[140:143]
	v_mfma_f32_16x16x32_bf16 v[132:135], v[76:79], v[92:95], v[132:135]
	v_mfma_f32_16x16x32_bf16 v[124:127], v[68:71], v[184:187], v[124:127]
	v_mfma_f32_16x16x32_bf16 v[116:119], v[76:79], v[184:187], v[116:119]
	v_mfma_f32_16x16x32_bf16 v[112:115], v[68:71], v[192:195], v[112:115]
	v_mfma_f32_16x16x32_bf16 v[108:111], v[76:79], v[192:195], v[108:111]
	s_barrier
	s_setprio 0
	s_add_i32 s59, s72, s62
	v_lshl_add_u64 v[196:197], s[48:49], 0, v[164:165]
	s_mov_b32 m0, s59
	ds_read_b128 v[206:209], v203
	ds_read_b128 v[212:215], v203 offset:1024
	ds_read_b128 v[216:219], v203 offset:2048
	ds_read_b128 v[220:223], v203 offset:3072
	global_load_lds_dwordx4 v[196:197], off
	v_lshl_add_u64 v[232:233], s[48:49], 0, v[160:161]
	s_add_i32 m0, s59, 0x2000
	s_nop 0
	global_load_lds_dwordx4 v[232:233], off
	s_barrier
	s_waitcnt lgkmcnt(0)
	s_setprio 1
	v_mfma_f32_16x16x32_bf16 v[152:155], v[206:209], v[80:83], v[152:155]
	v_mfma_f32_16x16x32_bf16 v[80:83], v[216:219], v[80:83], v[148:151]
	v_mfma_f32_16x16x32_bf16 v[152:155], v[212:215], v[84:87], v[152:155]
	v_mfma_f32_16x16x32_bf16 v[80:83], v[220:223], v[84:87], v[80:83]
	v_mfma_f32_16x16x32_bf16 v[84:87], v[206:209], v[88:91], v[136:139]
	v_mfma_f32_16x16x32_bf16 v[88:91], v[216:219], v[88:91], v[128:131]
	v_mfma_f32_16x16x32_bf16 v[104:107], v[216:219], v[180:183], v[104:107]
	v_mfma_f32_16x16x32_bf16 v[100:103], v[206:209], v[188:191], v[100:103]
	v_mfma_f32_16x16x32_bf16 v[96:99], v[216:219], v[188:191], v[96:99]
	v_mfma_f32_16x16x32_bf16 v[84:87], v[212:215], v[92:95], v[84:87]
	v_mfma_f32_16x16x32_bf16 v[88:91], v[220:223], v[92:95], v[88:91]
	v_mfma_f32_16x16x32_bf16 v[92:95], v[206:209], v[180:183], v[120:123]
	v_mfma_f32_16x16x32_bf16 v[104:107], v[220:223], v[184:187], v[104:107]
	v_mfma_f32_16x16x32_bf16 v[100:103], v[212:215], v[192:195], v[100:103]
	v_mfma_f32_16x16x32_bf16 v[96:99], v[220:223], v[192:195], v[96:99]
	v_mfma_f32_16x16x32_bf16 v[92:95], v[212:215], v[184:187], v[92:95]
	s_barrier
	s_setprio 0
	s_mov_b32 m0, s64
	v_lshl_add_u64 v[234:235], s[50:51], 0, v[166:167]
	ds_read_b128 v[120:123], v202 offset:16384
	ds_read_b128 v[128:131], v202 offset:17408
	ds_read_b128 v[136:139], v202 offset:18432
	ds_read_b128 v[148:151], v202 offset:19456
	ds_read_b128 v[180:183], v202 offset:20480
	ds_read_b128 v[184:187], v202 offset:21504
	ds_read_b128 v[188:191], v202 offset:22528
	ds_read_b128 v[192:195], v202 offset:23552
	global_load_lds_dwordx4 v[234:235], off
	v_lshl_add_u64 v[236:237], s[50:51], 0, v[162:163]
	s_mov_b32 m0, s65
	s_nop 0
	global_load_lds_dwordx4 v[236:237], off
	s_barrier
	s_waitcnt lgkmcnt(0)
	s_setprio 1
	v_mfma_f32_16x16x32_bf16 v[60:63], v[64:67], v[120:123], v[60:63]
	v_mfma_f32_16x16x32_bf16 v[48:51], v[72:75], v[120:123], v[48:51]
	v_mfma_f32_16x16x32_bf16 v[44:47], v[64:67], v[136:139], v[44:47]
	v_mfma_f32_16x16x32_bf16 v[36:39], v[72:75], v[136:139], v[36:39]
	v_mfma_f32_16x16x32_bf16 v[28:31], v[64:67], v[180:183], v[28:31]
	v_mfma_f32_16x16x32_bf16 v[20:23], v[72:75], v[180:183], v[20:23]
	v_mfma_f32_16x16x32_bf16 v[16:19], v[64:67], v[188:191], v[16:19]
	v_mfma_f32_16x16x32_bf16 v[12:15], v[72:75], v[188:191], v[12:15]
	v_mfma_f32_16x16x32_bf16 v[60:63], v[68:71], v[128:131], v[60:63]
	v_mfma_f32_16x16x32_bf16 v[48:51], v[76:79], v[128:131], v[48:51]
	v_mfma_f32_16x16x32_bf16 v[44:47], v[68:71], v[148:151], v[44:47]
	v_mfma_f32_16x16x32_bf16 v[36:39], v[76:79], v[148:151], v[36:39]
	v_mfma_f32_16x16x32_bf16 v[28:31], v[68:71], v[184:187], v[28:31]
	v_mfma_f32_16x16x32_bf16 v[20:23], v[76:79], v[184:187], v[20:23]
	v_mfma_f32_16x16x32_bf16 v[16:19], v[68:71], v[192:195], v[16:19]
	v_mfma_f32_16x16x32_bf16 v[12:15], v[76:79], v[192:195], v[12:15]
	s_barrier
; #define PG8_STAGE(bufoff, gbase, voff) do { _Pragma("unroll") for (int _i = 0; _i < 2; ++_i) \
;     __builtin_amdgcn_global_load_lds((const unsigned*)((const char*)(gbase) + (voff)[_i]), (LAS unsigned*)(lds + (bufoff) + ldsw + _i * 8192), 16, 0, 0); } while (0)
; #define PG8_LDA(dst, b, h) do { _Pragma("unroll") for (int m = 0; m < 4; ++m) _Pragma("unroll") for (int k = 0; k < 2; ++k) dst[m][k] = *(const LAS bf16x8*)(lds + PG8_SA(b, h) + aoff + m * 2048 + k * 1024); } while (0)
; #define PG8_LDB(dst, b, h) do { _Pragma("unroll") for (int n = 0; n < 2; ++n) _Pragma("unroll") for (int k = 0; k < 2; ++k) dst[n][k] = *(const LAS bf16x8*)(lds + PG8_SB(b, h) + boff + n * 2048 + k * 1024); } while (0)
; #define PG8_MMA(ai, bj, At, Bt) do { __builtin_amdgcn_s_setprio(1); _Pragma("unroll") for (int m = 0; m < 4; ++m) _Pragma("unroll") for (int n = 0; n < 2; ++n) _Pragma("unroll") for (int k = 0; k < 2; ++k) \
;     acc[ai][bj][m][n] = __builtin_amdgcn_mfma_f32_16x16x32_bf16(Bt[n][k], At[m][k], acc[ai][bj][m][n], 0, 0, 0); __builtin_amdgcn_s_setprio(0); } while (0)
; #define PG8_WAIT_V(n) asm volatile("s_waitcnt vmcnt(" #n ")" ::: "memory")
; #define PG8_WAIT_L(n) asm volatile("s_waitcnt lgkmcnt(" #n ")" ::: "memory")
; #define PG8_BAR __builtin_amdgcn_s_barrier()
; #define PG8_SCHED __builtin_amdgcn_sched_barrier(0)
; template <class Epi, class Sched = StaticOrder>
; DI void gemm_phase(LAS unsigned char* lds, const Gemm g, const Sched& S, const Epi& E) {
;     ...
;       PG8_STAGE(PG8_SB(0, 1), b2 + hstep, voffB);
;       PG8_WAIT_V(6); PG8_BAR; PG8_MMA(1, 1, At, B1); PG8_BAR;
;       PG8_LDB(B0, 1, 0); PG8_SCHED; PG8_LDA(At, 1, 0); PG8_STAGE(PG8_SA(0, 1), a2 + hstep, voffA);
;       PG8_WAIT_L(8); PG8_BAR; PG8_WAIT_L(0); PG8_MMA(0, 0, At, B0); PG8_BAR; PG8_SCHED;
;       PG8_LDB(B1, 1, 1); PG8_STAGE(PG8_SB(1, 0), b3, voffB);
;       PG8_BAR; PG8_WAIT_L(0); PG8_MMA(0, 1, At, B1); PG8_BAR;
;       PG8_LDA(At, 1, 1); PG8_STAGE(PG8_SA(1, 0), a3, voffA);
	s_setprio 0
	s_add_u32 s78, s48, 0x80000
	s_addc_u32 s79, s49, 0
	s_add_i32 s59, s73, s62
	v_lshl_add_u64 v[64:65], s[78:79], 0, v[164:165]
	s_mov_b32 m0, s59
	s_nop 0
	global_load_lds_dwordx4 v[64:65], off
	v_lshl_add_u64 v[64:65], s[78:79], 0, v[160:161]
	s_add_i32 m0, s59, 0x2000
	s_nop 0
	global_load_lds_dwordx4 v[64:65], off
	s_waitcnt vmcnt(6)
	s_barrier
	s_setprio 1
	v_mfma_f32_16x16x32_bf16 v[56:59], v[206:209], v[120:123], v[56:59]
	v_mfma_f32_16x16x32_bf16 v[52:55], v[216:219], v[120:123], v[52:55]
	v_mfma_f32_16x16x32_bf16 v[40:43], v[206:209], v[136:139], v[40:43]
	v_mfma_f32_16x16x32_bf16 v[32:35], v[216:219], v[136:139], v[32:35]
	v_mfma_f32_16x16x32_bf16 v[24:27], v[206:209], v[180:183], v[24:27]
	v_mfma_f32_16x16x32_bf16 v[8:11], v[216:219], v[180:183], v[8:11]
	v_mfma_f32_16x16x32_bf16 v[4:7], v[206:209], v[188:191], v[4:7]
	v_mfma_f32_16x16x32_bf16 v[0:3], v[216:219], v[188:191], v[0:3]
	v_mfma_f32_16x16x32_bf16 v[56:59], v[212:215], v[128:131], v[56:59]
	v_mfma_f32_16x16x32_bf16 v[52:55], v[220:223], v[128:131], v[52:55]
	v_mfma_f32_16x16x32_bf16 v[40:43], v[212:215], v[148:151], v[40:43]
	v_mfma_f32_16x16x32_bf16 v[32:35], v[220:223], v[148:151], v[32:35]
	v_mfma_f32_16x16x32_bf16 v[24:27], v[212:215], v[184:187], v[24:27]
	v_mfma_f32_16x16x32_bf16 v[8:11], v[220:223], v[184:187], v[8:11]
	v_mfma_f32_16x16x32_bf16 v[4:7], v[212:215], v[192:195], v[4:7]
	v_mfma_f32_16x16x32_bf16 v[0:3], v[220:223], v[192:195], v[0:3]
	s_barrier
	s_setprio 0
	s_add_i32 s59, 0, 0x18000
	v_add_u32_e32 v76, s59, v198
	ds_read_b128 v[64:67], v76
	ds_read_b128 v[68:71], v76 offset:1024
	ds_read_b128 v[72:75], v76 offset:2048
	ds_read_b128 v[76:79], v76 offset:3072
	s_add_u32 s50, s50, 0x80000
	s_addc_u32 s51, s51, 0
	s_mov_b32 m0, s66
	v_lshl_add_u64 v[136:137], s[50:51], 0, v[166:167]
	ds_read_b128 v[120:123], v202 offset:32768
	ds_read_b128 v[128:131], v202 offset:33792
	ds_read_b128 v[180:183], v202 offset:34816
	ds_read_b128 v[184:187], v202 offset:35840
	ds_read_b128 v[188:191], v202 offset:36864
	ds_read_b128 v[192:195], v202 offset:37888
	ds_read_b128 v[206:209], v202 offset:38912
	ds_read_b128 v[212:215], v202 offset:39936
	global_load_lds_dwordx4 v[136:137], off
	v_lshl_add_u64 v[136:137], s[50:51], 0, v[162:163]
	s_mov_b32 m0, s67
	s_nop 0
	global_load_lds_dwordx4 v[136:137], off
	s_waitcnt lgkmcnt(8)
	s_barrier
	s_waitcnt lgkmcnt(0)
	s_setprio 1
	v_mfma_f32_16x16x32_bf16 v[136:139], v[64:67], v[120:123], v[156:159]
	v_mfma_f32_16x16x32_bf16 v[156:159], v[68:71], v[128:131], v[136:139]
	v_mfma_f32_16x16x32_bf16 v[136:139], v[72:75], v[120:123], v[144:147]
	v_mfma_f32_16x16x32_bf16 v[144:147], v[76:79], v[128:131], v[136:139]
	v_mfma_f32_16x16x32_bf16 v[136:139], v[64:67], v[180:183], v[140:143]
	v_mfma_f32_16x16x32_bf16 v[132:135], v[72:75], v[180:183], v[132:135]
	v_mfma_f32_16x16x32_bf16 v[124:127], v[64:67], v[188:191], v[124:127]
	v_mfma_f32_16x16x32_bf16 v[116:119], v[72:75], v[188:191], v[116:119]
	v_mfma_f32_16x16x32_bf16 v[112:115], v[64:67], v[206:209], v[112:115]
	v_mfma_f32_16x16x32_bf16 v[108:111], v[72:75], v[206:209], v[108:111]
	v_mfma_f32_16x16x32_bf16 v[140:143], v[68:71], v[184:187], v[136:139]
	v_mfma_f32_16x16x32_bf16 v[132:135], v[76:79], v[184:187], v[132:135]
	v_mfma_f32_16x16x32_bf16 v[124:127], v[68:71], v[192:195], v[124:127]
	v_mfma_f32_16x16x32_bf16 v[116:119], v[76:79], v[192:195], v[116:119]
	v_mfma_f32_16x16x32_bf16 v[112:115], v[68:71], v[212:215], v[112:115]
	v_mfma_f32_16x16x32_bf16 v[108:111], v[76:79], v[212:215], v[108:111]
	s_barrier
	s_setprio 0
	s_add_i32 s50, 0, 0x1c000
	v_add_u32_e32 v136, s50, v198
	s_add_i32 s51, s59, s62
	ds_read_b128 v[216:219], v136
	ds_read_b128 v[220:223], v136 offset:1024
	ds_read_b128 v[224:227], v136 offset:2048
	ds_read_b128 v[228:231], v136 offset:3072
	v_lshl_add_u64 v[136:137], v[196:197], 0, s[28:29]
	s_mov_b32 m0, s51
	s_nop 0
	global_load_lds_dwordx4 v[136:137], off
	v_lshl_add_u64 v[136:137], v[232:233], 0, s[28:29]
	s_add_i32 m0, s51, 0x2000
	s_nop 0
	global_load_lds_dwordx4 v[136:137], off
	s_barrier
	s_waitcnt lgkmcnt(0)
	s_setprio 1
	v_mfma_f32_16x16x32_bf16 v[80:83], v[224:227], v[120:123], v[80:83]
	v_mfma_f32_16x16x32_bf16 v[136:139], v[216:219], v[120:123], v[152:155]
	v_mfma_f32_16x16x32_bf16 v[148:151], v[228:231], v[128:131], v[80:83]
	v_mfma_f32_16x16x32_bf16 v[80:83], v[216:219], v[180:183], v[84:87]
	v_mfma_f32_16x16x32_bf16 v[152:155], v[220:223], v[128:131], v[136:139]
	v_mfma_f32_16x16x32_bf16 v[136:139], v[220:223], v[184:187], v[80:83]
	v_mfma_f32_16x16x32_bf16 v[80:83], v[224:227], v[180:183], v[88:91]
	v_mfma_f32_16x16x32_bf16 v[128:131], v[228:231], v[184:187], v[80:83]
	v_mfma_f32_16x16x32_bf16 v[80:83], v[216:219], v[188:191], v[92:95]
	v_mfma_f32_16x16x32_bf16 v[120:123], v[220:223], v[192:195], v[80:83]
	v_mfma_f32_16x16x32_bf16 v[80:83], v[224:227], v[188:191], v[104:107]
	v_mfma_f32_16x16x32_bf16 v[104:107], v[228:231], v[192:195], v[80:83]
	v_mfma_f32_16x16x32_bf16 v[80:83], v[216:219], v[206:209], v[100:103]
	v_mfma_f32_16x16x32_bf16 v[100:103], v[220:223], v[212:215], v[80:83]
	v_mfma_f32_16x16x32_bf16 v[80:83], v[224:227], v[206:209], v[96:99]
	v_mfma_f32_16x16x32_bf16 v[96:99], v[228:231], v[212:215], v[80:83]
	s_barrier
	s_setprio 0
	s_mov_b32 m0, s55
	v_lshl_add_u64 v[196:197], v[234:235], 0, s[28:29]
	s_nop 2
	ds_read_b128 v[80:83], v202 offset:49152
	ds_read_b128 v[84:87], v202 offset:50176
	ds_read_b128 v[88:91], v202 offset:51200
	ds_read_b128 v[92:95], v202 offset:52224
	ds_read_b128 v[180:183], v202 offset:53248
	ds_read_b128 v[184:187], v202 offset:54272
	ds_read_b128 v[188:191], v202 offset:55296
	ds_read_b128 v[192:195], v202 offset:56320
	global_load_lds_dwordx4 v[196:197], off
	v_lshl_add_u64 v[196:197], v[236:237], 0, s[28:29]
	s_mov_b32 m0, s68
	s_nop 0
	global_load_lds_dwordx4 v[196:197], off
	s_barrier
; #define PG8_STAGE(bufoff, gbase, voff) do { _Pragma("unroll") for (int _i = 0; _i < 2; ++_i) \
;     __builtin_amdgcn_global_load_lds((const unsigned*)((const char*)(gbase) + (voff)[_i]), (LAS unsigned*)(lds + (bufoff) + ldsw + _i * 8192), 16, 0, 0); } while (0)
; #define PG8_LDA(dst, b, h) do { _Pragma("unroll") for (int m = 0; m < 4; ++m) _Pragma("unroll") for (int k = 0; k < 2; ++k) dst[m][k] = *(const LAS bf16x8*)(lds + PG8_SA(b, h) + aoff + m * 2048 + k * 1024); } while (0)
; #define PG8_MMA(ai, bj, At, Bt) do { __builtin_amdgcn_s_setprio(1); _Pragma("unroll") for (int m = 0; m < 4; ++m) _Pragma("unroll") for (int n = 0; n < 2; ++n) _Pragma("unroll") for (int k = 0; k < 2; ++k) \
;     acc[ai][bj][m][n] = __builtin_amdgcn_mfma_f32_16x16x32_bf16(Bt[n][k], At[m][k], acc[ai][bj][m][n], 0, 0, 0); __builtin_amdgcn_s_setprio(0); } while (0)
; #define PG8_WAIT_V(n) asm volatile("s_waitcnt vmcnt(" #n ")" ::: "memory")
; #define PG8_WAIT_L(n) asm volatile("s_waitcnt lgkmcnt(" #n ")" ::: "memory")
; #define PG8_BAR __builtin_amdgcn_s_barrier()
; #define PG8_SCHED __builtin_amdgcn_sched_barrier(0)
;   DI void operator()(const f32x4 (&acc)[2][2][4][2], const Unit& u, int wr, int wc, int fr, int fq) const {
;     const int col = u.pn * 128 + wc * 32 + 8 * fq;
;     float w0[8], w1[8], w2[8], bb[8];
; #pragma unroll
;     for (int e = 0; e < 8; ++e) { w0[e] = cw[col + e]; w1[e] = cw[5632 + col + e]; w2[e] = cw[2 * 5632 + col + e]; bb[e] = cb[col + e]; }
; #pragma unroll
;     for (int ai = 0; ai < 2; ++ai) {
;       const int row0 = u.pm * BM + ai * HALF + wr * 64, span = row0 >> 6;
;       float rsv[4];
; #pragma unroll
;       for (int m = 0; m < 4; ++m) rsv[m] = row_rstd(ssq, row0 + 16 * m + fr, fq);
; template <class Epi, class Sched = StaticOrder>
; DI void gemm_phase(LAS unsigned char* lds, const Gemm g, const Sched& S, const Epi& E) {
;     ...
;       PG8_LDA(At, 1, 1); PG8_STAGE(PG8_SA(1, 0), a3, voffA);
;       PG8_BAR; PG8_WAIT_L(0); PG8_MMA(1, 0, At, B0); PG8_BAR; PG8_SCHED;
;       PG8_STAGE(PG8_SB(1, 1), b3 + hstep, voffB);
;       PG8_WAIT_V(6); PG8_BAR; PG8_MMA(1, 1, At, B1); PG8_BAR;
	s_waitcnt lgkmcnt(0)
	s_setprio 1
	v_mfma_f32_16x16x32_bf16 v[60:63], v[64:67], v[80:83], v[60:63]
	v_mfma_f32_16x16x32_bf16 v[48:51], v[72:75], v[80:83], v[48:51]
	v_mfma_f32_16x16x32_bf16 v[44:47], v[64:67], v[88:91], v[44:47]
	v_mfma_f32_16x16x32_bf16 v[36:39], v[72:75], v[88:91], v[36:39]
	v_mfma_f32_16x16x32_bf16 v[28:31], v[64:67], v[180:183], v[28:31]
	v_mfma_f32_16x16x32_bf16 v[20:23], v[72:75], v[180:183], v[20:23]
	v_mfma_f32_16x16x32_bf16 v[16:19], v[64:67], v[188:191], v[16:19]
	v_mfma_f32_16x16x32_bf16 v[12:15], v[72:75], v[188:191], v[12:15]
	v_mfma_f32_16x16x32_bf16 v[60:63], v[68:71], v[84:87], v[60:63]
	v_mfma_f32_16x16x32_bf16 v[48:51], v[76:79], v[84:87], v[48:51]
	v_mfma_f32_16x16x32_bf16 v[44:47], v[68:71], v[92:95], v[44:47]
	v_mfma_f32_16x16x32_bf16 v[36:39], v[76:79], v[92:95], v[36:39]
	v_mfma_f32_16x16x32_bf16 v[28:31], v[68:71], v[184:187], v[28:31]
	v_mfma_f32_16x16x32_bf16 v[20:23], v[76:79], v[184:187], v[20:23]
	v_mfma_f32_16x16x32_bf16 v[16:19], v[68:71], v[192:195], v[16:19]
	v_mfma_f32_16x16x32_bf16 v[12:15], v[76:79], v[192:195], v[12:15]
	s_barrier
	s_setprio 0
	s_add_u32 s48, s48, 0x80080
	s_addc_u32 s49, s49, 0
	s_add_i32 s50, s50, s62
	v_lshl_add_u64 v[64:65], s[48:49], 0, v[164:165]
	s_mov_b32 m0, s50
	s_nop 0
	global_load_lds_dwordx4 v[64:65], off
	v_lshl_add_u64 v[64:65], s[48:49], 0, v[160:161]
	s_add_i32 m0, s50, 0x2000
	s_nop 0
	global_load_lds_dwordx4 v[64:65], off
	s_waitcnt vmcnt(6)
	s_barrier
	s_setprio 1
	v_mfma_f32_16x16x32_bf16 v[56:59], v[216:219], v[80:83], v[56:59]
	v_mfma_f32_16x16x32_bf16 v[52:55], v[224:227], v[80:83], v[52:55]
	v_mfma_f32_16x16x32_bf16 v[40:43], v[216:219], v[88:91], v[40:43]
	v_mfma_f32_16x16x32_bf16 v[32:35], v[224:227], v[88:91], v[32:35]
	v_mfma_f32_16x16x32_bf16 v[24:27], v[216:219], v[180:183], v[24:27]
	v_mfma_f32_16x16x32_bf16 v[8:11], v[224:227], v[180:183], v[8:11]
	v_mfma_f32_16x16x32_bf16 v[4:7], v[216:219], v[188:191], v[4:7]
	v_mfma_f32_16x16x32_bf16 v[0:3], v[224:227], v[188:191], v[0:3]
	v_mfma_f32_16x16x32_bf16 v[56:59], v[220:223], v[84:87], v[56:59]
	v_mfma_f32_16x16x32_bf16 v[52:55], v[228:231], v[84:87], v[52:55]
	v_mfma_f32_16x16x32_bf16 v[40:43], v[220:223], v[92:95], v[40:43]
	v_mfma_f32_16x16x32_bf16 v[32:35], v[228:231], v[92:95], v[32:35]
	v_mfma_f32_16x16x32_bf16 v[24:27], v[220:223], v[184:187], v[24:27]
	v_mfma_f32_16x16x32_bf16 v[8:11], v[228:231], v[184:187], v[8:11]
	v_mfma_f32_16x16x32_bf16 v[4:7], v[220:223], v[192:195], v[4:7]
	v_mfma_f32_16x16x32_bf16 v[0:3], v[228:231], v[192:195], v[0:3]
	s_add_i32 s58, s58, 2
	s_add_u32 s14, s14, 0x100
	s_addc_u32 s15, s15, 0
	s_add_u32 s52, s52, 0x100
	s_addc_u32 s53, s53, 0
	s_cmp_gt_u32 s58, 29
	s_barrier
	s_setprio 0
	s_cbranch_scc0 .LBB0_1277
	s_lshl_b32 s39, s12, 8
	s_add_i32 s39, s39, s54
	v_or_b32_e32 v190, s39, v179
	v_ashrrev_i32_e32 v191, 31, v190
	v_lshlrev_b64 v[64:65], 7, v[190:191]
	v_or_b32_e32 v188, 16, v190
	v_lshl_add_u64 v[64:65], v[168:169], 0, v[64:65]
	v_ashrrev_i32_e32 v189, 31, v188
	global_load_dwordx4 v[192:195], v[64:65], off
	global_load_dwordx4 v[206:209], v[64:65], off offset:16
	v_lshlrev_b64 v[64:65], 7, v[188:189]
	v_lshl_add_u64 v[64:65], v[168:169], 0, v[64:65]
	global_load_dwordx4 v[212:215], v[64:65], off
	global_load_dwordx4 v[216:219], v[64:65], off offset:16
	v_or_b32_e32 v186, 32, v190
	v_ashrrev_i32_e32 v187, 31, v186
	v_lshlrev_b64 v[64:65], 7, v[186:187]
	v_or_b32_e32 v184, 48, v190
	v_lshl_add_u64 v[64:65], v[168:169], 0, v[64:65]
	v_ashrrev_i32_e32 v185, 31, v184
	global_load_dwordx4 v[220:223], v[64:65], off
	global_load_dwordx4 v[224:227], v[64:65], off offset:16
	v_lshlrev_b64 v[64:65], 7, v[184:185]
	v_lshl_add_u64 v[64:65], v[168:169], 0, v[64:65]
	global_load_dwordx4 v[228:231], v[64:65], off
	global_load_dwordx4 v[232:235], v[64:65], off offset:16
	v_lshl_or_b32 v180, s13, 7, v200
	v_and_b32_e32 v65, 64, v204
	v_xor_b32_e32 v64, 16, v204
	v_ashrrev_i32_e32 v181, 31, v180
	v_add_u32_e32 v65, 64, v65
	v_xor_b32_e32 v66, 32, v204
	v_lshlrev_b64 v[182:183], 2, v[180:181]
	v_cmp_lt_i32_e32 vcc, v64, v65
	v_lshl_add_u64 v[88:89], s[16:17], 0, v[182:183]
	v_lshl_add_u64 v[72:73], s[18:19], 0, v[182:183]
	v_cndmask_b32_e32 v64, v204, v64, vcc
	v_cmp_lt_i32_e32 vcc, v66, v65
	v_lshl_add_u64 v[74:75], v[88:89], 0, s[30:31]
	v_lshl_add_u64 v[76:77], v[88:89], 0, s[34:35]
	v_cndmask_b32_e32 v65, v204, v66, vcc
	v_add_co_u32_e32 v90, vcc, 0x5000, v88
	v_lshlrev_b32_e32 v187, 2, v64
	s_nop 0
	v_addc_co_u32_e32 v91, vcc, 0, v89, vcc
	v_add_co_u32_e32 v92, vcc, 0xb000, v88
	v_lshlrev_b32_e32 v185, 2, v65
	s_nop 0
	v_addc_co_u32_e32 v93, vcc, 0, v89, vcc
	global_load_dwordx4 v[64:67], v[88:89], off offset:16
	global_load_dwordx4 v[80:83], v[88:89], off
	global_load_dwordx4 v[68:71], v[72:73], off offset:16
	global_load_dwordx4 v[84:87], v[72:73], off
	s_nop 0
	global_load_dwordx4 v[72:75], v[74:75], off offset:16
	s_nop 0
	global_load_dwordx4 v[76:79], v[76:77], off offset:16
	s_nop 0
	global_load_dwordx4 v[88:91], v[90:91], off offset:2048
	s_nop 0
	global_load_dwordx4 v[92:95], v[92:93], off
	v_mov_b32_e32 v211, 0
	v_mov_b32_e32 v205, 0
	s_waitcnt vmcnt(0)
	v_mov_b32_e32 v196, v192
	v_mov_b32_e32 v197, v206
	v_mov_b32_e32 v206, v193
	v_mov_b32_e32 v192, v194
	v_mov_b32_e32 v193, v208
	v_mov_b32_e32 v208, v195
	v_pk_add_f32 v[194:195], v[196:197], v[206:207]
	v_pk_add_f32 v[192:193], v[192:193], v[208:209]
	v_mov_b32_e32 v196, v212
	v_mov_b32_e32 v197, v216
	v_mov_b32_e32 v216, v213
	v_mov_b32_e32 v206, v214
	v_mov_b32_e32 v207, v218
	v_mov_b32_e32 v218, v215
	v_pk_add_f32 v[192:193], v[194:195], v[192:193]
	v_pk_add_f32 v[194:195], v[196:197], v[216:217]
	v_pk_add_f32 v[196:197], v[206:207], v[218:219]
	v_mov_b32_e32 v208, v220
	v_pk_add_f32 v[194:195], v[194:195], v[196:197]
	v_mov_b32_e32 v197, v192
	v_mov_b32_e32 v196, v194
	v_mov_b32_e32 v192, v195
	v_pk_add_f32 v[192:193], v[196:197], v[192:193]
	ds_bpermute_b32 v195, v187, v193
	ds_bpermute_b32 v194, v187, v192
	v_mov_b32_e32 v209, v224
	v_mov_b32_e32 v224, v221
	v_mov_b32_e32 v212, v222
	v_mov_b32_e32 v213, v226
	s_waitcnt lgkmcnt(0)
; DI unsigned pack2(float lo, float hi) { f32x2 v = {lo, hi}; bf16v2 r = __builtin_convertvector(v, bf16v2); return __builtin_bit_cast(unsigned, r); }
; DI float silu_f(float x) { return x * sigmoid_f(x); }
; DI float dpp_ror1(float v) { return __int_as_float(__builtin_amdgcn_update_dpp(0, __float_as_int(v), 0x121, 0xf, 0xf, false)); }
; DI float dpp_ror2(float v) { return __int_as_float(__builtin_amdgcn_update_dpp(0, __float_as_int(v), 0x122, 0xf, 0xf, false)); }
;   DI void operator()(const f32x4 (&acc)[2][2][4][2], const Unit& u, int wr, int wc, int fr, int fq) const {
;     ...
;       for (int m = 0; m < 4; ++m) rsv[m] = row_rstd(ssq, row0 + 16 * m + fr, fq);
;       float p1[8], p2[8];
; #pragma unroll
;       for (int e = 0; e < 8; ++e) { p1[e] = 0.f; p2[e] = 0.f; }
; #pragma unroll
;       for (int m = 0; m < 4; ++m) {
;         float g[8], uu[8], a[8];
;         const float rs = rsv[m];
; #pragma unroll
;         for (int e = 0; e < 4; ++e) { g[e] = acc[ai][0][m][0][e] * rs; g[4 + e] = acc[ai][0][m][1][e] * rs; uu[e] = acc[ai][1][m][0][e] * rs; uu[4 + e] = acc[ai][1][m][1][e] * rs; }
; #pragma unroll
;         for (int e = 0; e < 8; ++e) {
;           const float x1 = dpp_ror1(g[e]), x2 = dpp_ror2(g[e]);
;           const float pr1 = (fr == 0) ? p1[e] : x1, pr2 = (fr < 2) ? p2[e] : x2;
;           a[e] = w2[e] * g[e] + w1[e] * pr1 + w0[e] * pr2 + bb[e];
;           p1[e] = x1; p2[e] = x2;
;         }
;         if (m == 0 && fr < 2) {
;           float* ha = headA + (size_t)(span * 2 + fr) * 5632 + col; float* hu = headU + (size_t)(span * 2 + fr) * 5632 + col;
;           *(f32x4*)ha = (f32x4){a[0], a[1], a[2], a[3]}; *(f32x4*)(ha + 4) = (f32x4){a[4], a[5], a[6], a[7]};
;           *(f32x4*)hu = (f32x4){uu[0], uu[1], uu[2], uu[3]}; *(f32x4*)(hu + 4) = (f32x4){uu[4], uu[5], uu[6], uu[7]};
;         } else {
;           u32x4 w;
;           w.x = pack2(silu_f(a[0]) * uu[0], silu_f(a[1]) * uu[1]);
;           w.y = pack2(silu_f(a[2]) * uu[2], silu_f(a[3]) * uu[3]);
;           w.z = pack2(silu_f(a[4]) * uu[4], silu_f(a[5]) * uu[5]);
;           w.w = pack2(silu_f(a[6]) * uu[6], silu_f(a[7]) * uu[7]);
;           *(u32x4*)(H + (size_t)(row0 + 16 * m + fr) * 5632 + col) = w;
	v_pk_add_f32 v[192:193], v[192:193], v[194:195]
	ds_bpermute_b32 v195, v185, v193
	ds_bpermute_b32 v194, v185, v192
	v_mov_b32_e32 v226, v223
	v_mov_b32_e32 v196, v228
	v_mov_b32_e32 v197, v232
	v_mov_b32_e32 v232, v229
	s_waitcnt lgkmcnt(0)
	v_pk_add_f32 v[192:193], v[192:193], v[194:195]
	v_mov_b32_e32 v206, v230
	v_pk_fma_f32 v[192:193], v[192:193], s[36:37], v[178:179] op_sel_hi:[1,0,0]
	v_mov_b32_e32 v207, v234
	v_mul_f32_e32 v189, 0x4b800000, v193
	v_cmp_gt_f32_e64 s[12:13], s74, v193
	v_mov_b32_e32 v234, v231
	v_pk_add_f32 v[208:209], v[208:209], v[224:225]
	v_cndmask_b32_e64 v189, v193, v189, s[12:13]
	v_rsq_f32_e32 v189, v189
	v_pk_add_f32 v[212:213], v[212:213], v[226:227]
	v_pk_add_f32 v[196:197], v[196:197], v[232:233]
	v_pk_add_f32 v[194:195], v[206:207], v[234:235]
	v_mul_f32_e32 v191, 0x45800000, v189
	v_cndmask_b32_e64 v220, v189, v191, s[12:13]
	v_pk_add_f32 v[208:209], v[208:209], v[212:213]
	v_pk_add_f32 v[194:195], v[196:197], v[194:195]
	v_pk_mul_f32 v[156:157], v[156:157], v[220:221] op_sel_hi:[1,0]
	v_mov_b32_e32 v216, 0
	v_mov_b32_e32 v218, 0
	v_mov_b32_e32 v196, v194
	v_mov_b32_e32 v197, v208
	v_mov_b32_e32 v208, v195
	v_mov_b32_dpp v216, v156 row_ror:1 row_mask:0xf bank_mask:0xf
	v_mov_b32_dpp v218, v157 row_ror:1 row_mask:0xf bank_mask:0xf
	v_pk_add_f32 v[194:195], v[196:197], v[208:209]
	v_cndmask_b32_e64 v207, v218, 0, s[0:1]
	v_cndmask_b32_e64 v206, v216, 0, s[0:1]
	v_pk_mul_f32 v[158:159], v[158:159], v[220:221] op_sel_hi:[1,0]
	v_mov_b32_e32 v212, 0
	v_mov_b32_e32 v214, 0
	ds_bpermute_b32 v197, v187, v195
	ds_bpermute_b32 v196, v187, v194
	v_mov_b32_e32 v215, 0
	v_mov_b32_e32 v217, 0
	v_pk_mul_f32 v[206:207], v[88:89], v[206:207]
	v_mov_b32_dpp v212, v158 row_ror:1 row_mask:0xf bank_mask:0xf
	v_mov_b32_dpp v214, v159 row_ror:1 row_mask:0xf bank_mask:0xf
	v_mov_b32_dpp v215, v156 row_ror:2 row_mask:0xf bank_mask:0xf
	v_mov_b32_dpp v217, v157 row_ror:2 row_mask:0xf bank_mask:0xf
	v_pk_fma_f32 v[156:157], v[92:93], v[156:157], v[206:207]
	v_mov_b32_e32 v213, 0
	v_cndmask_b32_e64 v207, v214, 0, s[0:1]
	v_cndmask_b32_e64 v206, v212, 0, s[0:1]
	v_cndmask_b32_e64 v209, v217, 0, s[4:5]
	v_cndmask_b32_e64 v208, v215, 0, s[4:5]
	v_mov_b32_dpp v211, v158 row_ror:2 row_mask:0xf bank_mask:0xf
	v_mov_b32_dpp v213, v159 row_ror:2 row_mask:0xf bank_mask:0xf
	v_pk_mul_f32 v[206:207], v[90:91], v[206:207]
	v_pk_fma_f32 v[156:157], v[80:81], v[208:209], v[156:157]
	v_cndmask_b32_e64 v209, v213, 0, s[4:5]
	v_cndmask_b32_e64 v208, v211, 0, s[4:5]
	v_pk_fma_f32 v[158:159], v[94:95], v[158:159], v[206:207]
	v_pk_mul_f32 v[144:145], v[144:145], v[220:221] op_sel_hi:[1,0]
	v_pk_fma_f32 v[158:159], v[82:83], v[208:209], v[158:159]
	v_mov_b32_e32 v207, 0
	v_mov_b32_e32 v209, 0
	v_pk_mul_f32 v[146:147], v[146:147], v[220:221] op_sel_hi:[1,0]
	v_mov_b32_e32 v191, 0
	s_waitcnt lgkmcnt(0)
	v_pk_add_f32 v[194:195], v[194:195], v[196:197]
	v_mov_b32_dpp v207, v144 row_ror:1 row_mask:0xf bank_mask:0xf
	v_mov_b32_dpp v209, v145 row_ror:1 row_mask:0xf bank_mask:0xf
	v_mov_b32_dpp v191, v146 row_ror:1 row_mask:0xf bank_mask:0xf
	v_mov_b32_dpp v205, v147 row_ror:1 row_mask:0xf bank_mask:0xf
	ds_bpermute_b32 v197, v185, v195
	ds_bpermute_b32 v196, v185, v194
	v_pk_mul_f32 v[152:153], v[152:153], v[220:221] op_sel_hi:[1,0]
	v_pk_mul_f32 v[148:149], v[148:149], v[220:221] op_sel_hi:[1,0]
	v_pk_mul_f32 v[154:155], v[154:155], v[220:221] op_sel_hi:[1,0]
	v_pk_mul_f32 v[150:151], v[150:151], v[220:221] op_sel_hi:[1,0]
	v_mov_b32_e32 v206, 0
	v_mov_b32_e32 v208, 0
	v_cndmask_b32_e64 v223, v209, 0, s[0:1]
	v_cndmask_b32_e64 v222, v207, 0, s[0:1]
	v_mov_b32_e32 v189, 0
	v_mov_b32_e32 v193, 0
	v_cndmask_b32_e64 v221, v205, 0, s[0:1]
	v_cndmask_b32_e64 v220, v191, 0, s[0:1]
	v_mov_b32_dpp v206, v144 row_ror:2 row_mask:0xf bank_mask:0xf
	v_mov_b32_dpp v208, v145 row_ror:2 row_mask:0xf bank_mask:0xf
	v_pk_mul_f32 v[222:223], v[72:73], v[222:223]
	v_mov_b32_dpp v189, v146 row_ror:2 row_mask:0xf bank_mask:0xf
	v_mov_b32_dpp v193, v147 row_ror:2 row_mask:0xf bank_mask:0xf
	v_pk_mul_f32 v[220:221], v[74:75], v[220:221]
	v_cndmask_b32_e64 v225, v208, 0, s[4:5]
	v_cndmask_b32_e64 v224, v206, 0, s[4:5]
	v_pk_fma_f32 v[144:145], v[76:77], v[144:145], v[222:223]
	v_cndmask_b32_e64 v223, v193, 0, s[4:5]
	v_cndmask_b32_e64 v222, v189, 0, s[4:5]
	v_pk_fma_f32 v[146:147], v[78:79], v[146:147], v[220:221]
	v_pk_fma_f32 v[144:145], v[64:65], v[224:225], v[144:145]
	v_pk_fma_f32 v[146:147], v[66:67], v[222:223], v[146:147]
	v_cmp_gt_f32_e32 vcc, s74, v192
	v_pk_add_f32 v[156:157], v[84:85], v[156:157]
	v_pk_add_f32 v[158:159], v[86:87], v[158:159]
	v_pk_add_f32 v[144:145], v[68:69], v[144:145]
	v_pk_add_f32 v[146:147], v[70:71], v[146:147]
	s_and_saveexec_b64 s[12:13], s[10:11]
	s_xor_b64 s[12:13], exec, s[12:13]
	s_cbranch_execz .LBB0_1280
	v_mul_f32_e32 v219, 0xbfb8aa3b, v156
	v_exp_f32_e32 v219, v219
	v_mul_f32_e32 v220, 0xbfb8aa3b, v157
	v_exp_f32_e32 v220, v220
	v_mul_f32_e32 v222, 0xbfb8aa3b, v159
	v_add_f32_e32 v219, 1.0, v219
	v_exp_f32_e32 v223, v222
	v_add_f32_e32 v221, 1.0, v220
	v_rcp_f32_e32 v220, v219
	v_mul_f32_e32 v219, 0xbfb8aa3b, v158
	v_exp_f32_e32 v219, v219
	v_rcp_f32_e32 v221, v221
	v_add_f32_e32 v219, 1.0, v219
	v_rcp_f32_e32 v222, v219
	v_add_f32_e32 v219, 1.0, v223
	v_rcp_f32_e32 v223, v219
	v_pk_mul_f32 v[156:157], v[156:157], v[220:221]
	s_nop 0
	v_pk_mul_f32 v[152:153], v[152:153], v[156:157]
	v_pk_mul_f32 v[156:157], v[158:159], v[222:223]
	v_cvt_pk_bf16_f32 v152, v152, v153
	v_mul_f32_e32 v153, 0xbfb8aa3b, v144
	v_pk_mul_f32 v[154:155], v[154:155], v[156:157]
	v_exp_f32_e32 v156, v153
	v_mul_f32_e32 v153, 0xbfb8aa3b, v145
	v_exp_f32_e32 v157, v153
	v_cvt_pk_bf16_f32 v153, v154, v155
	v_add_f32_e32 v154, 1.0, v156
	v_mul_f32_e32 v156, 0xbfb8aa3b, v146
	v_add_f32_e32 v155, 1.0, v157
	v_mul_f32_e32 v157, 0xbfb8aa3b, v147
	v_exp_f32_e32 v156, v156
	v_exp_f32_e32 v157, v157
	v_rcp_f32_e32 v154, v154
	v_rcp_f32_e32 v155, v155
	v_add_f32_e32 v156, 1.0, v156
	v_add_f32_e32 v157, 1.0, v157
	v_rcp_f32_e32 v156, v156
	v_rcp_f32_e32 v157, v157
	v_pk_mul_f32 v[144:145], v[144:145], v[154:155]
	s_nop 0
	v_pk_mul_f32 v[144:145], v[148:149], v[144:145]
	s_nop 0
	v_cvt_pk_bf16_f32 v154, v144, v145
	v_pk_mul_f32 v[144:145], v[146:147], v[156:157]
	s_nop 0
	v_pk_mul_f32 v[144:145], v[150:151], v[144:145]
	s_nop 0
	v_cvt_pk_bf16_f32 v155, v144, v145
	v_mov_b64_e32 v[144:145], s[20:21]
	v_mad_i64_i32 v[144:145], s[14:15], v190, s75, v[144:145]
	v_lshl_add_u64 v[144:145], v[180:181], 1, v[144:145]
	global_store_dwordx4 v[144:145], v[152:155], off

; #define PG8_STAGE(bufoff, gbase, voff) do { _Pragma("unroll") for (int _i = 0; _i < 2; ++_i) \
;     __builtin_amdgcn_global_load_lds((const unsigned*)((const char*)(gbase) + (voff)[_i]), (LAS unsigned*)(lds + (bufoff) + ldsw + _i * 8192), 16, 0, 0); } while (0)
; #define PG8_LDA(dst, b, h) do { _Pragma("unroll") for (int m = 0; m < 4; ++m) _Pragma("unroll") for (int k = 0; k < 2; ++k) dst[m][k] = *(const LAS bf16x8*)(lds + PG8_SA(b, h) + aoff + m * 2048 + k * 1024); } while (0)
; #define PG8_LDB(dst, b, h) do { _Pragma("unroll") for (int n = 0; n < 2; ++n) _Pragma("unroll") for (int k = 0; k < 2; ++k) dst[n][k] = *(const LAS bf16x8*)(lds + PG8_SB(b, h) + boff + n * 2048 + k * 1024); } while (0)
; #define PG8_MMA(ai, bj, At, Bt) do { __builtin_amdgcn_s_setprio(1); _Pragma("unroll") for (int m = 0; m < 4; ++m) _Pragma("unroll") for (int n = 0; n < 2; ++n) _Pragma("unroll") for (int k = 0; k < 2; ++k) \
;     acc[ai][bj][m][n] = __builtin_amdgcn_mfma_f32_16x16x32_bf16(Bt[n][k], At[m][k], acc[ai][bj][m][n], 0, 0, 0); __builtin_amdgcn_s_setprio(0); } while (0)
; #define PG8_WAIT_V(n) asm volatile("s_waitcnt vmcnt(" #n ")" ::: "memory")
; #define PG8_WAIT_L(n) asm volatile("s_waitcnt lgkmcnt(" #n ")" ::: "memory")
; #define PG8_BAR __builtin_amdgcn_s_barrier()
; #define PG8_SCHED __builtin_amdgcn_sched_barrier(0)
; template <class Epi, class Sched = StaticOrder>
; DI void gemm_phase(LAS unsigned char* lds, const Gemm g, const Sched& S, const Epi& E) {
;     ...
;       PG8_LDB(B0, 0, 0); PG8_SCHED; PG8_LDA(At, 0, 0); PG8_STAGE(PG8_SA(1, 1), a1 + hstep, voffA);
;       PG8_WAIT_L(8); PG8_BAR; PG8_WAIT_L(0); PG8_MMA(0, 0, At, B0); PG8_BAR; PG8_SCHED;
;       PG8_LDB(B1, 0, 1); PG8_STAGE(PG8_SB(0, 0), b2, voffB);
;       PG8_BAR; PG8_WAIT_L(0); PG8_MMA(0, 1, At, B1); PG8_BAR;
;       PG8_LDA(At, 0, 1); PG8_STAGE(PG8_SA(0, 0), a2, voffA);
;       PG8_BAR; PG8_WAIT_L(0); PG8_MMA(1, 0, At, B0); PG8_BAR; PG8_SCHED;
;       PG8_STAGE(PG8_SB(0, 1), b2 + hstep, voffB);
;       PG8_WAIT_V(6); PG8_BAR; PG8_MMA(1, 1, At, B1); PG8_BAR;
.LBB0_1424:
	ds_read_b128 v[144:147], v159
	ds_read_b128 v[148:151], v159 offset:1024
	ds_read_b128 v[152:155], v159 offset:2048
	ds_read_b128 v[162:165], v159 offset:3072
	s_add_u32 s18, s16, 0xffea0080
	s_addc_u32 s19, s17, -1
	s_cmpk_eq_i32 s47, 0x54
	s_cselect_b32 s21, s3, s19
	s_cselect_b32 s20, s2, s18
	s_cselect_b32 s19, s5, s46
	s_cselect_b32 s18, s4, s45
	v_lshl_add_u64 v[198:199], s[16:17], 0, v[136:137]
	s_add_i32 m0, s30, 0xc000
	ds_read_b128 v[166:169], v160
	ds_read_b128 v[170:173], v160 offset:1024
	ds_read_b128 v[174:177], v160 offset:2048
	ds_read_b128 v[178:181], v160 offset:3072
	ds_read_b128 v[182:185], v160 offset:4096
	ds_read_b128 v[186:189], v160 offset:5120
	ds_read_b128 v[190:193], v160 offset:6144
	ds_read_b128 v[194:197], v160 offset:7168
	global_load_lds_dwordx4 v[198:199], off
	v_lshl_add_u64 v[198:199], s[16:17], 0, v[138:139]
	s_add_i32 m0, s30, 0xe000
	s_nop 0
	global_load_lds_dwordx4 v[198:199], off
	s_waitcnt lgkmcnt(8)
	s_barrier
	s_waitcnt lgkmcnt(0)
	s_setprio 1
	v_mfma_f32_16x16x32_bf16 v[124:127], v[144:147], v[166:169], v[124:127]
	v_mfma_f32_16x16x32_bf16 v[120:123], v[152:155], v[166:169], v[120:123]
	v_mfma_f32_16x16x32_bf16 v[116:119], v[144:147], v[174:177], v[116:119]
	v_mfma_f32_16x16x32_bf16 v[112:115], v[152:155], v[174:177], v[112:115]
	v_mfma_f32_16x16x32_bf16 v[104:107], v[144:147], v[182:185], v[104:107]
	v_mfma_f32_16x16x32_bf16 v[96:99], v[152:155], v[182:185], v[96:99]
	v_mfma_f32_16x16x32_bf16 v[88:91], v[144:147], v[190:193], v[88:91]
	v_mfma_f32_16x16x32_bf16 v[80:83], v[152:155], v[190:193], v[80:83]
	v_mfma_f32_16x16x32_bf16 v[124:127], v[148:151], v[170:173], v[124:127]
	v_mfma_f32_16x16x32_bf16 v[120:123], v[162:165], v[170:173], v[120:123]
	v_mfma_f32_16x16x32_bf16 v[116:119], v[148:151], v[178:181], v[116:119]
	v_mfma_f32_16x16x32_bf16 v[112:115], v[162:165], v[178:181], v[112:115]
	v_mfma_f32_16x16x32_bf16 v[104:107], v[148:151], v[186:189], v[104:107]
	v_mfma_f32_16x16x32_bf16 v[96:99], v[162:165], v[186:189], v[96:99]
	v_mfma_f32_16x16x32_bf16 v[88:91], v[148:151], v[194:197], v[88:91]
	v_mfma_f32_16x16x32_bf16 v[80:83], v[162:165], v[194:197], v[80:83]
	s_barrier
	s_setprio 0
	s_add_i32 s48, s39, s28
	v_lshl_add_u64 v[214:215], s[18:19], 0, v[132:133]
	s_mov_b32 m0, s48
	ds_read_b128 v[198:201], v161
	ds_read_b128 v[202:205], v161 offset:1024
	ds_read_b128 v[206:209], v161 offset:2048
	ds_read_b128 v[210:213], v161 offset:3072
	global_load_lds_dwordx4 v[214:215], off
	v_lshl_add_u64 v[216:217], s[18:19], 0, v[128:129]
	s_add_i32 m0, s48, 0x2000
	s_nop 0
	global_load_lds_dwordx4 v[216:217], off
	s_barrier
	s_waitcnt lgkmcnt(0)
	s_setprio 1
	v_mfma_f32_16x16x32_bf16 v[108:111], v[198:201], v[166:169], v[108:111]
	v_mfma_f32_16x16x32_bf16 v[100:103], v[206:209], v[166:169], v[100:103]
	v_mfma_f32_16x16x32_bf16 v[92:95], v[198:201], v[174:177], v[92:95]
	v_mfma_f32_16x16x32_bf16 v[84:87], v[206:209], v[174:177], v[84:87]
	v_mfma_f32_16x16x32_bf16 v[76:79], v[198:201], v[182:185], v[76:79]
	v_mfma_f32_16x16x32_bf16 v[72:75], v[206:209], v[182:185], v[72:75]
	v_mfma_f32_16x16x32_bf16 v[68:71], v[198:201], v[190:193], v[68:71]
	v_mfma_f32_16x16x32_bf16 v[64:67], v[206:209], v[190:193], v[64:67]
	v_mfma_f32_16x16x32_bf16 v[108:111], v[202:205], v[170:173], v[108:111]
	v_mfma_f32_16x16x32_bf16 v[100:103], v[210:213], v[170:173], v[100:103]
	v_mfma_f32_16x16x32_bf16 v[92:95], v[202:205], v[178:181], v[92:95]
	v_mfma_f32_16x16x32_bf16 v[84:87], v[210:213], v[178:181], v[84:87]
	v_mfma_f32_16x16x32_bf16 v[76:79], v[202:205], v[186:189], v[76:79]
	v_mfma_f32_16x16x32_bf16 v[72:75], v[210:213], v[186:189], v[72:75]
	v_mfma_f32_16x16x32_bf16 v[68:71], v[202:205], v[194:197], v[68:71]
	v_mfma_f32_16x16x32_bf16 v[64:67], v[210:213], v[194:197], v[64:67]
	s_barrier
	s_setprio 0
	s_mov_b32 m0, s30
	v_lshl_add_u64 v[218:219], s[20:21], 0, v[134:135]
	ds_read_b128 v[166:169], v160 offset:16384
	ds_read_b128 v[170:173], v160 offset:17408
	ds_read_b128 v[174:177], v160 offset:18432
	ds_read_b128 v[178:181], v160 offset:19456
	ds_read_b128 v[182:185], v160 offset:20480
	ds_read_b128 v[186:189], v160 offset:21504
	ds_read_b128 v[190:193], v160 offset:22528
	ds_read_b128 v[194:197], v160 offset:23552
	global_load_lds_dwordx4 v[218:219], off
	v_lshl_add_u64 v[220:221], s[20:21], 0, v[130:131]
	s_mov_b32 m0, s31
	s_nop 0
	global_load_lds_dwordx4 v[220:221], off
	s_barrier
	s_waitcnt lgkmcnt(0)
	s_setprio 1
	v_mfma_f32_16x16x32_bf16 v[60:63], v[144:147], v[166:169], v[60:63]
	v_mfma_f32_16x16x32_bf16 v[56:59], v[152:155], v[166:169], v[56:59]
	v_mfma_f32_16x16x32_bf16 v[52:55], v[144:147], v[174:177], v[52:55]
	v_mfma_f32_16x16x32_bf16 v[44:47], v[152:155], v[174:177], v[44:47]
	v_mfma_f32_16x16x32_bf16 v[36:39], v[144:147], v[182:185], v[36:39]
	v_mfma_f32_16x16x32_bf16 v[28:31], v[152:155], v[182:185], v[28:31]
	v_mfma_f32_16x16x32_bf16 v[20:23], v[144:147], v[190:193], v[20:23]
	v_mfma_f32_16x16x32_bf16 v[12:15], v[152:155], v[190:193], v[12:15]
	v_mfma_f32_16x16x32_bf16 v[60:63], v[148:151], v[170:173], v[60:63]
	v_mfma_f32_16x16x32_bf16 v[56:59], v[162:165], v[170:173], v[56:59]
	v_mfma_f32_16x16x32_bf16 v[52:55], v[148:151], v[178:181], v[52:55]
	v_mfma_f32_16x16x32_bf16 v[44:47], v[162:165], v[178:181], v[44:47]
	v_mfma_f32_16x16x32_bf16 v[36:39], v[148:151], v[186:189], v[36:39]
	v_mfma_f32_16x16x32_bf16 v[28:31], v[162:165], v[186:189], v[28:31]
	v_mfma_f32_16x16x32_bf16 v[20:23], v[148:151], v[194:197], v[20:23]
	v_mfma_f32_16x16x32_bf16 v[12:15], v[162:165], v[194:197], v[12:15]
	s_barrier
; #define PG8_STAGE(bufoff, gbase, voff) do { _Pragma("unroll") for (int _i = 0; _i < 2; ++_i) \
;     __builtin_amdgcn_global_load_lds((const unsigned*)((const char*)(gbase) + (voff)[_i]), (LAS unsigned*)(lds + (bufoff) + ldsw + _i * 8192), 16, 0, 0); } while (0)
; #define PG8_LDA(dst, b, h) do { _Pragma("unroll") for (int m = 0; m < 4; ++m) _Pragma("unroll") for (int k = 0; k < 2; ++k) dst[m][k] = *(const LAS bf16x8*)(lds + PG8_SA(b, h) + aoff + m * 2048 + k * 1024); } while (0)
; #define PG8_LDB(dst, b, h) do { _Pragma("unroll") for (int n = 0; n < 2; ++n) _Pragma("unroll") for (int k = 0; k < 2; ++k) dst[n][k] = *(const LAS bf16x8*)(lds + PG8_SB(b, h) + boff + n * 2048 + k * 1024); } while (0)
; #define PG8_MMA(ai, bj, At, Bt) do { __builtin_amdgcn_s_setprio(1); _Pragma("unroll") for (int m = 0; m < 4; ++m) _Pragma("unroll") for (int n = 0; n < 2; ++n) _Pragma("unroll") for (int k = 0; k < 2; ++k) \
;     acc[ai][bj][m][n] = __builtin_amdgcn_mfma_f32_16x16x32_bf16(Bt[n][k], At[m][k], acc[ai][bj][m][n], 0, 0, 0); __builtin_amdgcn_s_setprio(0); } while (0)
; #define PG8_WAIT_V(n) asm volatile("s_waitcnt vmcnt(" #n ")" ::: "memory")
; #define PG8_WAIT_L(n) asm volatile("s_waitcnt lgkmcnt(" #n ")" ::: "memory")
; #define PG8_BAR __builtin_amdgcn_s_barrier()
; #define PG8_SCHED __builtin_amdgcn_sched_barrier(0)
; template <class Epi, class Sched = StaticOrder>
; DI void gemm_phase(LAS unsigned char* lds, const Gemm g, const Sched& S, const Epi& E) {
;     ...
;       PG8_STAGE(PG8_SB(0, 1), b2 + hstep, voffB);
;       PG8_WAIT_V(6); PG8_BAR; PG8_MMA(1, 1, At, B1); PG8_BAR;
;       PG8_LDB(B0, 1, 0); PG8_SCHED; PG8_LDA(At, 1, 0); PG8_STAGE(PG8_SA(0, 1), a2 + hstep, voffA);
;       PG8_WAIT_L(8); PG8_BAR; PG8_WAIT_L(0); PG8_MMA(0, 0, At, B0); PG8_BAR; PG8_SCHED;
;       PG8_LDB(B1, 1, 1); PG8_STAGE(PG8_SB(1, 0), b3, voffB);
;       PG8_BAR; PG8_WAIT_L(0); PG8_MMA(0, 1, At, B1); PG8_BAR;
;       PG8_LDA(At, 1, 1); PG8_STAGE(PG8_SA(1, 0), a3, voffA);
	s_setprio 0
	s_add_u32 s48, s18, 0x160000
	s_addc_u32 s49, s19, 0
	s_add_i32 s50, s40, s28
	v_lshl_add_u64 v[144:145], s[48:49], 0, v[132:133]
	s_mov_b32 m0, s50
	s_nop 0
	global_load_lds_dwordx4 v[144:145], off
	v_lshl_add_u64 v[144:145], s[48:49], 0, v[128:129]
	s_add_i32 m0, s50, 0x2000
	s_nop 0
	global_load_lds_dwordx4 v[144:145], off
	s_waitcnt vmcnt(6)
	s_barrier
	s_setprio 1
	v_mfma_f32_16x16x32_bf16 v[48:51], v[198:201], v[166:169], v[48:51]
	v_mfma_f32_16x16x32_bf16 v[40:43], v[206:209], v[166:169], v[40:43]
	v_mfma_f32_16x16x32_bf16 v[32:35], v[198:201], v[174:177], v[32:35]
	v_mfma_f32_16x16x32_bf16 v[24:27], v[206:209], v[174:177], v[24:27]
	v_mfma_f32_16x16x32_bf16 v[16:19], v[198:201], v[182:185], v[16:19]
	v_mfma_f32_16x16x32_bf16 v[8:11], v[206:209], v[182:185], v[8:11]
	v_mfma_f32_16x16x32_bf16 v[4:7], v[198:201], v[190:193], v[4:7]
	v_mfma_f32_16x16x32_bf16 v[0:3], v[206:209], v[190:193], v[0:3]
	v_mfma_f32_16x16x32_bf16 v[48:51], v[202:205], v[170:173], v[48:51]
	v_mfma_f32_16x16x32_bf16 v[40:43], v[210:213], v[170:173], v[40:43]
	v_mfma_f32_16x16x32_bf16 v[32:35], v[202:205], v[178:181], v[32:35]
	v_mfma_f32_16x16x32_bf16 v[24:27], v[210:213], v[178:181], v[24:27]
	v_mfma_f32_16x16x32_bf16 v[16:19], v[202:205], v[186:189], v[16:19]
	v_mfma_f32_16x16x32_bf16 v[8:11], v[210:213], v[186:189], v[8:11]
	v_mfma_f32_16x16x32_bf16 v[4:7], v[202:205], v[194:197], v[4:7]
	v_mfma_f32_16x16x32_bf16 v[0:3], v[210:213], v[194:197], v[0:3]
	s_barrier
	s_setprio 0
	s_add_i32 s48, 0, 0x18000
	v_add_u32_e32 v162, s48, v157
	ds_read_b128 v[144:147], v162
	ds_read_b128 v[148:151], v162 offset:1024
	ds_read_b128 v[152:155], v162 offset:2048
	ds_read_b128 v[162:165], v162 offset:3072
	s_add_u32 s20, s20, 0x160000
	s_addc_u32 s21, s21, 0
	s_mov_b32 m0, s33
	v_lshl_add_u64 v[198:199], s[20:21], 0, v[134:135]
	ds_read_b128 v[166:169], v160 offset:32768
	ds_read_b128 v[170:173], v160 offset:33792
	ds_read_b128 v[174:177], v160 offset:34816
	ds_read_b128 v[178:181], v160 offset:35840
	ds_read_b128 v[182:185], v160 offset:36864
	ds_read_b128 v[186:189], v160 offset:37888
	ds_read_b128 v[190:193], v160 offset:38912
	ds_read_b128 v[194:197], v160 offset:39936
	global_load_lds_dwordx4 v[198:199], off
	v_lshl_add_u64 v[198:199], s[20:21], 0, v[130:131]
	s_mov_b32 m0, s34
	s_nop 0
	global_load_lds_dwordx4 v[198:199], off
	s_waitcnt lgkmcnt(8)
	s_barrier
	s_waitcnt lgkmcnt(0)
	s_setprio 1
	v_mfma_f32_16x16x32_bf16 v[124:127], v[144:147], v[166:169], v[124:127]
	v_mfma_f32_16x16x32_bf16 v[120:123], v[152:155], v[166:169], v[120:123]
	v_mfma_f32_16x16x32_bf16 v[116:119], v[144:147], v[174:177], v[116:119]
	v_mfma_f32_16x16x32_bf16 v[112:115], v[152:155], v[174:177], v[112:115]
	v_mfma_f32_16x16x32_bf16 v[104:107], v[144:147], v[182:185], v[104:107]
	v_mfma_f32_16x16x32_bf16 v[96:99], v[152:155], v[182:185], v[96:99]
	v_mfma_f32_16x16x32_bf16 v[88:91], v[144:147], v[190:193], v[88:91]
	v_mfma_f32_16x16x32_bf16 v[80:83], v[152:155], v[190:193], v[80:83]
	v_mfma_f32_16x16x32_bf16 v[124:127], v[148:151], v[170:173], v[124:127]
	v_mfma_f32_16x16x32_bf16 v[120:123], v[162:165], v[170:173], v[120:123]
	v_mfma_f32_16x16x32_bf16 v[116:119], v[148:151], v[178:181], v[116:119]
	v_mfma_f32_16x16x32_bf16 v[112:115], v[162:165], v[178:181], v[112:115]
	v_mfma_f32_16x16x32_bf16 v[104:107], v[148:151], v[186:189], v[104:107]
	v_mfma_f32_16x16x32_bf16 v[96:99], v[162:165], v[186:189], v[96:99]
	v_mfma_f32_16x16x32_bf16 v[88:91], v[148:151], v[194:197], v[88:91]
	v_mfma_f32_16x16x32_bf16 v[80:83], v[162:165], v[194:197], v[80:83]
	s_barrier
	s_setprio 0
	s_add_i32 s20, 0, 0x1c000
	s_add_i32 s21, s48, s28
	v_add_u32_e32 v210, s20, v157
	v_lshl_add_u64 v[214:215], v[214:215], 0, s[8:9]
	s_mov_b32 m0, s21
	ds_read_b128 v[198:201], v210
	ds_read_b128 v[202:205], v210 offset:1024
	ds_read_b128 v[206:209], v210 offset:2048
	ds_read_b128 v[210:213], v210 offset:3072
	global_load_lds_dwordx4 v[214:215], off
	v_lshl_add_u64 v[214:215], v[216:217], 0, s[8:9]
	s_add_i32 m0, s21, 0x2000
	s_nop 0
	global_load_lds_dwordx4 v[214:215], off
	s_barrier
	s_waitcnt lgkmcnt(0)
	s_setprio 1
	v_mfma_f32_16x16x32_bf16 v[108:111], v[198:201], v[166:169], v[108:111]
	v_mfma_f32_16x16x32_bf16 v[100:103], v[206:209], v[166:169], v[100:103]
	v_mfma_f32_16x16x32_bf16 v[92:95], v[198:201], v[174:177], v[92:95]
	v_mfma_f32_16x16x32_bf16 v[84:87], v[206:209], v[174:177], v[84:87]
	v_mfma_f32_16x16x32_bf16 v[76:79], v[198:201], v[182:185], v[76:79]
	v_mfma_f32_16x16x32_bf16 v[72:75], v[206:209], v[182:185], v[72:75]
	v_mfma_f32_16x16x32_bf16 v[68:71], v[198:201], v[190:193], v[68:71]
	v_mfma_f32_16x16x32_bf16 v[64:67], v[206:209], v[190:193], v[64:67]
	v_mfma_f32_16x16x32_bf16 v[108:111], v[202:205], v[170:173], v[108:111]
	v_mfma_f32_16x16x32_bf16 v[100:103], v[210:213], v[170:173], v[100:103]
	v_mfma_f32_16x16x32_bf16 v[92:95], v[202:205], v[178:181], v[92:95]
	v_mfma_f32_16x16x32_bf16 v[84:87], v[210:213], v[178:181], v[84:87]
	v_mfma_f32_16x16x32_bf16 v[76:79], v[202:205], v[186:189], v[76:79]
	v_mfma_f32_16x16x32_bf16 v[72:75], v[210:213], v[186:189], v[72:75]
	v_mfma_f32_16x16x32_bf16 v[68:71], v[202:205], v[194:197], v[68:71]
	v_mfma_f32_16x16x32_bf16 v[64:67], v[210:213], v[194:197], v[64:67]
	s_barrier
	s_setprio 0
	s_mov_b32 m0, s35
	v_lshl_add_u64 v[214:215], v[218:219], 0, s[8:9]
	ds_read_b128 v[166:169], v160 offset:49152
	ds_read_b128 v[170:173], v160 offset:50176
	ds_read_b128 v[174:177], v160 offset:51200
	ds_read_b128 v[178:181], v160 offset:52224
	ds_read_b128 v[182:185], v160 offset:53248
	ds_read_b128 v[186:189], v160 offset:54272
	ds_read_b128 v[190:193], v160 offset:55296
	ds_read_b128 v[194:197], v160 offset:56320
	global_load_lds_dwordx4 v[214:215], off
	v_lshl_add_u64 v[214:215], v[220:221], 0, s[8:9]
	s_mov_b32 m0, s36
	s_nop 0
	global_load_lds_dwordx4 v[214:215], off
	s_barrier
; #define PG8_STAGE(bufoff, gbase, voff) do { _Pragma("unroll") for (int _i = 0; _i < 2; ++_i) \
;     __builtin_amdgcn_global_load_lds((const unsigned*)((const char*)(gbase) + (voff)[_i]), (LAS unsigned*)(lds + (bufoff) + ldsw + _i * 8192), 16, 0, 0); } while (0)
; #define PG8_LDA(dst, b, h) do { _Pragma("unroll") for (int m = 0; m < 4; ++m) _Pragma("unroll") for (int k = 0; k < 2; ++k) dst[m][k] = *(const LAS bf16x8*)(lds + PG8_SA(b, h) + aoff + m * 2048 + k * 1024); } while (0)
; #define PG8_MMA(ai, bj, At, Bt) do { __builtin_amdgcn_s_setprio(1); _Pragma("unroll") for (int m = 0; m < 4; ++m) _Pragma("unroll") for (int n = 0; n < 2; ++n) _Pragma("unroll") for (int k = 0; k < 2; ++k) \
;     acc[ai][bj][m][n] = __builtin_amdgcn_mfma_f32_16x16x32_bf16(Bt[n][k], At[m][k], acc[ai][bj][m][n], 0, 0, 0); __builtin_amdgcn_s_setprio(0); } while (0)
; #define PG8_WAIT_V(n) asm volatile("s_waitcnt vmcnt(" #n ")" ::: "memory")
; #define PG8_WAIT_L(n) asm volatile("s_waitcnt lgkmcnt(" #n ")" ::: "memory")
; #define PG8_BAR __builtin_amdgcn_s_barrier()
; #define PG8_SCHED __builtin_amdgcn_sched_barrier(0)
;   DI void operator()(const f32x4 (&acc)[2][2][4][2], const Unit& u, int wr, int wc, int fr, int fq) const {
;     const int row0 = u.pm * BM + wr * 64 + fr, col0 = u.pn * BM + wc * 32 + 8 * fq;
; #pragma unroll
;     for (int ai = 0; ai < 2; ++ai) {
;       f32x4 bv[4][2][2];
; #pragma unroll
;       for (int m = 0; m < 4; ++m)
; #pragma unroll
;         for (int bj = 0; bj < 2; ++bj) {
;           const float* bp = base + (size_t)(row0 + ai * HALF + m * 16) * 2048 + col0 + bj * HALF;
;           bv[m][bj][0] = *(const f32x4*)bp; bv[m][bj][1] = *(const f32x4*)(bp + 4);
; template <class Epi, class Sched = StaticOrder>
; DI void gemm_phase(LAS unsigned char* lds, const Gemm g, const Sched& S, const Epi& E) {
;     ...
;       PG8_LDA(At, 1, 1); PG8_STAGE(PG8_SA(1, 0), a3, voffA);
;       PG8_BAR; PG8_WAIT_L(0); PG8_MMA(1, 0, At, B0); PG8_BAR; PG8_SCHED;
;       PG8_STAGE(PG8_SB(1, 1), b3 + hstep, voffB);
;       PG8_WAIT_V(6); PG8_BAR; PG8_MMA(1, 1, At, B1); PG8_BAR;
	s_waitcnt lgkmcnt(0)
	s_setprio 1
	v_mfma_f32_16x16x32_bf16 v[60:63], v[144:147], v[166:169], v[60:63]
	v_mfma_f32_16x16x32_bf16 v[56:59], v[152:155], v[166:169], v[56:59]
	v_mfma_f32_16x16x32_bf16 v[52:55], v[144:147], v[174:177], v[52:55]
	v_mfma_f32_16x16x32_bf16 v[44:47], v[152:155], v[174:177], v[44:47]
	v_mfma_f32_16x16x32_bf16 v[36:39], v[144:147], v[182:185], v[36:39]
	v_mfma_f32_16x16x32_bf16 v[28:31], v[152:155], v[182:185], v[28:31]
	v_mfma_f32_16x16x32_bf16 v[20:23], v[144:147], v[190:193], v[20:23]
	v_mfma_f32_16x16x32_bf16 v[12:15], v[152:155], v[190:193], v[12:15]
	v_mfma_f32_16x16x32_bf16 v[60:63], v[148:151], v[170:173], v[60:63]
	v_mfma_f32_16x16x32_bf16 v[56:59], v[162:165], v[170:173], v[56:59]
	v_mfma_f32_16x16x32_bf16 v[52:55], v[148:151], v[178:181], v[52:55]
	v_mfma_f32_16x16x32_bf16 v[44:47], v[162:165], v[178:181], v[44:47]
	v_mfma_f32_16x16x32_bf16 v[36:39], v[148:151], v[186:189], v[36:39]
	v_mfma_f32_16x16x32_bf16 v[28:31], v[162:165], v[186:189], v[28:31]
	v_mfma_f32_16x16x32_bf16 v[20:23], v[148:151], v[194:197], v[20:23]
	v_mfma_f32_16x16x32_bf16 v[12:15], v[162:165], v[194:197], v[12:15]
	s_barrier
	s_setprio 0
	s_add_u32 s18, s18, 0x160080
	s_addc_u32 s19, s19, 0
	s_add_i32 s20, s20, s28
	v_lshl_add_u64 v[144:145], s[18:19], 0, v[132:133]
	s_mov_b32 m0, s20
	s_nop 0
	global_load_lds_dwordx4 v[144:145], off
	v_lshl_add_u64 v[144:145], s[18:19], 0, v[128:129]
	s_add_i32 m0, s20, 0x2000
	s_nop 0
	global_load_lds_dwordx4 v[144:145], off
	s_waitcnt vmcnt(6)
	s_barrier
	s_setprio 1
	v_mfma_f32_16x16x32_bf16 v[48:51], v[198:201], v[166:169], v[48:51]
	v_mfma_f32_16x16x32_bf16 v[40:43], v[206:209], v[166:169], v[40:43]
	v_mfma_f32_16x16x32_bf16 v[32:35], v[198:201], v[174:177], v[32:35]
	v_mfma_f32_16x16x32_bf16 v[24:27], v[206:209], v[174:177], v[24:27]
	v_mfma_f32_16x16x32_bf16 v[16:19], v[198:201], v[182:185], v[16:19]
	v_mfma_f32_16x16x32_bf16 v[8:11], v[206:209], v[182:185], v[8:11]
	v_mfma_f32_16x16x32_bf16 v[4:7], v[198:201], v[190:193], v[4:7]
	v_mfma_f32_16x16x32_bf16 v[0:3], v[206:209], v[190:193], v[0:3]
	v_mfma_f32_16x16x32_bf16 v[48:51], v[202:205], v[170:173], v[48:51]
	v_mfma_f32_16x16x32_bf16 v[40:43], v[210:213], v[170:173], v[40:43]
	v_mfma_f32_16x16x32_bf16 v[32:35], v[202:205], v[178:181], v[32:35]
	v_mfma_f32_16x16x32_bf16 v[24:27], v[210:213], v[178:181], v[24:27]
	v_mfma_f32_16x16x32_bf16 v[16:19], v[202:205], v[186:189], v[16:19]
	v_mfma_f32_16x16x32_bf16 v[8:11], v[210:213], v[186:189], v[8:11]
	v_mfma_f32_16x16x32_bf16 v[4:7], v[202:205], v[194:197], v[4:7]
	v_mfma_f32_16x16x32_bf16 v[0:3], v[210:213], v[194:197], v[0:3]
	s_add_i32 s47, s47, 2
	s_add_u32 s16, s16, 0x100
	s_addc_u32 s17, s17, 0
	s_add_u32 s45, s45, 0x100
	s_addc_u32 s46, s46, 0
	s_cmpk_gt_u32 s47, 0x55
	s_barrier
	s_setprio 0
	s_cbranch_scc0 .LBB0_1424
	v_lshl_or_b32 v144, s44, 8, v158
	v_lshl_add_u32 v154, s43, 8, v156
	v_ashrrev_i32_e32 v145, 31, v144
	v_lshlrev_b64 v[144:145], 2, v[144:145]
	v_ashrrev_i32_e32 v155, 31, v154
	v_lshl_add_u64 v[146:147], s[54:55], 0, v[144:145]
	v_lshlrev_b64 v[148:149], 13, v[154:155]
	v_or_b32_e32 v174, 16, v154
	v_lshl_add_u64 v[170:171], v[146:147], 0, v[148:149]
	v_ashrrev_i32_e32 v175, 31, v174
	global_load_dwordx4 v[150:153], v[170:171], off offset:16
	global_load_dwordx4 v[162:165], v[170:171], off
	global_load_dwordx4 v[166:169], v[170:171], off offset:528
	s_nop 0
	global_load_dwordx4 v[170:173], v[170:171], off offset:512
	v_lshlrev_b64 v[222:223], 13, v[174:175]
	v_or_b32_e32 v190, 32, v154
	v_lshl_add_u64 v[186:187], v[146:147], 0, v[222:223]
	v_ashrrev_i32_e32 v191, 31, v190
	global_load_dwordx4 v[174:177], v[186:187], off offset:16
	global_load_dwordx4 v[178:181], v[186:187], off
	global_load_dwordx4 v[182:185], v[186:187], off offset:528
	s_nop 0
	global_load_dwordx4 v[186:189], v[186:187], off offset:512
	v_lshlrev_b64 v[224:225], 13, v[190:191]
	v_or_b32_e32 v154, 48, v154
	v_lshl_add_u64 v[202:203], v[146:147], 0, v[224:225]
	v_ashrrev_i32_e32 v155, 31, v154
	global_load_dwordx4 v[190:193], v[202:203], off offset:16
	global_load_dwordx4 v[194:197], v[202:203], off
	global_load_dwordx4 v[198:201], v[202:203], off offset:528
	s_nop 0
	global_load_dwordx4 v[202:205], v[202:203], off offset:512
	v_lshlrev_b64 v[154:155], 13, v[154:155]
	v_lshl_add_u64 v[218:219], v[146:147], 0, v[154:155]
	global_load_dwordx4 v[206:209], v[218:219], off offset:16
	global_load_dwordx4 v[210:213], v[218:219], off
	global_load_dwordx4 v[214:217], v[218:219], off offset:528
	s_nop 0
	global_load_dwordx4 v[218:221], v[218:219], off offset:512
	s_and_b64 vcc, exec, s[0:1]
	s_mov_b32 s44, s41
	s_mov_b32 s43, s42
	s_mov_b64 s[18:19], s[4:5]
	s_mov_b64 s[16:17], s[2:3]
	s_waitcnt vmcnt(0)
;   DI void operator()(const f32x4 (&acc)[2][2][4][2], const Unit& u, int wr, int wc, int fr, int fq) const {
;     const int row0 = u.pm * BM + wr * 64 + fr, col0 = u.pn * BM + wc * 32 + 8 * fq;
; #pragma unroll
;     for (int ai = 0; ai < 2; ++ai) {
;       f32x4 bv[4][2][2];
; #pragma unroll
;       for (int m = 0; m < 4; ++m)
; #pragma unroll
;         for (int bj = 0; bj < 2; ++bj) {
;           const float* bp = base + (size_t)(row0 + ai * HALF + m * 16) * 2048 + col0 + bj * HALF;
;           bv[m][bj][0] = *(const f32x4*)bp; bv[m][bj][1] = *(const f32x4*)(bp + 4);
;         }
; #pragma unroll
;       for (int m = 0; m < 4; ++m) {
;         const int row = row0 + ai * HALF + m * 16;
;         const size_t off = (size_t)row * 2048 + col0;
;         float ss = 0.f;
; #pragma unroll
;         for (int bj = 0; bj < 2; ++bj) {
;           const f32x4 v0 = acc[ai][bj][m][0] + bv[m][bj][0], v1 = acc[ai][bj][m][1] + bv[m][bj][1];
;           *(f32x4*)(C + off + bj * HALF) = v0; *(f32x4*)(C + off + bj * HALF + 4) = v1;
	v_pk_add_f32 v[120:121], v[120:121], v[150:151]
	v_lshl_add_u64 v[150:151], s[54:55], 0, v[148:149]
	v_pk_add_f32 v[126:127], v[126:127], v[164:165]
	v_pk_add_f32 v[124:125], v[124:125], v[162:163]
	v_lshl_add_u64 v[150:151], v[150:151], 0, v[144:145]
	v_pk_add_f32 v[110:111], v[110:111], v[172:173]
	v_pk_add_f32 v[108:109], v[108:109], v[170:171]
	v_pk_add_f32 v[122:123], v[122:123], v[152:153]
	global_store_dwordx4 v[150:151], v[124:127], off
	global_store_dwordx4 v[150:151], v[120:123], off offset:16
	v_pk_add_f32 v[102:103], v[102:103], v[168:169]
	v_pk_add_f32 v[100:101], v[100:101], v[166:167]
	global_store_dwordx4 v[150:151], v[108:111], off offset:512
	global_store_dwordx4 v[150:151], v[100:103], off offset:528
	v_pk_add_f32 v[94:95], v[94:95], v[188:189]
	v_pk_add_f32 v[108:109], v[112:113], v[174:175]
	v_lshl_add_u64 v[112:113], s[54:55], 0, v[222:223]
	v_pk_add_f32 v[102:103], v[118:119], v[180:181]
	v_pk_add_f32 v[100:101], v[116:117], v[178:179]
	v_lshl_add_u64 v[112:113], v[112:113], 0, v[144:145]
	v_pk_add_f32 v[92:93], v[92:93], v[186:187]
	v_pk_add_f32 v[110:111], v[114:115], v[176:177]
	global_store_dwordx4 v[112:113], v[100:103], off
	global_store_dwordx4 v[112:113], v[108:111], off offset:16
	v_pk_add_f32 v[86:87], v[86:87], v[184:185]
	v_pk_add_f32 v[84:85], v[84:85], v[182:183]
	global_store_dwordx4 v[112:113], v[92:95], off offset:512
	global_store_dwordx4 v[112:113], v[84:87], off offset:528
	v_pk_add_f32 v[78:79], v[78:79], v[204:205]
	v_pk_add_f32 v[92:93], v[96:97], v[190:191]
	v_lshl_add_u64 v[96:97], s[54:55], 0, v[224:225]
	v_pk_add_f32 v[86:87], v[106:107], v[196:197]
	v_pk_add_f32 v[84:85], v[104:105], v[194:195]
	v_lshl_add_u64 v[96:97], v[96:97], 0, v[144:145]
	v_pk_add_f32 v[76:77], v[76:77], v[202:203]
	v_pk_add_f32 v[94:95], v[98:99], v[192:193]
	global_store_dwordx4 v[96:97], v[84:87], off
	global_store_dwordx4 v[96:97], v[92:95], off offset:16
	v_pk_add_f32 v[74:75], v[74:75], v[200:201]
	v_pk_add_f32 v[72:73], v[72:73], v[198:199]
	global_store_dwordx4 v[96:97], v[76:79], off offset:512
	global_store_dwordx4 v[96:97], v[72:75], off offset:528
	v_pk_add_f32 v[70:71], v[70:71], v[220:221]
	v_pk_add_f32 v[76:77], v[80:81], v[206:207]
	v_lshl_add_u64 v[80:81], s[54:55], 0, v[154:155]
	v_pk_add_f32 v[74:75], v[90:91], v[212:213]
	v_pk_add_f32 v[72:73], v[88:89], v[210:211]
	v_lshl_add_u64 v[80:81], v[80:81], 0, v[144:145]
	v_pk_add_f32 v[68:69], v[68:69], v[218:219]
	v_pk_add_f32 v[64:65], v[64:65], v[214:215]
	v_lshl_add_u64 v[154:155], v[148:149], 0, s[10:11]
	v_pk_add_f32 v[78:79], v[82:83], v[208:209]
	global_store_dwordx4 v[80:81], v[72:75], off
	global_store_dwordx4 v[80:81], v[76:79], off offset:16
	v_pk_add_f32 v[66:67], v[66:67], v[216:217]
	global_store_dwordx4 v[80:81], v[68:71], off offset:512
	global_store_dwordx4 v[80:81], v[64:67], off offset:528
	v_lshl_add_u64 v[152:153], v[148:149], 0, s[12:13]
	v_lshl_add_u64 v[150:151], v[148:149], 0, s[14:15]
	v_lshl_add_u64 v[64:65], v[146:147], 0, v[154:155]
	global_load_dwordx4 v[108:111], v[64:65], off offset:16
	global_load_dwordx4 v[120:123], v[64:65], off
	global_load_dwordx4 v[92:95], v[64:65], off offset:528
	global_load_dwordx4 v[100:103], v[64:65], off offset:512
	v_lshl_add_u64 v[64:65], v[146:147], 0, v[152:153]
	global_load_dwordx4 v[88:91], v[64:65], off offset:16
	global_load_dwordx4 v[96:99], v[64:65], off
	global_load_dwordx4 v[76:79], v[64:65], off offset:528
	global_load_dwordx4 v[84:87], v[64:65], off offset:512
	v_lshl_add_u64 v[68:69], v[146:147], 0, v[150:151]
	global_load_dwordx4 v[72:75], v[68:69], off offset:16
	global_load_dwordx4 v[80:83], v[68:69], off
	global_load_dwordx4 v[64:67], v[68:69], off offset:528
	s_nop 0
	global_load_dwordx4 v[68:71], v[68:69], off offset:512
	v_lshl_add_u64 v[148:149], v[148:149], 0, s[6:7]
	v_lshl_add_u64 v[112:113], v[146:147], 0, v[148:149]
	global_load_dwordx4 v[116:119], v[112:113], off offset:16
	global_load_dwordx4 v[124:127], v[112:113], off
	global_load_dwordx4 v[104:107], v[112:113], off offset:528
	s_nop 0
	global_load_dwordx4 v[112:115], v[112:113], off offset:512
	s_waitcnt vmcnt(0)
	v_pk_add_f32 v[56:57], v[56:57], v[108:109]
	v_lshl_add_u64 v[108:109], s[54:55], 0, v[154:155]
	v_pk_add_f32 v[62:63], v[62:63], v[122:123]
	v_pk_add_f32 v[60:61], v[60:61], v[120:121]
	v_lshl_add_u64 v[108:109], v[108:109], 0, v[144:145]
	v_pk_add_f32 v[50:51], v[50:51], v[102:103]
	v_pk_add_f32 v[48:49], v[48:49], v[100:101]
	v_pk_add_f32 v[58:59], v[58:59], v[110:111]
	global_store_dwordx4 v[108:109], v[60:63], off
	global_store_dwordx4 v[108:109], v[56:59], off offset:16
	v_pk_add_f32 v[42:43], v[42:43], v[94:95]
	v_pk_add_f32 v[40:41], v[40:41], v[92:93]
	global_store_dwordx4 v[108:109], v[48:51], off offset:512
	global_store_dwordx4 v[108:109], v[40:43], off offset:528
	v_pk_add_f32 v[34:35], v[34:35], v[86:87]
	v_lshl_add_u64 v[48:49], s[54:55], 0, v[152:153]
	v_pk_add_f32 v[42:43], v[54:55], v[98:99]
	v_pk_add_f32 v[40:41], v[52:53], v[96:97]
	v_lshl_add_u64 v[48:49], v[48:49], 0, v[144:145]
	v_pk_add_f32 v[32:33], v[32:33], v[84:85]
	v_pk_add_f32 v[46:47], v[46:47], v[90:91]
	v_pk_add_f32 v[44:45], v[44:45], v[88:89]
	global_store_dwordx4 v[48:49], v[40:43], off
	global_store_dwordx4 v[48:49], v[44:47], off offset:16
	v_pk_add_f32 v[26:27], v[26:27], v[78:79]
	v_pk_add_f32 v[24:25], v[24:25], v[76:77]
	global_store_dwordx4 v[48:49], v[32:35], off offset:512
	global_store_dwordx4 v[48:49], v[24:27], off offset:528
	v_pk_add_f32 v[18:19], v[18:19], v[70:71]
	v_lshl_add_u64 v[32:33], s[54:55], 0, v[150:151]
	v_pk_add_f32 v[26:27], v[38:39], v[82:83]
	v_pk_add_f32 v[24:25], v[36:37], v[80:81]
	v_lshl_add_u64 v[32:33], v[32:33], 0, v[144:145]
	v_pk_add_f32 v[16:17], v[16:17], v[68:69]
	v_pk_add_f32 v[30:31], v[30:31], v[74:75]
	v_pk_add_f32 v[28:29], v[28:29], v[72:73]
	global_store_dwordx4 v[32:33], v[24:27], off
	global_store_dwordx4 v[32:33], v[28:31], off offset:16
	v_pk_add_f32 v[10:11], v[10:11], v[66:67]
	v_pk_add_f32 v[8:9], v[8:9], v[64:65]
	global_store_dwordx4 v[32:33], v[16:19], off offset:512
	global_store_dwordx4 v[32:33], v[8:11], off offset:528
	v_pk_add_f32 v[6:7], v[6:7], v[114:115]
	v_lshl_add_u64 v[16:17], s[54:55], 0, v[148:149]
	v_pk_add_f32 v[10:11], v[22:23], v[126:127]
	v_pk_add_f32 v[8:9], v[20:21], v[124:125]
	v_lshl_add_u64 v[16:17], v[16:17], 0, v[144:145]
	v_pk_add_f32 v[4:5], v[4:5], v[112:113]
	v_pk_add_f32 v[14:15], v[14:15], v[118:119]
	v_pk_add_f32 v[12:13], v[12:13], v[116:117]
	global_store_dwordx4 v[16:17], v[8:11], off
	global_store_dwordx4 v[16:17], v[12:15], off offset:16
	v_pk_add_f32 v[2:3], v[2:3], v[106:107]
	v_pk_add_f32 v[0:1], v[0:1], v[104:105]
	global_store_dwordx4 v[16:17], v[4:7], off offset:512
	global_store_dwordx4 v[16:17], v[0:3], off offset:528
	s_cbranch_vccz .LBB0_1417
	s_waitcnt vmcnt(0)
	s_cmpk_gt_u32 s23, 0xff
	s_cbranch_scc1 .LBB0_1428
	s_barrier
